# xor-16/xor-32 butterfly shuffles (56 ds_bpermute + wait, in attention softmax and mout row sums) replaced by v_permlane16/32_swap, no LDS round trip; on top of v63
# baseline (speedup 1.0000x reference)
.LBB0_254:
	s_add_i32 s2, s53, -1
	s_add_i32 s60, s52, s3
	s_and_b32 s50, s2, 1
	s_and_b32 s61, s53, 1
	s_and_b64 s[40:41], s[66:67], exec
	s_cselect_b32 s2, s50, s61
	s_mul_i32 s38, s2, 0x11000
	s_add_i32 s38, s38, s96
	s_and_b64 s[40:41], s[68:69], exec
	s_cselect_b32 s2, s50, s61
	s_mul_i32 s33, s2, 0x11000
	s_add_i32 s33, s33, s97
	v_add_u32_e32 v146, s38, v84
	v_lshlrev_b32_e32 v129, s48, v64
	s_and_b64 s[40:41], s[70:71], exec
	ds_read_b128 v[64:67], v146
	ds_read_b128 v[68:71], v146 offset:64
	ds_read_b128 v[130:133], v146 offset:128
	ds_read_b128 v[134:137], v146 offset:192
	ds_read_b128 v[138:141], v146 offset:1088
	ds_read_b128 v[142:145], v146 offset:1152
	ds_read_b128 v[148:151], v146 offset:1216
	ds_read_b128 v[152:155], v146 offset:1280
	v_add_u32_e32 v146, s33, v84
	s_cselect_b32 s2, s50, s61
	ds_read_b128 v[156:159], v146
	ds_read_b128 v[160:163], v146 offset:64
	ds_read_b128 v[164:167], v146 offset:128
	ds_read_b128 v[168:171], v146 offset:192
	ds_read_b128 v[172:175], v146 offset:1088
	ds_read_b128 v[176:179], v146 offset:1152
	ds_read_b128 v[184:187], v146 offset:1216
	ds_read_b128 v[188:191], v146 offset:1280
	s_mul_i32 s2, s2, 0x11000
	s_add_i32 s2, s2, s62
	s_and_b64 s[40:41], s[72:73], exec
	s_cselect_b32 s40, s50, s61
	s_mul_i32 s41, s40, 0x11000
	s_add_i32 s41, s41, s63
	s_and_b64 vcc, s[76:77], exec
	s_cselect_b32 s40, s50, s61
	s_mul_i32 s40, s40, 0x11000
	s_add_i32 s40, s40, s96
	s_waitcnt lgkmcnt(14)
	v_mfma_f32_16x16x32_bf16 v[64:67], v[64:67], v[48:51], 0
	v_mfma_f32_16x16x32_bf16 v[64:67], v[68:71], v[52:55], v[64:67]
	s_waitcnt lgkmcnt(11)
	v_mfma_f32_16x16x32_bf16 v[68:71], v[138:141], v[48:51], 0
	s_waitcnt lgkmcnt(10)
	v_mfma_f32_16x16x32_bf16 v[68:71], v[142:145], v[52:55], v[68:71]
	v_mfma_f32_16x16x32_bf16 v[64:67], v[130:133], v[56:59], v[64:67]
	s_waitcnt lgkmcnt(9)
	v_mfma_f32_16x16x32_bf16 v[68:71], v[148:151], v[56:59], v[68:71]
	v_mfma_f32_16x16x32_bf16 v[64:67], v[134:137], v[60:63], v[64:67]
	s_waitcnt lgkmcnt(8)
	v_mfma_f32_16x16x32_bf16 v[68:71], v[152:155], v[60:63], v[68:71]
	v_add_u32_e32 v146, s2, v84
	ds_read_b128 v[130:133], v146
	ds_read_b128 v[134:137], v146 offset:64
	ds_read_b128 v[138:141], v146 offset:128
	ds_read_b128 v[142:145], v146 offset:192
	ds_read_b128 v[148:151], v146 offset:1088
	ds_read_b128 v[152:155], v146 offset:1152
	ds_read_b128 v[192:195], v146 offset:1216
	ds_read_b128 v[196:199], v146 offset:1280
	s_waitcnt lgkmcnt(14)
	v_mfma_f32_16x16x32_bf16 v[156:159], v[156:159], v[48:51], 0
	v_mfma_f32_16x16x32_bf16 v[156:159], v[160:163], v[52:55], v[156:159]
	s_waitcnt lgkmcnt(11)
	v_mfma_f32_16x16x32_bf16 v[160:163], v[172:175], v[48:51], 0
	s_waitcnt lgkmcnt(10)
	v_mfma_f32_16x16x32_bf16 v[160:163], v[176:179], v[52:55], v[160:163]
	v_mfma_f32_16x16x32_bf16 v[156:159], v[164:167], v[56:59], v[156:159]
	s_waitcnt lgkmcnt(9)
	v_mfma_f32_16x16x32_bf16 v[160:163], v[184:187], v[56:59], v[160:163]
	v_mfma_f32_16x16x32_bf16 v[156:159], v[168:171], v[60:63], v[156:159]
	s_waitcnt lgkmcnt(8)
	v_mfma_f32_16x16x32_bf16 v[160:163], v[188:191], v[60:63], v[160:163]
	v_add_u32_e32 v146, s41, v84
	ds_read_b128 v[164:167], v146
	ds_read_b128 v[168:171], v146 offset:64
	ds_read_b128 v[172:175], v146 offset:128
	ds_read_b128 v[176:179], v146 offset:192
	ds_read_b128 v[184:187], v146 offset:1088
	ds_read_b128 v[188:191], v146 offset:1152
	ds_read_b128 v[200:203], v146 offset:1216
	ds_read_b128 v[204:207], v146 offset:1280
	s_waitcnt lgkmcnt(14)
	v_mfma_f32_16x16x32_bf16 v[130:133], v[130:133], v[48:51], 0
	v_mfma_f32_16x16x32_bf16 v[130:133], v[134:137], v[52:55], v[130:133]
	s_waitcnt lgkmcnt(11)
	v_mfma_f32_16x16x32_bf16 v[134:137], v[148:151], v[48:51], 0
	v_mfma_f32_16x16x32_bf16 v[130:133], v[138:141], v[56:59], v[130:133]
	s_waitcnt lgkmcnt(10)
	v_mfma_f32_16x16x32_bf16 v[134:137], v[152:155], v[52:55], v[134:137]
	v_mfma_f32_16x16x32_bf16 v[130:133], v[142:145], v[60:63], v[130:133]
	s_waitcnt lgkmcnt(9)
	v_mfma_f32_16x16x32_bf16 v[134:137], v[192:195], v[56:59], v[134:137]
	s_waitcnt lgkmcnt(8)
	v_mfma_f32_16x16x32_bf16 v[134:137], v[196:199], v[60:63], v[134:137]
	v_add_u32_e32 v146, s40, v84
	ds_read_b128 v[138:141], v146
	ds_read_b128 v[142:145], v146 offset:64
	ds_read_b128 v[148:151], v146 offset:128
	ds_read_b128 v[152:155], v146 offset:192
	ds_read_b128 v[192:195], v146 offset:1088
	ds_read_b128 v[196:199], v146 offset:1152
	ds_read_b128 v[208:211], v146 offset:1216
	ds_read_b128 v[212:215], v146 offset:1280
	s_waitcnt lgkmcnt(14)
	v_mfma_f32_16x16x32_bf16 v[164:167], v[164:167], v[48:51], 0
	v_mfma_f32_16x16x32_bf16 v[164:167], v[168:171], v[52:55], v[164:167]
	s_waitcnt lgkmcnt(11)
	v_mfma_f32_16x16x32_bf16 v[168:171], v[184:187], v[48:51], 0
	s_waitcnt lgkmcnt(10)
	v_mfma_f32_16x16x32_bf16 v[168:171], v[188:191], v[52:55], v[168:171]
	v_mfma_f32_16x16x32_bf16 v[164:167], v[172:175], v[56:59], v[164:167]
	s_waitcnt lgkmcnt(9)
	v_mfma_f32_16x16x32_bf16 v[168:171], v[200:203], v[56:59], v[168:171]
	v_mfma_f32_16x16x32_bf16 v[164:167], v[176:179], v[60:63], v[164:167]
	s_waitcnt lgkmcnt(8)
	v_mfma_f32_16x16x32_bf16 v[168:171], v[204:207], v[60:63], v[168:171]
	s_waitcnt lgkmcnt(7)
	v_mfma_f32_16x16x32_bf16 v[138:141], v[138:141], v[48:51], 0
	s_waitcnt lgkmcnt(3)
	v_mfma_f32_16x16x32_bf16 v[48:51], v[192:195], v[48:51], 0
	s_waitcnt lgkmcnt(2)
	v_mfma_f32_16x16x32_bf16 v[48:51], v[196:199], v[52:55], v[48:51]
	v_mfma_f32_16x16x32_bf16 v[138:141], v[142:145], v[52:55], v[138:141]
	s_waitcnt lgkmcnt(1)
	v_mfma_f32_16x16x32_bf16 v[48:51], v[208:211], v[56:59], v[48:51]
	v_mfma_f32_16x16x32_bf16 v[138:141], v[148:151], v[56:59], v[138:141]
	s_waitcnt lgkmcnt(0)
	v_mfma_f32_16x16x32_bf16 v[48:51], v[212:215], v[60:63], v[48:51]
	v_mfma_f32_16x16x32_bf16 v[138:141], v[152:155], v[60:63], v[138:141]
	s_cmp_lg_u32 s60, 0
	s_cselect_b64 s[92:93], -1, 0
	s_or_b64 s[60:61], s[92:93], s[78:79]
	v_fmamk_f32 v52, v64, 0x3e0293ee, v89
	s_and_b64 vcc, s[60:61], s[4:5]
	v_cndmask_b32_e32 v52, v82, v52, vcc
	v_fmamk_f32 v53, v65, 0x3e0293ee, v90
	s_and_b64 vcc, s[60:61], s[6:7]
	v_cndmask_b32_e32 v53, v82, v53, vcc
	v_fmamk_f32 v55, v66, 0x3e0293ee, v91
	s_and_b64 vcc, s[60:61], s[8:9]
	v_cndmask_b32_e32 v55, v82, v55, vcc
	v_fmamk_f32 v56, v67, 0x3e0293ee, v92
	s_and_b64 vcc, s[60:61], s[10:11]
	v_cndmask_b32_e32 v56, v82, v56, vcc
	v_fmamk_f32 v57, v68, 0x3e0293ee, v93
	s_and_b64 vcc, s[60:61], s[12:13]
	v_cndmask_b32_e32 v57, v82, v57, vcc
	v_fmamk_f32 v58, v69, 0x3e0293ee, v94
	s_and_b64 vcc, s[60:61], s[14:15]
	v_cndmask_b32_e32 v58, v82, v58, vcc
	v_fmamk_f32 v59, v70, 0x3e0293ee, v95
	s_and_b64 vcc, s[60:61], s[16:17]
	v_cndmask_b32_e32 v59, v82, v59, vcc
	v_fmamk_f32 v60, v71, 0x3e0293ee, v96
	s_and_b64 vcc, s[60:61], s[18:19]
	v_cndmask_b32_e32 v60, v82, v60, vcc
	v_fmamk_f32 v61, v156, 0x3e0293ee, v97
	s_or_b64 vcc, s[92:93], s[80:81]
	v_fmamk_f32 v62, v157, 0x3e0293ee, v98
	v_fmamk_f32 v63, v158, 0x3e0293ee, v99
	v_fmamk_f32 v64, v159, 0x3e0293ee, v100
	v_fmamk_f32 v65, v160, 0x3e0293ee, v101
	v_fmamk_f32 v66, v161, 0x3e0293ee, v102
	v_fmamk_f32 v67, v162, 0x3e0293ee, v103
	v_fmamk_f32 v68, v163, 0x3e0293ee, v104
	v_cndmask_b32_e32 v61, v82, v61, vcc
	v_cndmask_b32_e32 v62, v82, v62, vcc
	v_cndmask_b32_e32 v63, v82, v63, vcc
	v_cndmask_b32_e32 v64, v82, v64, vcc
	v_cndmask_b32_e32 v65, v82, v65, vcc
	v_cndmask_b32_e32 v66, v82, v66, vcc
	v_cndmask_b32_e32 v67, v82, v67, vcc
	v_cndmask_b32_e32 v68, v82, v68, vcc
	v_fmamk_f32 v69, v130, 0x3e0293ee, v105
	s_or_b64 vcc, s[92:93], s[82:83]
	v_fmamk_f32 v130, v133, 0x3e0293ee, v108
	v_fmamk_f32 v70, v131, 0x3e0293ee, v106
	v_cndmask_b32_e32 v131, v82, v130, vcc
	v_fmamk_f32 v130, v134, 0x3e0293ee, v109
	v_fmamk_f32 v71, v132, 0x3e0293ee, v107
	v_cndmask_b32_e32 v132, v82, v130, vcc
	v_fmamk_f32 v130, v135, 0x3e0293ee, v110
	v_max3_f32 v54, v52, s74, v53
	v_cndmask_b32_e32 v133, v82, v130, vcc
	v_fmamk_f32 v130, v136, 0x3e0293ee, v111
	v_max3_f32 v54, v54, v55, v56
	v_cndmask_b32_e32 v134, v82, v130, vcc
	v_fmamk_f32 v130, v137, 0x3e0293ee, v112
	v_max3_f32 v54, v54, v57, v58
	v_cndmask_b32_e32 v69, v82, v69, vcc
	v_cndmask_b32_e32 v70, v82, v70, vcc
	v_cndmask_b32_e32 v71, v82, v71, vcc
	v_cndmask_b32_e32 v135, v82, v130, vcc
	v_fmamk_f32 v130, v164, 0x3e0293ee, v113
	s_or_b64 vcc, s[92:93], s[84:85]
	v_max3_f32 v54, v54, v59, v60
	v_cndmask_b32_e32 v136, v82, v130, vcc
	v_fmamk_f32 v130, v165, 0x3e0293ee, v114
	v_max3_f32 v54, v54, v61, v62
	v_cndmask_b32_e32 v137, v82, v130, vcc
	v_fmamk_f32 v130, v166, 0x3e0293ee, v115
	v_max3_f32 v54, v54, v63, v64
	v_cndmask_b32_e32 v142, v82, v130, vcc
	v_fmamk_f32 v130, v167, 0x3e0293ee, v116
	v_max3_f32 v54, v54, v65, v66
	v_cndmask_b32_e32 v143, v82, v130, vcc
	v_fmamk_f32 v130, v168, 0x3e0293ee, v117
	v_max3_f32 v54, v54, v67, v68
	v_cndmask_b32_e32 v144, v82, v130, vcc
	v_fmamk_f32 v130, v169, 0x3e0293ee, v118
	v_max3_f32 v54, v54, v69, v70
	v_cndmask_b32_e32 v145, v82, v130, vcc
	v_fmamk_f32 v130, v170, 0x3e0293ee, v119
	v_max3_f32 v54, v54, v71, v131
	v_cndmask_b32_e32 v146, v82, v130, vcc
	v_fmamk_f32 v130, v171, 0x3e0293ee, v120
	s_or_b64 s[60:61], s[92:93], s[86:87]
	v_max3_f32 v54, v54, v132, v133
	v_cndmask_b32_e32 v147, v82, v130, vcc
	v_fmamk_f32 v130, v138, 0x3e0293ee, v121
	s_and_b64 vcc, s[60:61], s[20:21]
	v_max3_f32 v54, v54, v134, v135
	v_cndmask_b32_e32 v138, v82, v130, vcc
	v_fmamk_f32 v130, v139, 0x3e0293ee, v122
	s_and_b64 vcc, s[60:61], s[22:23]
	v_max3_f32 v54, v54, v136, v137
	v_cndmask_b32_e32 v139, v82, v130, vcc
	v_fmamk_f32 v130, v140, 0x3e0293ee, v123
	s_and_b64 vcc, s[60:61], s[24:25]
	v_max3_f32 v54, v54, v142, v143
	v_cndmask_b32_e32 v140, v82, v130, vcc
	v_fmamk_f32 v130, v141, 0x3e0293ee, v124
	s_and_b64 vcc, s[60:61], s[26:27]
	v_max3_f32 v54, v54, v144, v145
	v_cndmask_b32_e32 v141, v82, v130, vcc
	v_fmamk_f32 v48, v48, 0x3e0293ee, v125
	s_and_b64 vcc, s[60:61], s[28:29]
	v_max3_f32 v54, v54, v146, v147
	v_cndmask_b32_e32 v48, v82, v48, vcc
	v_fmamk_f32 v49, v49, 0x3e0293ee, v126
	s_and_b64 vcc, s[60:61], s[30:31]
	v_max3_f32 v54, v54, v138, v139
	v_cndmask_b32_e32 v49, v82, v49, vcc
	v_fmamk_f32 v50, v50, 0x3e0293ee, v127
	s_and_b64 vcc, s[60:61], s[34:35]
	v_max3_f32 v54, v54, v140, v141
	v_cndmask_b32_e32 v50, v82, v50, vcc
	v_fmamk_f32 v51, v51, 0x3e0293ee, v85
	s_and_b64 vcc, s[60:61], s[36:37]
	v_max3_f32 v54, v54, v48, v49
	v_cndmask_b32_e32 v51, v82, v51, vcc
	v_max3_f32 v54, v54, v50, v51
	v_mov_b32_e32 v130, v54
	s_nop 1
	v_permlane16_swap_b32 v54, v130
	s_waitcnt lgkmcnt(0)
	v_max_f32_e32 v130, v130, v130
	v_max_f32_e32 v54, v54, v130
	v_mov_b32_e32 v130, v54
	s_nop 1
	v_permlane32_swap_b32 v54, v130
	s_waitcnt lgkmcnt(0)
	v_max_f32_e32 v130, v130, v130
	v_max_f32_e32 v130, v54, v130
	v_sub_f32_e32 v52, v52, v130
	v_exp_f32_e32 v52, v52
	v_sub_f32_e32 v53, v53, v130
	v_exp_f32_e32 v53, v53
	v_sub_f32_e32 v54, v55, v130
	v_exp_f32_e32 v54, v54
	v_sub_f32_e32 v55, v56, v130
	v_exp_f32_e32 v55, v55
	v_sub_f32_e32 v57, v57, v130
	v_add_f32_e32 v56, 0, v52
	v_exp_f32_e32 v57, v57
	v_sub_f32_e32 v58, v58, v130
	v_add_f32_e32 v56, v53, v56
	v_exp_f32_e32 v58, v58
	v_sub_f32_e32 v59, v59, v130
	v_add_f32_e32 v56, v54, v56
	v_exp_f32_e32 v59, v59
	v_sub_f32_e32 v60, v60, v130
	v_add_f32_e32 v56, v55, v56
	v_exp_f32_e32 v60, v60
	v_sub_f32_e32 v61, v61, v130
	v_add_f32_e32 v56, v57, v56
	v_exp_f32_e32 v181, v61
	v_sub_f32_e32 v61, v62, v130
	v_add_f32_e32 v56, v58, v56
	v_exp_f32_e32 v183, v61
	v_sub_f32_e32 v61, v63, v130
	v_add_f32_e32 v56, v59, v56
	v_exp_f32_e32 v192, v61
	v_sub_f32_e32 v61, v64, v130
	v_add_f32_e32 v56, v60, v56
	v_exp_f32_e32 v193, v61
	v_sub_f32_e32 v61, v65, v130
	v_add_f32_e32 v56, v181, v56
	v_exp_f32_e32 v194, v61
	v_sub_f32_e32 v61, v66, v130
	v_add_f32_e32 v56, v183, v56
	v_exp_f32_e32 v195, v61
	v_sub_f32_e32 v61, v67, v130
	v_add_f32_e32 v56, v192, v56
	v_exp_f32_e32 v196, v61
	v_sub_f32_e32 v61, v68, v130
	v_add_f32_e32 v56, v193, v56
	v_exp_f32_e32 v197, v61
	v_sub_f32_e32 v61, v69, v130
	v_add_f32_e32 v56, v194, v56
	v_exp_f32_e32 v200, v61
	v_sub_f32_e32 v61, v70, v130
	v_add_f32_e32 v56, v195, v56
	v_exp_f32_e32 v201, v61
	v_sub_f32_e32 v61, v71, v130
	v_add_f32_e32 v56, v196, v56
	v_exp_f32_e32 v202, v61
	v_sub_f32_e32 v61, v131, v130
	v_add_f32_e32 v56, v197, v56
	v_exp_f32_e32 v203, v61
	v_sub_f32_e32 v61, v132, v130
	v_add_f32_e32 v56, v200, v56
	v_exp_f32_e32 v204, v61
	v_sub_f32_e32 v61, v133, v130
	v_add_f32_e32 v56, v201, v56
	v_exp_f32_e32 v205, v61
	v_sub_f32_e32 v61, v134, v130
	v_add_f32_e32 v56, v202, v56
	v_exp_f32_e32 v206, v61
	v_sub_f32_e32 v61, v135, v130
	v_add_f32_e32 v56, v203, v56
	v_exp_f32_e32 v207, v61
	v_sub_f32_e32 v61, v136, v130
	v_add_f32_e32 v56, v204, v56
	v_exp_f32_e32 v208, v61
	v_sub_f32_e32 v61, v137, v130
	v_add_f32_e32 v56, v205, v56
	v_exp_f32_e32 v209, v61
	v_sub_f32_e32 v61, v142, v130
	v_add_f32_e32 v56, v206, v56
	v_exp_f32_e32 v210, v61
	v_sub_f32_e32 v61, v143, v130
	v_add_f32_e32 v56, v207, v56
	v_exp_f32_e32 v211, v61
	v_sub_f32_e32 v61, v144, v130
	v_add_f32_e32 v56, v208, v56
	v_exp_f32_e32 v144, v61
	v_sub_f32_e32 v61, v145, v130
	v_add_f32_e32 v56, v209, v56
	v_exp_f32_e32 v145, v61
	v_sub_f32_e32 v61, v146, v130
	v_add_f32_e32 v56, v210, v56
	v_exp_f32_e32 v146, v61
	v_sub_f32_e32 v61, v147, v130
	v_add_f32_e32 v56, v211, v56
	v_exp_f32_e32 v147, v61
	v_sub_f32_e32 v61, v138, v130
	v_add_f32_e32 v56, v144, v56
	v_exp_f32_e32 v132, v61
	v_sub_f32_e32 v61, v139, v130
	v_add_f32_e32 v56, v145, v56
	v_exp_f32_e32 v133, v61
	v_sub_f32_e32 v61, v140, v130
	v_add_f32_e32 v56, v146, v56
	v_exp_f32_e32 v134, v61
	v_sub_f32_e32 v61, v141, v130
	v_add_f32_e32 v56, v147, v56
	v_exp_f32_e32 v135, v61
	v_sub_f32_e32 v48, v48, v130
	v_add_f32_e32 v56, v132, v56
	v_exp_f32_e32 v136, v48
	v_sub_f32_e32 v48, v49, v130
	v_add_f32_e32 v56, v133, v56
	v_exp_f32_e32 v137, v48
	v_sub_f32_e32 v48, v50, v130
	v_add_f32_e32 v56, v134, v56
	v_exp_f32_e32 v138, v48
	v_sub_f32_e32 v48, v51, v130
	v_add_f32_e32 v56, v135, v56
	v_exp_f32_e32 v139, v48
	v_add_f32_e32 v48, v136, v56
	v_add_f32_e32 v48, v137, v48
	v_add_f32_e32 v48, v138, v48
	v_add_f32_e32 v48, v139, v48
	v_mov_b32_e32 v49, v48
	s_nop 1
	v_permlane16_swap_b32 v48, v49
	v_cvt_pk_bf16_f32 v176, v52, v53
	v_cvt_pk_bf16_f32 v177, v54, v55
	v_cvt_pk_bf16_f32 v178, v57, v58
	v_cvt_pk_bf16_f32 v179, v59, v60
	s_waitcnt lgkmcnt(0)
	v_add_f32_e32 v48, v48, v49
	v_mov_b32_e32 v49, v48
	s_nop 1
	v_permlane32_swap_b32 v48, v49
	s_waitcnt lgkmcnt(0)
	v_add_f32_e32 v131, v48, v49
	v_add_u32_e32 v48, s38, v88
	ds_read_b64_tr_b16 v[140:141], v48 offset:0
	ds_read_b64_tr_b16 v[142:143], v48 offset:0x440
	ds_read_b64_tr_b16 v[148:149], v48 offset:32
	ds_read_b64_tr_b16 v[150:151], v48 offset:0x460
	ds_read_b64_tr_b16 v[152:153], v48 offset:64
	ds_read_b64_tr_b16 v[154:155], v48 offset:0x480
	ds_read_b64_tr_b16 v[156:157], v48 offset:0x60
	ds_read_b64_tr_b16 v[158:159], v48 offset:0x4a0
	ds_read_b64_tr_b16 v[160:161], v48 offset:0x80
	ds_read_b64_tr_b16 v[162:163], v48 offset:0x4c0
	ds_read_b64_tr_b16 v[164:165], v48 offset:0xa0
	ds_read_b64_tr_b16 v[166:167], v48 offset:0x4e0
	ds_read_b64_tr_b16 v[168:169], v48 offset:0xc0
	ds_read_b64_tr_b16 v[170:171], v48 offset:0x500
	ds_read_b64_tr_b16 v[172:173], v48 offset:0xe0
	ds_read_b64_tr_b16 v[174:175], v48 offset:0x520
	s_waitcnt lgkmcnt(0)
	v_add_u32_e32 v198, s33, v88
	ds_read_b64_tr_b16 v[184:185], v198 offset:0
	ds_read_b64_tr_b16 v[186:187], v198 offset:0x440
	ds_read_b64_tr_b16 v[188:189], v198 offset:32
	ds_read_b64_tr_b16 v[190:191], v198 offset:0x460
	ds_read_b64_tr_b16 v[68:69], v198 offset:64
	ds_read_b64_tr_b16 v[70:71], v198 offset:0x480
	ds_read_b64_tr_b16 v[64:65], v198 offset:0x60
	ds_read_b64_tr_b16 v[66:67], v198 offset:0x4a0
	ds_read_b64_tr_b16 v[60:61], v198 offset:0x80
	ds_read_b64_tr_b16 v[62:63], v198 offset:0x4c0
	ds_read_b64_tr_b16 v[56:57], v198 offset:0xa0
	ds_read_b64_tr_b16 v[58:59], v198 offset:0x4e0
	ds_read_b64_tr_b16 v[52:53], v198 offset:0xc0
	ds_read_b64_tr_b16 v[54:55], v198 offset:0x500
	ds_read_b64_tr_b16 v[48:49], v198 offset:0xe0
	ds_read_b64_tr_b16 v[50:51], v198 offset:0x520
	s_waitcnt lgkmcnt(0)
	v_mfma_f32_16x16x32_bf16 v[140:143], v[140:143], v[176:179], 0
	v_mfma_f32_16x16x32_bf16 v[148:151], v[148:151], v[176:179], 0
	v_mfma_f32_16x16x32_bf16 v[152:155], v[152:155], v[176:179], 0
	v_mfma_f32_16x16x32_bf16 v[156:159], v[156:159], v[176:179], 0
	v_mfma_f32_16x16x32_bf16 v[160:163], v[160:163], v[176:179], 0
	v_mfma_f32_16x16x32_bf16 v[164:167], v[164:167], v[176:179], 0
	v_mfma_f32_16x16x32_bf16 v[168:171], v[168:171], v[176:179], 0
	v_mfma_f32_16x16x32_bf16 v[172:175], v[172:175], v[176:179], 0
	v_cvt_pk_bf16_f32 v176, v181, v183
	v_cvt_pk_bf16_f32 v177, v192, v193
	v_cvt_pk_bf16_f32 v178, v194, v195
	v_cvt_pk_bf16_f32 v179, v196, v197
	s_nop 1
	v_mfma_f32_16x16x32_bf16 v[140:143], v[184:187], v[176:179], v[140:143]
	v_add_u32_e32 v181, s2, v88
	ds_read_b64_tr_b16 v[184:185], v181 offset:0
	ds_read_b64_tr_b16 v[186:187], v181 offset:0x440
	v_mfma_f32_16x16x32_bf16 v[148:151], v[188:191], v[176:179], v[148:151]
	ds_read_b64_tr_b16 v[188:189], v181 offset:32
	ds_read_b64_tr_b16 v[190:191], v181 offset:0x460
	ds_read_b64_tr_b16 v[192:193], v181 offset:64
	ds_read_b64_tr_b16 v[194:195], v181 offset:0x480
	v_mfma_f32_16x16x32_bf16 v[68:71], v[68:71], v[176:179], v[152:155]
	ds_read_b64_tr_b16 v[152:153], v181 offset:0x60
	ds_read_b64_tr_b16 v[154:155], v181 offset:0x4a0
	v_cvt_pk_bf16_f32 v200, v200, v201
	v_mfma_f32_16x16x32_bf16 v[64:67], v[64:67], v[176:179], v[156:159]
	ds_read_b64_tr_b16 v[156:157], v181 offset:0x80
	ds_read_b64_tr_b16 v[158:159], v181 offset:0x4c0
	ds_read_b64_tr_b16 v[196:197], v181 offset:0xa0
	ds_read_b64_tr_b16 v[198:199], v181 offset:0x4e0
	v_mfma_f32_16x16x32_bf16 v[60:63], v[60:63], v[176:179], v[160:163]
	ds_read_b64_tr_b16 v[160:161], v181 offset:0xc0
	ds_read_b64_tr_b16 v[162:163], v181 offset:0x500
	v_cvt_pk_bf16_f32 v201, v202, v203
	v_mfma_f32_16x16x32_bf16 v[56:59], v[56:59], v[176:179], v[164:167]
	ds_read_b64_tr_b16 v[164:165], v181 offset:0xe0
	ds_read_b64_tr_b16 v[166:167], v181 offset:0x520
	s_waitcnt lgkmcnt(0)
	v_mfma_f32_16x16x32_bf16 v[48:51], v[48:51], v[176:179], v[172:175]
	v_cvt_pk_bf16_f32 v202, v204, v205
	v_cvt_pk_bf16_f32 v203, v206, v207
	v_mfma_f32_16x16x32_bf16 v[52:55], v[52:55], v[176:179], v[168:171]
	v_add_u32_e32 v181, s41, v88
	ds_read_b64_tr_b16 v[168:169], v181 offset:0
	ds_read_b64_tr_b16 v[170:171], v181 offset:0x440
	ds_read_b64_tr_b16 v[172:173], v181 offset:32
	ds_read_b64_tr_b16 v[174:175], v181 offset:0x460
	ds_read_b64_tr_b16 v[176:177], v181 offset:64
	ds_read_b64_tr_b16 v[178:179], v181 offset:0x480
	v_mfma_f32_16x16x32_bf16 v[140:143], v[184:187], v[200:203], v[140:143]
	ds_read_b64_tr_b16 v[184:185], v181 offset:0x60
	ds_read_b64_tr_b16 v[186:187], v181 offset:0x4a0
	v_mfma_f32_16x16x32_bf16 v[64:67], v[152:155], v[200:203], v[64:67]
	ds_read_b64_tr_b16 v[152:153], v181 offset:0x80
	ds_read_b64_tr_b16 v[154:155], v181 offset:0x4c0
	v_mfma_f32_16x16x32_bf16 v[148:151], v[188:191], v[200:203], v[148:151]
	ds_read_b64_tr_b16 v[188:189], v181 offset:0xa0
	ds_read_b64_tr_b16 v[190:191], v181 offset:0x4e0
	v_mfma_f32_16x16x32_bf16 v[60:63], v[156:159], v[200:203], v[60:63]
	ds_read_b64_tr_b16 v[156:157], v181 offset:0xc0
	ds_read_b64_tr_b16 v[158:159], v181 offset:0x500
	v_mfma_f32_16x16x32_bf16 v[68:71], v[192:195], v[200:203], v[68:71]
	ds_read_b64_tr_b16 v[192:193], v181 offset:0xe0
	ds_read_b64_tr_b16 v[194:195], v181 offset:0x520
	s_waitcnt lgkmcnt(0)
	v_mfma_f32_16x16x32_bf16 v[48:51], v[164:167], v[200:203], v[48:51]
	v_mfma_f32_16x16x32_bf16 v[56:59], v[196:199], v[200:203], v[56:59]
	v_cvt_pk_bf16_f32 v196, v208, v209
	v_cvt_pk_bf16_f32 v197, v210, v211
	v_cvt_pk_bf16_f32 v198, v144, v145
	v_mfma_f32_16x16x32_bf16 v[52:55], v[160:163], v[200:203], v[52:55]
	v_cvt_pk_bf16_f32 v199, v146, v147
	v_add_u32_e32 v144, s40, v88
	ds_read_b64_tr_b16 v[160:161], v144 offset:0
	ds_read_b64_tr_b16 v[162:163], v144 offset:0x440
	ds_read_b64_tr_b16 v[164:165], v144 offset:32
	ds_read_b64_tr_b16 v[166:167], v144 offset:0x460
	s_nop 0
	v_mfma_f32_16x16x32_bf16 v[140:143], v[168:171], v[196:199], v[140:143]
	ds_read_b64_tr_b16 v[168:169], v144 offset:64
	ds_read_b64_tr_b16 v[170:171], v144 offset:0x480
	v_mfma_f32_16x16x32_bf16 v[148:151], v[172:175], v[196:199], v[148:151]
	ds_read_b64_tr_b16 v[172:173], v144 offset:0x60
	ds_read_b64_tr_b16 v[174:175], v144 offset:0x4a0
	v_mfma_f32_16x16x32_bf16 v[60:63], v[152:155], v[196:199], v[60:63]
	ds_read_b64_tr_b16 v[152:153], v144 offset:0x80
	ds_read_b64_tr_b16 v[154:155], v144 offset:0x4c0
	v_mfma_f32_16x16x32_bf16 v[68:71], v[176:179], v[196:199], v[68:71]
	ds_read_b64_tr_b16 v[176:177], v144 offset:0xa0
	ds_read_b64_tr_b16 v[178:179], v144 offset:0x4e0
	v_mfma_f32_16x16x32_bf16 v[64:67], v[184:187], v[196:199], v[64:67]
	ds_read_b64_tr_b16 v[184:185], v144 offset:0xc0
	ds_read_b64_tr_b16 v[186:187], v144 offset:0x500
	v_mfma_f32_16x16x32_bf16 v[52:55], v[156:159], v[196:199], v[52:55]
	ds_read_b64_tr_b16 v[156:157], v144 offset:0xe0
	ds_read_b64_tr_b16 v[158:159], v144 offset:0x520
	s_waitcnt lgkmcnt(0)
	v_mfma_f32_16x16x32_bf16 v[56:59], v[188:191], v[196:199], v[56:59]
	v_mfma_f32_16x16x32_bf16 v[188:191], v[192:195], v[196:199], v[48:51]
	v_cvt_pk_bf16_f32 v132, v132, v133
	v_cvt_pk_bf16_f32 v133, v134, v135
	v_cvt_pk_bf16_f32 v134, v136, v137
	v_cvt_pk_bf16_f32 v135, v138, v139
	v_rcp_f32_e32 v144, v131
	v_add_u32_e32 v48, s95, v129
	v_mfma_f32_16x16x32_bf16 v[136:139], v[160:163], v[132:135], v[140:143]
	v_ashrrev_i32_e32 v49, 31, v48
	v_lshl_add_u64 v[48:49], s[64:65], 0, v[48:49]
	v_lshlrev_b64 v[50:51], 11, v[48:49]
	v_mfma_f32_16x16x32_bf16 v[140:143], v[164:167], v[132:135], v[148:151]
	v_lshl_add_u64 v[146:147], v[78:79], 0, v[50:51]
	s_nop 2
	v_pk_mul_f32 v[50:51], v[144:145], v[136:137] op_sel_hi:[0,1]
	v_pk_mul_f32 v[136:137], v[144:145], v[138:139] op_sel_hi:[0,1]
	v_mfma_f32_16x16x32_bf16 v[68:71], v[168:171], v[132:135], v[68:71]
	v_cvt_pk_bf16_f32 v50, v50, v51
	v_cvt_pk_bf16_f32 v51, v136, v137
	global_store_dwordx2 v[146:147], v[50:51], off
	v_mfma_f32_16x16x32_bf16 v[64:67], v[172:175], v[132:135], v[64:67]
	v_mul_f32_e64 v50, v144, v140
	v_mul_f32_e64 v51, v144, v141
	v_pk_mul_f32 v[136:137], v[144:145], v[142:143] op_sel_hi:[0,1]
	v_cvt_pk_bf16_f32 v50, v50, v51
	v_cvt_pk_bf16_f32 v51, v136, v137
	v_mfma_f32_16x16x32_bf16 v[60:63], v[152:155], v[132:135], v[60:63]
	global_store_dwordx2 v[146:147], v[50:51], off offset:32
	v_pk_mul_f32 v[136:137], v[144:145], v[70:71] op_sel_hi:[0,1]
	v_mfma_f32_16x16x32_bf16 v[50:53], v[184:187], v[132:135], v[52:55]
	s_nop 2
	v_mul_f32_e64 v54, v144, v68
	v_mul_f32_e64 v55, v144, v69
	v_cvt_pk_bf16_f32 v54, v54, v55
	v_cvt_pk_bf16_f32 v55, v136, v137
	v_mfma_f32_16x16x32_bf16 v[56:59], v[176:179], v[132:135], v[56:59]
	global_store_dwordx2 v[146:147], v[54:55], off offset:64
	v_pk_mul_f32 v[54:55], v[144:145], v[64:65] op_sel_hi:[0,1]
	v_pk_mul_f32 v[64:65], v[144:145], v[66:67] op_sel_hi:[0,1]
	v_mfma_f32_16x16x32_bf16 v[68:71], v[156:159], v[132:135], v[188:191]
	v_cvt_pk_bf16_f32 v54, v54, v55
	v_cvt_pk_bf16_f32 v55, v64, v65
	global_store_dwordx2 v[146:147], v[54:55], off offset:96
	v_pk_mul_f32 v[54:55], v[144:145], v[60:61] op_sel_hi:[0,1]
	v_pk_mul_f32 v[60:61], v[144:145], v[62:63] op_sel_hi:[0,1]
	v_pk_mul_f32 v[50:51], v[144:145], v[50:51] op_sel_hi:[0,1]
	v_pk_mul_f32 v[52:53], v[144:145], v[52:53] op_sel_hi:[0,1]
	v_cvt_pk_bf16_f32 v54, v54, v55
	v_cvt_pk_bf16_f32 v55, v60, v61
	v_cvt_pk_bf16_f32 v50, v50, v51
	v_cvt_pk_bf16_f32 v51, v52, v53
	global_store_dwordx2 v[146:147], v[54:55], off offset:128
	v_pk_mul_f32 v[54:55], v[144:145], v[56:57] op_sel_hi:[0,1]
	v_pk_mul_f32 v[56:57], v[144:145], v[58:59] op_sel_hi:[0,1]
	global_store_dwordx2 v[146:147], v[50:51], off offset:192
	v_pk_mul_f32 v[50:51], v[144:145], v[68:69] op_sel_hi:[0,1]
	v_pk_mul_f32 v[52:53], v[144:145], v[70:71] op_sel_hi:[0,1]
	v_cvt_pk_bf16_f32 v54, v54, v55
	v_cvt_pk_bf16_f32 v55, v56, v57
	v_cvt_pk_bf16_f32 v50, v50, v51
	v_cvt_pk_bf16_f32 v51, v52, v53
	global_store_dwordx2 v[146:147], v[54:55], off offset:160
	global_store_dwordx2 v[146:147], v[50:51], off offset:224
	s_and_saveexec_b64 s[40:41], s[0:1]
	s_cbranch_execz .LBB0_256
	v_log_f32_e32 v50, v131
	v_lshlrev_b64 v[48:49], 5, v[48:49]
	v_lshl_add_u64 v[48:49], s[88:89], 0, v[48:49]
	v_add_f32_e32 v50, v130, v50
	v_mul_f32_e32 v50, 0x3f317218, v50
	global_store_dword v[48:49], v50, off

.Lpadskip_1:
	s_branch .Lpadskip_3
	s_nop 0
	s_nop 0
	s_nop 0
	s_nop 0
	s_nop 0
	s_nop 0
	s_nop 0
	s_nop 0
	s_nop 0
	s_nop 0
	s_nop 0
	s_nop 0
	s_nop 0
	s_nop 0
	s_nop 0
	s_nop 0
	s_nop 0
	s_nop 0
	s_nop 0
	s_nop 0
	s_nop 0
	s_nop 0
	s_nop 0
	s_nop 0
	s_nop 0
	s_nop 0
	s_nop 0
	s_nop 0
	s_nop 0
	s_nop 0
	s_nop 0
	s_nop 0
	s_nop 0
	s_nop 0
	s_nop 0
	s_nop 0
	s_nop 0
	s_nop 0
	s_nop 0
	s_nop 0
	s_nop 0
	s_nop 0
	s_nop 0
	s_nop 0
	s_nop 0
	s_nop 0
	s_nop 0
	s_nop 0
	s_nop 0
	s_nop 0
	s_nop 0
	s_nop 0
	s_nop 0
	s_nop 0
	s_nop 0
	s_nop 0
	s_nop 0
	s_nop 0
	s_nop 0

.LBB0_414:
	s_add_i32 s40, s53, -1
	s_add_i32 s42, s52, s3
	s_and_b32 s94, s40, 1
	s_and_b32 s43, s53, 1
	s_and_b64 s[40:41], s[64:65], exec
	s_cselect_b32 s40, s94, s43
	s_mul_i32 s63, s40, 0x11000
	s_add_i32 s63, s63, s97
	s_and_b64 s[40:41], s[66:67], exec
	s_cselect_b32 s40, s94, s43
	s_mul_i32 s62, s40, 0x11000
	s_add_i32 s62, s62, s0
	s_and_b64 s[40:41], s[68:69], exec
	v_add_u32_e32 v150, s63, v84
	v_add_u32_e32 v178, s62, v84
	v_lshlrev_b32_e32 v129, s48, v64
	s_cselect_b32 s40, s94, s43
	ds_read_b128 v[64:67], v150
	ds_read_b128 v[68:71], v150 offset:64
	ds_read_b128 v[130:133], v150 offset:128
	ds_read_b128 v[134:137], v150 offset:192
	ds_read_b128 v[138:141], v150 offset:1088
	ds_read_b128 v[142:145], v150 offset:1152
	ds_read_b128 v[146:149], v150 offset:1216
	ds_read_b128 v[150:153], v150 offset:1280
	ds_read_b128 v[154:157], v178
	ds_read_b128 v[158:161], v178 offset:64
	ds_read_b128 v[162:165], v178 offset:128
	ds_read_b128 v[166:169], v178 offset:192
	ds_read_b128 v[170:173], v178 offset:1088
	ds_read_b128 v[174:177], v178 offset:1152
	ds_read_b128 v[184:187], v178 offset:1216
	ds_read_b128 v[188:191], v178 offset:1280
	s_mul_i32 s95, s40, 0x11000
	s_add_i32 s95, s95, s1
	s_and_b64 s[40:41], s[70:71], exec
	s_cselect_b32 s40, s94, s43
	s_mul_i32 s41, s40, 0x11000
	s_add_i32 s41, s41, s93
	s_and_b64 s[60:61], s[72:73], exec
	s_cselect_b32 s40, s94, s43
	s_mul_i32 s40, s40, 0x11000
	s_add_i32 s40, s40, s97
	s_waitcnt lgkmcnt(14)
	v_mfma_f32_16x16x32_bf16 v[64:67], v[64:67], v[48:51], 0
	v_mfma_f32_16x16x32_bf16 v[64:67], v[68:71], v[52:55], v[64:67]
	s_waitcnt lgkmcnt(11)
	v_mfma_f32_16x16x32_bf16 v[68:71], v[138:141], v[48:51], 0
	s_waitcnt lgkmcnt(10)
	v_mfma_f32_16x16x32_bf16 v[68:71], v[142:145], v[52:55], v[68:71]
	v_mfma_f32_16x16x32_bf16 v[64:67], v[130:133], v[56:59], v[64:67]
	s_waitcnt lgkmcnt(9)
	v_mfma_f32_16x16x32_bf16 v[68:71], v[146:149], v[56:59], v[68:71]
	v_mfma_f32_16x16x32_bf16 v[64:67], v[134:137], v[60:63], v[64:67]
	s_waitcnt lgkmcnt(8)
	v_mfma_f32_16x16x32_bf16 v[68:71], v[150:153], v[60:63], v[68:71]
	v_add_u32_e32 v178, s95, v84
	ds_read_b128 v[130:133], v178
	ds_read_b128 v[134:137], v178 offset:64
	ds_read_b128 v[138:141], v178 offset:128
	ds_read_b128 v[142:145], v178 offset:192
	ds_read_b128 v[146:149], v178 offset:1088
	ds_read_b128 v[150:153], v178 offset:1152
	ds_read_b128 v[192:195], v178 offset:1216
	ds_read_b128 v[196:199], v178 offset:1280
	s_waitcnt lgkmcnt(14)
	v_mfma_f32_16x16x32_bf16 v[154:157], v[154:157], v[48:51], 0
	v_mfma_f32_16x16x32_bf16 v[154:157], v[158:161], v[52:55], v[154:157]
	s_waitcnt lgkmcnt(11)
	v_mfma_f32_16x16x32_bf16 v[158:161], v[170:173], v[48:51], 0
	s_waitcnt lgkmcnt(10)
	v_mfma_f32_16x16x32_bf16 v[158:161], v[174:177], v[52:55], v[158:161]
	v_mfma_f32_16x16x32_bf16 v[154:157], v[162:165], v[56:59], v[154:157]
	s_waitcnt lgkmcnt(9)
	v_mfma_f32_16x16x32_bf16 v[158:161], v[184:187], v[56:59], v[158:161]
	v_mfma_f32_16x16x32_bf16 v[154:157], v[166:169], v[60:63], v[154:157]
	s_waitcnt lgkmcnt(8)
	v_mfma_f32_16x16x32_bf16 v[158:161], v[188:191], v[60:63], v[158:161]
	v_add_u32_e32 v178, s41, v84
	ds_read_b128 v[162:165], v178
	ds_read_b128 v[166:169], v178 offset:64
	ds_read_b128 v[170:173], v178 offset:128
	ds_read_b128 v[174:177], v178 offset:192
	ds_read_b128 v[184:187], v178 offset:1088
	ds_read_b128 v[188:191], v178 offset:1152
	ds_read_b128 v[200:203], v178 offset:1216
	ds_read_b128 v[204:207], v178 offset:1280
	s_waitcnt lgkmcnt(14)
	v_mfma_f32_16x16x32_bf16 v[130:133], v[130:133], v[48:51], 0
	v_mfma_f32_16x16x32_bf16 v[130:133], v[134:137], v[52:55], v[130:133]
	s_waitcnt lgkmcnt(11)
	v_mfma_f32_16x16x32_bf16 v[134:137], v[146:149], v[48:51], 0
	v_mfma_f32_16x16x32_bf16 v[130:133], v[138:141], v[56:59], v[130:133]
	s_waitcnt lgkmcnt(10)
	v_mfma_f32_16x16x32_bf16 v[134:137], v[150:153], v[52:55], v[134:137]
	v_mfma_f32_16x16x32_bf16 v[130:133], v[142:145], v[60:63], v[130:133]
	s_waitcnt lgkmcnt(9)
	v_mfma_f32_16x16x32_bf16 v[134:137], v[192:195], v[56:59], v[134:137]
	s_waitcnt lgkmcnt(8)
	v_mfma_f32_16x16x32_bf16 v[134:137], v[196:199], v[60:63], v[134:137]
	v_add_u32_e32 v178, s40, v84
	ds_read_b128 v[138:141], v178
	ds_read_b128 v[142:145], v178 offset:64
	ds_read_b128 v[146:149], v178 offset:128
	ds_read_b128 v[150:153], v178 offset:192
	ds_read_b128 v[192:195], v178 offset:1088
	ds_read_b128 v[196:199], v178 offset:1152
	ds_read_b128 v[208:211], v178 offset:1216
	ds_read_b128 v[212:215], v178 offset:1280
	s_waitcnt lgkmcnt(14)
	v_mfma_f32_16x16x32_bf16 v[162:165], v[162:165], v[48:51], 0
	v_mfma_f32_16x16x32_bf16 v[162:165], v[166:169], v[52:55], v[162:165]
	s_waitcnt lgkmcnt(11)
	v_mfma_f32_16x16x32_bf16 v[166:169], v[184:187], v[48:51], 0
	s_waitcnt lgkmcnt(10)
	v_mfma_f32_16x16x32_bf16 v[166:169], v[188:191], v[52:55], v[166:169]
	v_mfma_f32_16x16x32_bf16 v[162:165], v[170:173], v[56:59], v[162:165]
	s_waitcnt lgkmcnt(9)
	v_mfma_f32_16x16x32_bf16 v[166:169], v[200:203], v[56:59], v[166:169]
	v_mfma_f32_16x16x32_bf16 v[162:165], v[174:177], v[60:63], v[162:165]
	s_waitcnt lgkmcnt(8)
	v_mfma_f32_16x16x32_bf16 v[166:169], v[204:207], v[60:63], v[166:169]
	s_waitcnt lgkmcnt(7)
	v_mfma_f32_16x16x32_bf16 v[138:141], v[138:141], v[48:51], 0
	s_waitcnt lgkmcnt(3)
	v_mfma_f32_16x16x32_bf16 v[48:51], v[192:195], v[48:51], 0
	s_waitcnt lgkmcnt(2)
	v_mfma_f32_16x16x32_bf16 v[48:51], v[196:199], v[52:55], v[48:51]
	v_mfma_f32_16x16x32_bf16 v[138:141], v[142:145], v[52:55], v[138:141]
	s_waitcnt lgkmcnt(1)
	v_mfma_f32_16x16x32_bf16 v[48:51], v[208:211], v[56:59], v[48:51]
	v_mfma_f32_16x16x32_bf16 v[138:141], v[146:149], v[56:59], v[138:141]
	s_waitcnt lgkmcnt(0)
	v_mfma_f32_16x16x32_bf16 v[48:51], v[212:215], v[60:63], v[48:51]
	v_mfma_f32_16x16x32_bf16 v[138:141], v[150:153], v[60:63], v[138:141]
	s_cmp_lg_u32 s42, 0
	s_cselect_b64 s[60:61], -1, 0
	s_or_b64 s[42:43], s[60:61], s[74:75]
	v_fmamk_f32 v52, v64, 0x3e0293ee, v89
	s_and_b64 vcc, s[42:43], s[6:7]
	v_cndmask_b32_e32 v52, v82, v52, vcc
	v_fmamk_f32 v53, v65, 0x3e0293ee, v90
	s_and_b64 vcc, s[42:43], s[8:9]
	v_cndmask_b32_e32 v53, v82, v53, vcc
	v_fmamk_f32 v55, v66, 0x3e0293ee, v91
	s_and_b64 vcc, s[42:43], s[10:11]
	v_cndmask_b32_e32 v55, v82, v55, vcc
	v_fmamk_f32 v56, v67, 0x3e0293ee, v92
	s_and_b64 vcc, s[42:43], s[12:13]
	v_cndmask_b32_e32 v56, v82, v56, vcc
	v_fmamk_f32 v57, v68, 0x3e0293ee, v93
	s_and_b64 vcc, s[42:43], s[14:15]
	v_cndmask_b32_e32 v57, v82, v57, vcc
	v_fmamk_f32 v58, v69, 0x3e0293ee, v94
	s_and_b64 vcc, s[42:43], s[16:17]
	v_cndmask_b32_e32 v58, v82, v58, vcc
	v_fmamk_f32 v59, v70, 0x3e0293ee, v95
	s_and_b64 vcc, s[42:43], s[18:19]
	v_cndmask_b32_e32 v59, v82, v59, vcc
	v_fmamk_f32 v60, v71, 0x3e0293ee, v96
	s_and_b64 vcc, s[42:43], s[20:21]
	v_cndmask_b32_e32 v60, v82, v60, vcc
	v_fmamk_f32 v61, v154, 0x3e0293ee, v97
	s_or_b64 vcc, s[60:61], s[76:77]
	v_fmamk_f32 v62, v155, 0x3e0293ee, v98
	v_fmamk_f32 v63, v156, 0x3e0293ee, v99
	v_fmamk_f32 v64, v157, 0x3e0293ee, v100
	v_fmamk_f32 v65, v158, 0x3e0293ee, v101
	v_fmamk_f32 v66, v159, 0x3e0293ee, v102
	v_fmamk_f32 v67, v160, 0x3e0293ee, v103
	v_fmamk_f32 v68, v161, 0x3e0293ee, v104
	v_cndmask_b32_e32 v61, v82, v61, vcc
	v_cndmask_b32_e32 v62, v82, v62, vcc
	v_cndmask_b32_e32 v63, v82, v63, vcc
	v_cndmask_b32_e32 v64, v82, v64, vcc
	v_cndmask_b32_e32 v65, v82, v65, vcc
	v_cndmask_b32_e32 v66, v82, v66, vcc
	v_cndmask_b32_e32 v67, v82, v67, vcc
	v_cndmask_b32_e32 v68, v82, v68, vcc
	v_fmamk_f32 v69, v130, 0x3e0293ee, v105
	s_or_b64 vcc, s[60:61], s[78:79]
	v_fmamk_f32 v130, v133, 0x3e0293ee, v108
	v_fmamk_f32 v70, v131, 0x3e0293ee, v106
	v_cndmask_b32_e32 v131, v82, v130, vcc
	v_fmamk_f32 v130, v134, 0x3e0293ee, v109
	s_mov_b32 s33, 0xff800000
	v_fmamk_f32 v71, v132, 0x3e0293ee, v107
	v_cndmask_b32_e32 v132, v82, v130, vcc
	v_fmamk_f32 v130, v135, 0x3e0293ee, v110
	v_max3_f32 v54, v52, s33, v53
	v_cndmask_b32_e32 v133, v82, v130, vcc
	v_fmamk_f32 v130, v136, 0x3e0293ee, v111
	v_max3_f32 v54, v54, v55, v56
	v_cndmask_b32_e32 v134, v82, v130, vcc
	v_fmamk_f32 v130, v137, 0x3e0293ee, v112
	v_max3_f32 v54, v54, v57, v58
	v_cndmask_b32_e32 v69, v82, v69, vcc
	v_cndmask_b32_e32 v70, v82, v70, vcc
	v_cndmask_b32_e32 v71, v82, v71, vcc
	v_cndmask_b32_e32 v135, v82, v130, vcc
	v_fmamk_f32 v130, v162, 0x3e0293ee, v113
	s_or_b64 vcc, s[60:61], s[80:81]
	v_max3_f32 v54, v54, v59, v60
	v_cndmask_b32_e32 v136, v82, v130, vcc
	v_fmamk_f32 v130, v163, 0x3e0293ee, v114
	v_max3_f32 v54, v54, v61, v62
	v_cndmask_b32_e32 v137, v82, v130, vcc
	v_fmamk_f32 v130, v164, 0x3e0293ee, v115
	v_max3_f32 v54, v54, v63, v64
	v_cndmask_b32_e32 v142, v82, v130, vcc
	v_fmamk_f32 v130, v165, 0x3e0293ee, v116
	v_max3_f32 v54, v54, v65, v66
	v_cndmask_b32_e32 v143, v82, v130, vcc
	v_fmamk_f32 v130, v166, 0x3e0293ee, v117
	v_max3_f32 v54, v54, v67, v68
	v_cndmask_b32_e32 v144, v82, v130, vcc
	v_fmamk_f32 v130, v167, 0x3e0293ee, v118
	v_max3_f32 v54, v54, v69, v70
	v_cndmask_b32_e32 v145, v82, v130, vcc
	v_fmamk_f32 v130, v168, 0x3e0293ee, v119
	v_max3_f32 v54, v54, v71, v131
	v_cndmask_b32_e32 v146, v82, v130, vcc
	v_fmamk_f32 v130, v169, 0x3e0293ee, v120
	s_or_b64 s[42:43], s[60:61], s[82:83]
	v_max3_f32 v54, v54, v132, v133
	v_cndmask_b32_e32 v147, v82, v130, vcc
	v_fmamk_f32 v130, v138, 0x3e0293ee, v121
	s_and_b64 vcc, s[42:43], s[22:23]
	v_max3_f32 v54, v54, v134, v135
	v_cndmask_b32_e32 v138, v82, v130, vcc
	v_fmamk_f32 v130, v139, 0x3e0293ee, v122
	s_and_b64 vcc, s[42:43], s[24:25]
	v_max3_f32 v54, v54, v136, v137
	v_cndmask_b32_e32 v139, v82, v130, vcc
	v_fmamk_f32 v130, v140, 0x3e0293ee, v123
	s_and_b64 vcc, s[42:43], s[26:27]
	v_max3_f32 v54, v54, v142, v143
	v_cndmask_b32_e32 v140, v82, v130, vcc
	v_fmamk_f32 v130, v141, 0x3e0293ee, v124
	s_and_b64 vcc, s[42:43], s[28:29]
	v_max3_f32 v54, v54, v144, v145
	v_cndmask_b32_e32 v141, v82, v130, vcc
	v_fmamk_f32 v48, v48, 0x3e0293ee, v125
	s_and_b64 vcc, s[42:43], s[30:31]
	v_max3_f32 v54, v54, v146, v147
	v_cndmask_b32_e32 v48, v82, v48, vcc
	v_fmamk_f32 v49, v49, 0x3e0293ee, v126
	s_and_b64 vcc, s[42:43], s[34:35]
	v_max3_f32 v54, v54, v138, v139
	v_cndmask_b32_e32 v49, v82, v49, vcc
	v_fmamk_f32 v50, v50, 0x3e0293ee, v127
	s_and_b64 vcc, s[42:43], s[36:37]
	v_max3_f32 v54, v54, v140, v141
	v_cndmask_b32_e32 v50, v82, v50, vcc
	v_fmamk_f32 v51, v51, 0x3e0293ee, v85
	s_and_b64 vcc, s[42:43], s[38:39]
	v_max3_f32 v54, v54, v48, v49
	v_cndmask_b32_e32 v51, v82, v51, vcc
	v_max3_f32 v54, v54, v50, v51
	v_mov_b32_e32 v130, v54
	s_nop 1
	v_permlane16_swap_b32 v54, v130
	s_waitcnt lgkmcnt(0)
	v_max_f32_e32 v130, v130, v130
	v_max_f32_e32 v54, v54, v130
	v_mov_b32_e32 v130, v54
	s_nop 1
	v_permlane32_swap_b32 v54, v130
	s_waitcnt lgkmcnt(0)
	v_max_f32_e32 v130, v130, v130
	v_max_f32_e32 v130, v54, v130
	v_sub_f32_e32 v52, v52, v130
	v_exp_f32_e32 v52, v52
	v_sub_f32_e32 v53, v53, v130
	v_exp_f32_e32 v53, v53
	v_sub_f32_e32 v54, v55, v130
	v_exp_f32_e32 v54, v54
	v_sub_f32_e32 v55, v56, v130
	v_exp_f32_e32 v55, v55
	v_sub_f32_e32 v57, v57, v130
	v_add_f32_e32 v56, 0, v52
	v_exp_f32_e32 v57, v57
	v_sub_f32_e32 v58, v58, v130
	v_add_f32_e32 v56, v53, v56
	v_exp_f32_e32 v58, v58
	v_sub_f32_e32 v59, v59, v130
	v_add_f32_e32 v56, v54, v56
	v_exp_f32_e32 v59, v59
	v_sub_f32_e32 v60, v60, v130
	v_add_f32_e32 v56, v55, v56
	v_exp_f32_e32 v60, v60
	v_sub_f32_e32 v61, v61, v130
	v_add_f32_e32 v56, v57, v56
	v_exp_f32_e32 v181, v61
	v_sub_f32_e32 v61, v62, v130
	v_add_f32_e32 v56, v58, v56
	v_exp_f32_e32 v183, v61
	v_sub_f32_e32 v61, v63, v130
	v_add_f32_e32 v56, v59, v56
	v_exp_f32_e32 v188, v61
	v_sub_f32_e32 v61, v64, v130
	v_add_f32_e32 v56, v60, v56
	v_exp_f32_e32 v189, v61
	v_sub_f32_e32 v61, v65, v130
	v_add_f32_e32 v56, v181, v56
	v_exp_f32_e32 v190, v61
	v_sub_f32_e32 v61, v66, v130
	v_add_f32_e32 v56, v183, v56
	v_exp_f32_e32 v191, v61
	v_sub_f32_e32 v61, v67, v130
	v_add_f32_e32 v56, v188, v56
	v_exp_f32_e32 v192, v61
	v_sub_f32_e32 v61, v68, v130
	v_add_f32_e32 v56, v189, v56
	v_exp_f32_e32 v193, v61
	v_sub_f32_e32 v61, v69, v130
	v_add_f32_e32 v56, v190, v56
	v_exp_f32_e32 v196, v61
	v_sub_f32_e32 v61, v70, v130
	v_add_f32_e32 v56, v191, v56
	v_exp_f32_e32 v197, v61
	v_sub_f32_e32 v61, v71, v130
	v_add_f32_e32 v56, v192, v56
	v_exp_f32_e32 v198, v61
	v_sub_f32_e32 v61, v131, v130
	v_add_f32_e32 v56, v193, v56
	v_exp_f32_e32 v199, v61
	v_sub_f32_e32 v61, v132, v130
	v_add_f32_e32 v56, v196, v56
	v_exp_f32_e32 v200, v61
	v_sub_f32_e32 v61, v133, v130
	v_add_f32_e32 v56, v197, v56
	v_exp_f32_e32 v201, v61
	v_sub_f32_e32 v61, v134, v130
	v_add_f32_e32 v56, v198, v56
	v_exp_f32_e32 v202, v61
	v_sub_f32_e32 v61, v135, v130
	v_add_f32_e32 v56, v199, v56
	v_exp_f32_e32 v203, v61
	v_sub_f32_e32 v61, v136, v130
	v_add_f32_e32 v56, v200, v56
	v_exp_f32_e32 v204, v61
	v_sub_f32_e32 v61, v137, v130
	v_add_f32_e32 v56, v201, v56
	v_exp_f32_e32 v205, v61
	v_sub_f32_e32 v61, v142, v130
	v_add_f32_e32 v56, v202, v56
	v_exp_f32_e32 v206, v61
	v_sub_f32_e32 v61, v143, v130
	v_add_f32_e32 v56, v203, v56
	v_exp_f32_e32 v207, v61
	v_sub_f32_e32 v61, v144, v130
	v_add_f32_e32 v56, v204, v56
	v_exp_f32_e32 v208, v61
	v_sub_f32_e32 v61, v145, v130
	v_add_f32_e32 v56, v205, v56
	v_exp_f32_e32 v209, v61
	v_sub_f32_e32 v61, v146, v130
	v_add_f32_e32 v56, v206, v56
	v_exp_f32_e32 v210, v61
	v_sub_f32_e32 v61, v147, v130
	v_add_f32_e32 v56, v207, v56
	v_exp_f32_e32 v211, v61
	v_sub_f32_e32 v61, v138, v130
	v_add_f32_e32 v56, v208, v56
	v_exp_f32_e32 v132, v61
	v_sub_f32_e32 v61, v139, v130
	v_add_f32_e32 v56, v209, v56
	v_exp_f32_e32 v133, v61
	v_sub_f32_e32 v61, v140, v130
	v_add_f32_e32 v56, v210, v56
	v_exp_f32_e32 v134, v61
	v_sub_f32_e32 v61, v141, v130
	v_add_f32_e32 v56, v211, v56
	v_exp_f32_e32 v135, v61
	v_sub_f32_e32 v48, v48, v130
	v_add_f32_e32 v56, v132, v56
	v_exp_f32_e32 v136, v48
	v_sub_f32_e32 v48, v49, v130
	v_add_f32_e32 v56, v133, v56
	v_exp_f32_e32 v137, v48
	v_sub_f32_e32 v48, v50, v130
	v_add_f32_e32 v56, v134, v56
	v_exp_f32_e32 v138, v48
	v_sub_f32_e32 v48, v51, v130
	v_add_f32_e32 v56, v135, v56
	v_exp_f32_e32 v139, v48
	v_add_f32_e32 v48, v136, v56
	v_add_f32_e32 v48, v137, v48
	v_add_f32_e32 v48, v138, v48
	v_add_f32_e32 v48, v139, v48
	v_mov_b32_e32 v49, v48
	s_nop 1
	v_permlane16_swap_b32 v48, v49
	v_cvt_pk_bf16_f32 v172, v52, v53
	v_cvt_pk_bf16_f32 v173, v54, v55
	v_cvt_pk_bf16_f32 v174, v57, v58
	v_cvt_pk_bf16_f32 v175, v59, v60
	s_waitcnt lgkmcnt(0)
	v_add_f32_e32 v48, v48, v49
	v_mov_b32_e32 v49, v48
	s_nop 1
	v_permlane32_swap_b32 v48, v49
	s_waitcnt lgkmcnt(0)
	v_add_f32_e32 v131, v48, v49
	v_add_u32_e32 v48, s63, v88
	ds_read_b64_tr_b16 v[140:141], v48 offset:0
	ds_read_b64_tr_b16 v[142:143], v48 offset:0x440
	ds_read_b64_tr_b16 v[144:145], v48 offset:32
	ds_read_b64_tr_b16 v[146:147], v48 offset:0x460
	ds_read_b64_tr_b16 v[148:149], v48 offset:64
	ds_read_b64_tr_b16 v[150:151], v48 offset:0x480
	ds_read_b64_tr_b16 v[152:153], v48 offset:0x60
	ds_read_b64_tr_b16 v[154:155], v48 offset:0x4a0
	ds_read_b64_tr_b16 v[156:157], v48 offset:0x80
	ds_read_b64_tr_b16 v[158:159], v48 offset:0x4c0
	ds_read_b64_tr_b16 v[160:161], v48 offset:0xa0
	ds_read_b64_tr_b16 v[162:163], v48 offset:0x4e0
	ds_read_b64_tr_b16 v[164:165], v48 offset:0xc0
	ds_read_b64_tr_b16 v[166:167], v48 offset:0x500
	ds_read_b64_tr_b16 v[168:169], v48 offset:0xe0
	ds_read_b64_tr_b16 v[170:171], v48 offset:0x520
	s_waitcnt lgkmcnt(0)
	v_add_u32_e32 v194, s62, v88
	ds_read_b64_tr_b16 v[176:177], v194 offset:0
	ds_read_b64_tr_b16 v[178:179], v194 offset:0x440
	ds_read_b64_tr_b16 v[184:185], v194 offset:32
	ds_read_b64_tr_b16 v[186:187], v194 offset:0x460
	ds_read_b64_tr_b16 v[68:69], v194 offset:64
	ds_read_b64_tr_b16 v[70:71], v194 offset:0x480
	ds_read_b64_tr_b16 v[64:65], v194 offset:0x60
	ds_read_b64_tr_b16 v[66:67], v194 offset:0x4a0
	ds_read_b64_tr_b16 v[60:61], v194 offset:0x80
	ds_read_b64_tr_b16 v[62:63], v194 offset:0x4c0
	ds_read_b64_tr_b16 v[56:57], v194 offset:0xa0
	ds_read_b64_tr_b16 v[58:59], v194 offset:0x4e0
	ds_read_b64_tr_b16 v[52:53], v194 offset:0xc0
	ds_read_b64_tr_b16 v[54:55], v194 offset:0x500
	ds_read_b64_tr_b16 v[48:49], v194 offset:0xe0
	ds_read_b64_tr_b16 v[50:51], v194 offset:0x520
	s_waitcnt lgkmcnt(0)
	v_mfma_f32_16x16x32_bf16 v[140:143], v[140:143], v[172:175], 0
	v_mfma_f32_16x16x32_bf16 v[144:147], v[144:147], v[172:175], 0
	v_mfma_f32_16x16x32_bf16 v[148:151], v[148:151], v[172:175], 0
	v_mfma_f32_16x16x32_bf16 v[152:155], v[152:155], v[172:175], 0
	v_mfma_f32_16x16x32_bf16 v[156:159], v[156:159], v[172:175], 0
	v_mfma_f32_16x16x32_bf16 v[160:163], v[160:163], v[172:175], 0
	v_mfma_f32_16x16x32_bf16 v[164:167], v[164:167], v[172:175], 0
	v_mfma_f32_16x16x32_bf16 v[168:171], v[168:171], v[172:175], 0
	v_cvt_pk_bf16_f32 v172, v181, v183
	v_cvt_pk_bf16_f32 v173, v188, v189
	v_cvt_pk_bf16_f32 v174, v190, v191
	v_cvt_pk_bf16_f32 v175, v192, v193
	s_nop 1
	v_mfma_f32_16x16x32_bf16 v[140:143], v[176:179], v[172:175], v[140:143]
	v_add_u32_e32 v181, s95, v88
	ds_read_b64_tr_b16 v[176:177], v181 offset:0
	ds_read_b64_tr_b16 v[178:179], v181 offset:0x440
	v_mfma_f32_16x16x32_bf16 v[144:147], v[184:187], v[172:175], v[144:147]
	ds_read_b64_tr_b16 v[184:185], v181 offset:32
	ds_read_b64_tr_b16 v[186:187], v181 offset:0x460
	ds_read_b64_tr_b16 v[188:189], v181 offset:64
	ds_read_b64_tr_b16 v[190:191], v181 offset:0x480
	v_mfma_f32_16x16x32_bf16 v[68:71], v[68:71], v[172:175], v[148:151]
	ds_read_b64_tr_b16 v[148:149], v181 offset:0x60
	ds_read_b64_tr_b16 v[150:151], v181 offset:0x4a0
	v_cvt_pk_bf16_f32 v196, v196, v197
	v_mfma_f32_16x16x32_bf16 v[64:67], v[64:67], v[172:175], v[152:155]
	ds_read_b64_tr_b16 v[152:153], v181 offset:0x80
	ds_read_b64_tr_b16 v[154:155], v181 offset:0x4c0
	ds_read_b64_tr_b16 v[192:193], v181 offset:0xa0
	ds_read_b64_tr_b16 v[194:195], v181 offset:0x4e0
	v_mfma_f32_16x16x32_bf16 v[60:63], v[60:63], v[172:175], v[156:159]
	ds_read_b64_tr_b16 v[156:157], v181 offset:0xc0
	ds_read_b64_tr_b16 v[158:159], v181 offset:0x500
	v_cvt_pk_bf16_f32 v197, v198, v199
	v_mfma_f32_16x16x32_bf16 v[56:59], v[56:59], v[172:175], v[160:163]
	ds_read_b64_tr_b16 v[160:161], v181 offset:0xe0
	ds_read_b64_tr_b16 v[162:163], v181 offset:0x520
	s_waitcnt lgkmcnt(0)
	v_mfma_f32_16x16x32_bf16 v[48:51], v[48:51], v[172:175], v[168:171]
	v_cvt_pk_bf16_f32 v198, v200, v201
	v_cvt_pk_bf16_f32 v199, v202, v203
	v_mfma_f32_16x16x32_bf16 v[52:55], v[52:55], v[172:175], v[164:167]
	v_add_u32_e32 v181, s41, v88
	ds_read_b64_tr_b16 v[164:165], v181 offset:0
	ds_read_b64_tr_b16 v[166:167], v181 offset:0x440
	ds_read_b64_tr_b16 v[168:169], v181 offset:32
	ds_read_b64_tr_b16 v[170:171], v181 offset:0x460
	ds_read_b64_tr_b16 v[172:173], v181 offset:64
	ds_read_b64_tr_b16 v[174:175], v181 offset:0x480
	v_mfma_f32_16x16x32_bf16 v[140:143], v[176:179], v[196:199], v[140:143]
	ds_read_b64_tr_b16 v[176:177], v181 offset:0x60
	ds_read_b64_tr_b16 v[178:179], v181 offset:0x4a0
	v_mfma_f32_16x16x32_bf16 v[64:67], v[148:151], v[196:199], v[64:67]
	ds_read_b64_tr_b16 v[148:149], v181 offset:0x80
	ds_read_b64_tr_b16 v[150:151], v181 offset:0x4c0
	v_mfma_f32_16x16x32_bf16 v[144:147], v[184:187], v[196:199], v[144:147]
	ds_read_b64_tr_b16 v[184:185], v181 offset:0xa0
	ds_read_b64_tr_b16 v[186:187], v181 offset:0x4e0
	v_mfma_f32_16x16x32_bf16 v[60:63], v[152:155], v[196:199], v[60:63]
	ds_read_b64_tr_b16 v[152:153], v181 offset:0xc0
	ds_read_b64_tr_b16 v[154:155], v181 offset:0x500
	v_mfma_f32_16x16x32_bf16 v[68:71], v[188:191], v[196:199], v[68:71]
	ds_read_b64_tr_b16 v[188:189], v181 offset:0xe0
	ds_read_b64_tr_b16 v[190:191], v181 offset:0x520
	s_waitcnt lgkmcnt(0)
	v_mfma_f32_16x16x32_bf16 v[48:51], v[160:163], v[196:199], v[48:51]
	v_mfma_f32_16x16x32_bf16 v[56:59], v[192:195], v[196:199], v[56:59]
	v_cvt_pk_bf16_f32 v192, v204, v205
	v_cvt_pk_bf16_f32 v193, v206, v207
	v_cvt_pk_bf16_f32 v194, v208, v209
	v_mfma_f32_16x16x32_bf16 v[52:55], v[156:159], v[196:199], v[52:55]
	v_cvt_pk_bf16_f32 v195, v210, v211
	v_add_u32_e32 v181, s40, v88
	ds_read_b64_tr_b16 v[156:157], v181 offset:0
	ds_read_b64_tr_b16 v[158:159], v181 offset:0x440
	ds_read_b64_tr_b16 v[160:161], v181 offset:32
	ds_read_b64_tr_b16 v[162:163], v181 offset:0x460
	s_nop 0
	v_mfma_f32_16x16x32_bf16 v[140:143], v[164:167], v[192:195], v[140:143]
	ds_read_b64_tr_b16 v[164:165], v181 offset:64
	ds_read_b64_tr_b16 v[166:167], v181 offset:0x480
	v_mfma_f32_16x16x32_bf16 v[144:147], v[168:171], v[192:195], v[144:147]
	ds_read_b64_tr_b16 v[168:169], v181 offset:0x60
	ds_read_b64_tr_b16 v[170:171], v181 offset:0x4a0
	v_mfma_f32_16x16x32_bf16 v[60:63], v[148:151], v[192:195], v[60:63]
	ds_read_b64_tr_b16 v[148:149], v181 offset:0x80
	ds_read_b64_tr_b16 v[150:151], v181 offset:0x4c0
	v_mfma_f32_16x16x32_bf16 v[68:71], v[172:175], v[192:195], v[68:71]
	ds_read_b64_tr_b16 v[172:173], v181 offset:0xa0
	ds_read_b64_tr_b16 v[174:175], v181 offset:0x4e0
	v_mfma_f32_16x16x32_bf16 v[64:67], v[176:179], v[192:195], v[64:67]
	ds_read_b64_tr_b16 v[176:177], v181 offset:0xc0
	ds_read_b64_tr_b16 v[178:179], v181 offset:0x500
	v_mfma_f32_16x16x32_bf16 v[52:55], v[152:155], v[192:195], v[52:55]
	ds_read_b64_tr_b16 v[152:153], v181 offset:0xe0
	ds_read_b64_tr_b16 v[154:155], v181 offset:0x520
	s_waitcnt lgkmcnt(0)
	v_mfma_f32_16x16x32_bf16 v[56:59], v[184:187], v[192:195], v[56:59]
	v_mfma_f32_16x16x32_bf16 v[184:187], v[188:191], v[192:195], v[48:51]
	v_cvt_pk_bf16_f32 v132, v132, v133
	v_cvt_pk_bf16_f32 v133, v134, v135
	v_cvt_pk_bf16_f32 v134, v136, v137
	v_cvt_pk_bf16_f32 v135, v138, v139
	v_add_u32_e32 v48, s96, v129
	v_ashrrev_i32_e32 v49, 31, v48
	v_mfma_f32_16x16x32_bf16 v[136:139], v[156:159], v[132:135], v[140:143]
	v_rcp_f32_e32 v156, v131
	v_lshl_add_u64 v[48:49], s[44:45], 0, v[48:49]
	v_lshlrev_b64 v[50:51], 11, v[48:49]
	v_mfma_f32_16x16x32_bf16 v[140:143], v[160:163], v[132:135], v[144:147]
	v_mfma_f32_16x16x32_bf16 v[68:71], v[164:167], v[132:135], v[68:71]
	s_nop 1
	v_lshl_add_u64 v[144:145], v[78:79], 0, v[50:51]
	v_pk_mul_f32 v[50:51], v[156:157], v[136:137] op_sel_hi:[0,1]
	v_pk_mul_f32 v[136:137], v[156:157], v[138:139] op_sel_hi:[0,1]
	v_cvt_pk_bf16_f32 v50, v50, v51
	v_cvt_pk_bf16_f32 v51, v136, v137
	v_mfma_f32_16x16x32_bf16 v[64:67], v[168:171], v[132:135], v[64:67]
	global_store_dwordx2 v[144:145], v[50:51], off
	v_pk_mul_f32 v[50:51], v[156:157], v[140:141] op_sel_hi:[0,1]
	v_pk_mul_f32 v[136:137], v[156:157], v[142:143] op_sel_hi:[0,1]
	v_cvt_pk_bf16_f32 v50, v50, v51
	v_cvt_pk_bf16_f32 v51, v136, v137
	v_mfma_f32_16x16x32_bf16 v[60:63], v[148:151], v[132:135], v[60:63]
	global_store_dwordx2 v[144:145], v[50:51], off offset:32
	v_pk_mul_f32 v[136:137], v[156:157], v[70:71] op_sel_hi:[0,1]
	v_mfma_f32_16x16x32_bf16 v[50:53], v[176:179], v[132:135], v[52:55]
	s_nop 2
	v_mul_f32_e64 v54, v156, v68
	v_mul_f32_e64 v55, v156, v69
	v_cvt_pk_bf16_f32 v54, v54, v55
	v_cvt_pk_bf16_f32 v55, v136, v137
	v_mfma_f32_16x16x32_bf16 v[56:59], v[172:175], v[132:135], v[56:59]
	global_store_dwordx2 v[144:145], v[54:55], off offset:64
	v_pk_mul_f32 v[54:55], v[156:157], v[64:65] op_sel_hi:[0,1]
	v_pk_mul_f32 v[64:65], v[156:157], v[66:67] op_sel_hi:[0,1]
	v_mfma_f32_16x16x32_bf16 v[68:71], v[152:155], v[132:135], v[184:187]
	v_cvt_pk_bf16_f32 v54, v54, v55
	v_cvt_pk_bf16_f32 v55, v64, v65
	global_store_dwordx2 v[144:145], v[54:55], off offset:96
	v_pk_mul_f32 v[54:55], v[156:157], v[60:61] op_sel_hi:[0,1]
	v_pk_mul_f32 v[60:61], v[156:157], v[62:63] op_sel_hi:[0,1]
	v_pk_mul_f32 v[50:51], v[156:157], v[50:51] op_sel_hi:[0,1]
	v_pk_mul_f32 v[52:53], v[156:157], v[52:53] op_sel_hi:[0,1]
	v_cvt_pk_bf16_f32 v54, v54, v55
	v_cvt_pk_bf16_f32 v55, v60, v61
	v_cvt_pk_bf16_f32 v50, v50, v51
	v_cvt_pk_bf16_f32 v51, v52, v53
	global_store_dwordx2 v[144:145], v[54:55], off offset:128
	v_pk_mul_f32 v[54:55], v[156:157], v[56:57] op_sel_hi:[0,1]
	v_pk_mul_f32 v[56:57], v[156:157], v[58:59] op_sel_hi:[0,1]
	global_store_dwordx2 v[144:145], v[50:51], off offset:192
	v_pk_mul_f32 v[50:51], v[156:157], v[68:69] op_sel_hi:[0,1]
	v_pk_mul_f32 v[52:53], v[156:157], v[70:71] op_sel_hi:[0,1]
	v_cvt_pk_bf16_f32 v54, v54, v55
	v_cvt_pk_bf16_f32 v55, v56, v57
	v_cvt_pk_bf16_f32 v50, v50, v51
	v_cvt_pk_bf16_f32 v51, v52, v53
	global_store_dwordx2 v[144:145], v[54:55], off offset:160
	global_store_dwordx2 v[144:145], v[50:51], off offset:224
	s_and_saveexec_b64 s[40:41], s[4:5]
	s_cbranch_execz .LBB0_416
	v_log_f32_e32 v50, v131
	v_lshlrev_b64 v[48:49], 5, v[48:49]
	v_lshl_add_u64 v[48:49], s[84:85], 0, v[48:49]
	v_add_f32_e32 v50, v130, v50
	v_mul_f32_e32 v50, 0x3f317218, v50
	global_store_dword v[48:49], v50, off

.LBB0_639:
	v_and_b32_e32 v131, 64, v183
	s_and_b32 s42, s2, 3
	s_lshl_b64 s[0:1], s[18:19], 17
	v_xor_b32_e32 v130, 16, v183
	v_add_u32_e32 v131, 64, v131
	v_mov_b32_e32 v128, v182
	s_add_u32 s22, s41, s0
	v_cmp_lt_i32_e32 vcc, v130, v131
	s_addc_u32 s23, s44, s1
	v_and_b32_e32 v129, 63, v128
	s_ashr_i32 s79, s81, 2
	v_cndmask_b32_e32 v130, v183, v130, vcc
	s_andn2_b32 s79, s79, 63
	v_ashrrev_i32_e32 v128, 1, v129
	v_lshlrev_b32_e32 v172, 2, v130
	v_xor_b32_e32 v130, 32, v183
	v_and_or_b32 v132, v129, 15, s79
	s_lshl_b32 s80, s42, 5
	v_and_b32_e32 v128, -8, v128
	v_cmp_lt_i32_e32 vcc, v130, v131
	v_add_u32_e32 v128, s80, v128
	s_mov_b64 s[26:27], s[22:23]
	v_cndmask_b32_e32 v130, v183, v130, vcc
	v_cmp_gt_u32_e32 vcc, 16, v129
	v_lshl_add_u32 v129, v132, 2, 0
	v_add_u32_e32 v135, 0x20000, v129
	v_lshl_add_u32 v129, v128, 2, 0
	v_add_u32_e32 v134, 0x20800, v129
	ds_read_b32 v150, v135
	ds_read_b128 v[136:139], v134
	ds_read_b128 v[140:143], v134 offset:16
	s_lshl_b32 s0, s42, 10
	v_ashrrev_i32_e32 v133, 31, v132
	v_lshlrev_b32_e32 v173, 2, v130
	s_add_i32 s2, s0, 0
	v_lshlrev_b64 v[130:131], 9, v[132:133]
	v_cmp_gt_i32_e64 s[0:1], v128, v132
	v_lshl_add_u64 v[144:145], s[26:27], 0, v[130:131]
	s_waitcnt lgkmcnt(0)
	v_sub_f32_e32 v129, v136, v150
	v_cndmask_b32_e64 v130, 1.0, 0, s[0:1]
	v_mul_f32_e32 v130, v124, v130
	v_sub_f32_e32 v124, v140, v150
	v_min_f32_e32 v124, 0, v124
	v_mul_f32_e32 v124, 0x3fb8aa3b, v124
	v_exp_f32_e32 v136, v124
	v_sub_f32_e32 v124, v137, v150
	v_sub_f32_e32 v137, v141, v150
	v_min_f32_e32 v124, 0, v124
	v_min_f32_e32 v137, 0, v137
	v_min_f32_e32 v129, 0, v129
	v_cmp_lt_i32_e64 s[0:1], v128, v132
	v_mul_f32_e32 v124, 0x3fb8aa3b, v124
	v_or_b32_e32 v131, 5, v128
	v_mul_f32_e32 v137, 0x3fb8aa3b, v137
	v_mul_f32_e32 v129, 0x3fb8aa3b, v129
	v_cndmask_b32_e64 v140, 0, 1.0, s[0:1]
	v_exp_f32_e32 v146, v124
	v_or_b32_e32 v124, 4, v128
	v_exp_f32_e32 v137, v137
	v_cmp_gt_i32_e64 s[0:1], v131, v132
	v_exp_f32_e32 v129, v129
	v_mul_f32_e32 v125, v125, v140
	v_cndmask_b32_e64 v141, 1.0, 0, s[0:1]
	v_cmp_gt_i32_e64 s[0:1], v124, v132
	v_mul_f32_e32 v133, v130, v129
	v_mul_f32_e32 v148, v125, v146
	v_cndmask_b32_e64 v140, 1.0, 0, s[0:1]
	v_pk_mul_f32 v[120:121], v[120:121], v[140:141]
	s_add_i32 s2, s2, 0x21400
	v_pk_mul_f32 v[140:141], v[120:121], v[136:137]
	s_nop 0
	v_fma_f32 v120, v130, v129, v140
	v_add_f32_e32 v120, 0, v120
	v_fma_f32 v121, v125, v146, v141
	v_add_f32_e32 v149, v121, v120
	v_sub_f32_e32 v120, v138, v150
	v_sub_f32_e32 v129, v139, v150
	v_min_f32_e32 v120, 0, v120
	v_min_f32_e32 v129, 0, v129
	v_mul_f32_e32 v120, 0x3fb8aa3b, v120
	v_mul_f32_e32 v129, 0x3fb8aa3b, v129
	v_exp_f32_e32 v136, v120
	v_sub_f32_e32 v120, v142, v150
	v_or_b32_e32 v125, 3, v128
	v_exp_f32_e32 v137, v129
	v_sub_f32_e32 v129, v143, v150
	v_min_f32_e32 v120, 0, v120
	v_or_b32_e32 v130, 2, v128
	v_cmp_gt_i32_e64 s[0:1], v125, v132
	v_min_f32_e32 v129, 0, v129
	v_mul_f32_e32 v120, 0x3fb8aa3b, v120
	v_or_b32_e32 v121, 7, v128
	v_cndmask_b32_e64 v147, 1.0, 0, s[0:1]
	v_cmp_gt_i32_e64 s[0:1], v130, v132
	v_mul_f32_e32 v129, 0x3fb8aa3b, v129
	v_exp_f32_e32 v138, v120
	v_or_b32_e32 v120, 6, v128
	v_cndmask_b32_e64 v146, 1.0, 0, s[0:1]
	v_exp_f32_e32 v139, v129
	v_cmp_gt_i32_e64 s[0:1], v121, v132
	v_pk_mul_f32 v[126:127], v[126:127], v[146:147]
	v_ashrrev_i32_e32 v129, 31, v128
	v_cndmask_b32_e64 v143, 1.0, 0, s[0:1]
	v_cmp_gt_i32_e64 s[0:1], v120, v132
	v_pk_mul_f32 v[146:147], v[126:127], v[136:137]
	v_lshl_add_u64 v[144:145], v[128:129], 1, v[144:145]
	v_cndmask_b32_e64 v142, 1.0, 0, s[0:1]
	v_pk_mul_f32 v[122:123], v[122:123], v[142:143]
	s_nop 0
	v_pk_mul_f32 v[122:123], v[122:123], v[138:139]
	v_cvt_pk_bf16_f32 v138, v140, v141
	v_pk_fma_f32 v[126:127], v[126:127], v[136:137], v[122:123]
	v_cvt_pk_bf16_f32 v136, v133, v148
	v_cvt_pk_bf16_f32 v137, v146, v147
	v_cvt_pk_bf16_f32 v139, v122, v123
	global_store_dwordx4 v[144:145], v[136:139], off
	ds_read_b128 v[136:139], v134 offset:512
	ds_read_b128 v[140:143], v134 offset:528
	v_add_f32_e32 v122, v126, v149
	v_add_u32_e32 v126, 0x80, v128
	v_add_f32_e32 v127, v127, v122
	s_waitcnt lgkmcnt(0)
	v_sub_f32_e32 v122, v136, v150
	v_cmp_gt_i32_e64 s[0:1], v132, v126
	v_min_f32_e32 v122, 0, v122
	v_mul_f32_e32 v122, 0x3fb8aa3b, v122
	v_cndmask_b32_e64 v147, 0, 1.0, s[0:1]
	v_cmp_gt_i32_e64 s[0:1], v126, v132
	v_exp_f32_e32 v136, v122
	v_sub_f32_e32 v122, v140, v150
	v_cndmask_b32_e64 v146, 1.0, 0, s[0:1]
	v_pk_mul_f32 v[146:147], v[116:117], v[146:147]
	v_sub_f32_e32 v116, v141, v150
	v_min_f32_e32 v122, 0, v122
	v_sub_f32_e32 v133, v137, v150
	v_min_f32_e32 v116, 0, v116
	v_mul_f32_e32 v122, 0x3fb8aa3b, v122
	v_or_b32_e32 v123, 5, v126
	v_min_f32_e32 v133, 0, v133
	v_mul_f32_e32 v116, 0x3fb8aa3b, v116
	v_exp_f32_e32 v140, v122
	v_or_b32_e32 v122, 4, v126
	v_mul_f32_e32 v133, 0x3fb8aa3b, v133
	v_exp_f32_e32 v141, v116
	v_cmp_gt_i32_e64 s[0:1], v123, v132
	v_exp_f32_e32 v137, v133
	v_sub_f32_e32 v133, v139, v150
	v_cndmask_b32_e64 v117, 1.0, 0, s[0:1]
	v_cmp_gt_i32_e64 s[0:1], v122, v132
	v_min_f32_e32 v133, 0, v133
	v_mul_f32_e32 v133, 0x3fb8aa3b, v133
	v_cndmask_b32_e64 v116, 1.0, 0, s[0:1]
	v_pk_mul_f32 v[112:113], v[112:113], v[116:117]
	v_or_b32_e32 v117, 3, v126
	v_pk_mul_f32 v[140:141], v[112:113], v[140:141]
	v_exp_f32_e32 v139, v133
	v_pk_fma_f32 v[112:113], v[146:147], v[136:137], v[140:141]
	v_sub_f32_e32 v133, v143, v150
	v_add_f32_e32 v112, v112, v127
	v_add_f32_e32 v127, v113, v112
	v_sub_f32_e32 v112, v138, v150
	v_min_f32_e32 v112, 0, v112
	v_mul_f32_e32 v112, 0x3fb8aa3b, v112
	v_exp_f32_e32 v138, v112
	v_sub_f32_e32 v112, v142, v150
	v_min_f32_e32 v112, 0, v112
	v_or_b32_e32 v116, 2, v126
	v_cmp_gt_i32_e64 s[0:1], v117, v132
	v_min_f32_e32 v133, 0, v133
	v_mul_f32_e32 v112, 0x3fb8aa3b, v112
	v_or_b32_e32 v113, 7, v126
	v_cndmask_b32_e64 v149, 1.0, 0, s[0:1]
	v_cmp_gt_i32_e64 s[0:1], v116, v132
	v_mul_f32_e32 v133, 0x3fb8aa3b, v133
	v_exp_f32_e32 v142, v112
	v_or_b32_e32 v112, 6, v126
	v_cndmask_b32_e64 v148, 1.0, 0, s[0:1]
	v_exp_f32_e32 v143, v133
	v_cmp_gt_i32_e64 s[0:1], v113, v132
	v_pk_mul_f32 v[118:119], v[118:119], v[148:149]
	s_nop 0
	v_cndmask_b32_e64 v149, 1.0, 0, s[0:1]
	v_cmp_gt_i32_e64 s[0:1], v112, v132
	s_nop 1
	v_cndmask_b32_e64 v148, 1.0, 0, s[0:1]
	v_pk_mul_f32 v[114:115], v[114:115], v[148:149]
	s_nop 0
	v_pk_mul_f32 v[142:143], v[114:115], v[142:143]
	s_nop 0
	v_pk_fma_f32 v[114:115], v[118:119], v[138:139], v[142:143]
	v_pk_mul_f32 v[118:119], v[118:119], v[138:139]
	v_add_f32_e32 v114, v114, v127
	v_add_f32_e32 v127, v115, v114
	v_mov_b32_e32 v133, v127
	s_nop 1
	v_permlane16_swap_b32 v127, v133
	v_pk_mul_f32 v[114:115], v[146:147], v[136:137]
	v_cvt_pk_bf16_f32 v137, v118, v119
	v_cvt_pk_bf16_f32 v136, v114, v115
	v_cvt_pk_bf16_f32 v138, v140, v141
	s_waitcnt lgkmcnt(0)
	v_add_f32_e32 v115, v127, v133
	v_mov_b32_e32 v118, v115
	s_nop 1
	v_permlane32_swap_b32 v115, v118
	v_cvt_pk_bf16_f32 v139, v142, v143
	v_lshl_add_u32 v114, v132, 2, s2
	global_store_dwordx4 v[144:145], v[136:139], off offset:256
	s_and_saveexec_b64 s[0:1], vcc
	s_cbranch_execz .LBB0_641
	s_waitcnt lgkmcnt(0)
	v_add_f32_e32 v115, v115, v118
	ds_write_b32 v114, v115
.LBB0_641:
	s_or_b64 exec, exec, s[0:1]
	s_waitcnt lgkmcnt(0)
	v_or_b32_e32 v118, 16, v132
	v_lshl_add_u32 v115, v118, 2, 0
	v_add_u32_e32 v115, 0x20000, v115
	ds_read_b32 v115, v115
	ds_read_b128 v[136:139], v134
	v_ashrrev_i32_e32 v119, 31, v118
	v_lshlrev_b64 v[140:141], 9, v[118:119]
	v_lshl_add_u64 v[144:145], s[26:27], 0, v[140:141]
	ds_read_b128 v[140:143], v134 offset:16
	s_waitcnt lgkmcnt(0)
	v_sub_f32_e32 v119, v136, v115
	v_min_f32_e32 v119, 0, v119
	v_mul_f32_e32 v119, 0x3fb8aa3b, v119
	v_exp_f32_e32 v136, v119
	v_sub_f32_e32 v119, v140, v115
	v_min_f32_e32 v119, 0, v119
	v_mul_f32_e32 v119, 0x3fb8aa3b, v119
	v_exp_f32_e32 v140, v119
	v_sub_f32_e32 v119, v137, v115
	v_min_f32_e32 v119, 0, v119
	v_mul_f32_e32 v119, 0x3fb8aa3b, v119
	v_exp_f32_e32 v137, v119
	v_sub_f32_e32 v119, v141, v115
	v_cmp_gt_i32_e64 s[0:1], v118, v128
	v_min_f32_e32 v119, 0, v119
	v_mul_f32_e32 v119, 0x3fb8aa3b, v119
	v_cndmask_b32_e64 v147, 0, 1.0, s[0:1]
	v_cmp_gt_i32_e64 s[0:1], v128, v118
	v_exp_f32_e32 v141, v119
	s_nop 0
	v_cndmask_b32_e64 v146, 1.0, 0, s[0:1]
	v_cmp_gt_i32_e64 s[0:1], v131, v118
	v_pk_mul_f32 v[108:109], v[108:109], v[146:147]
	s_nop 0
	v_cndmask_b32_e64 v149, 1.0, 0, s[0:1]
	v_cmp_gt_i32_e64 s[0:1], v124, v118
	v_pk_mul_f32 v[146:147], v[108:109], v[136:137]
	s_nop 0
	v_cndmask_b32_e64 v148, 1.0, 0, s[0:1]
	v_pk_mul_f32 v[104:105], v[104:105], v[148:149]
	v_cmp_gt_i32_e64 s[0:1], v125, v118
	v_pk_mul_f32 v[140:141], v[104:105], v[140:141]
	s_nop 0
	v_pk_fma_f32 v[104:105], v[108:109], v[136:137], v[140:141]
	v_cndmask_b32_e64 v137, 1.0, 0, s[0:1]
	v_add_f32_e32 v104, 0, v104
	v_add_f32_e32 v119, v105, v104
	v_sub_f32_e32 v104, v138, v115
	v_sub_f32_e32 v105, v139, v115
	v_min_f32_e32 v104, 0, v104
	v_min_f32_e32 v105, 0, v105
	v_mul_f32_e32 v104, 0x3fb8aa3b, v104
	v_mul_f32_e32 v105, 0x3fb8aa3b, v105
	v_exp_f32_e32 v108, v104
	v_sub_f32_e32 v104, v142, v115
	v_exp_f32_e32 v109, v105
	v_sub_f32_e32 v105, v143, v115
	v_min_f32_e32 v104, 0, v104
	v_min_f32_e32 v105, 0, v105
	v_mul_f32_e32 v104, 0x3fb8aa3b, v104
	v_cmp_gt_i32_e64 s[0:1], v130, v118
	v_mul_f32_e32 v105, 0x3fb8aa3b, v105
	v_exp_f32_e32 v104, v104
	v_cndmask_b32_e64 v136, 1.0, 0, s[0:1]
	v_exp_f32_e32 v105, v105
	v_cmp_gt_i32_e64 s[0:1], v121, v118
	v_pk_mul_f32 v[110:111], v[110:111], v[136:137]
	s_nop 0
	v_cndmask_b32_e64 v139, 1.0, 0, s[0:1]
	v_cmp_gt_i32_e64 s[0:1], v120, v118
	v_pk_mul_f32 v[136:137], v[110:111], v[108:109]
	s_nop 0
	v_cndmask_b32_e64 v138, 1.0, 0, s[0:1]
	v_pk_mul_f32 v[106:107], v[106:107], v[138:139]
	v_cmp_gt_i32_e64 s[0:1], v118, v126
	v_pk_mul_f32 v[138:139], v[106:107], v[104:105]
	v_cvt_pk_bf16_f32 v104, v146, v147
	v_cvt_pk_bf16_f32 v105, v136, v137
	v_cvt_pk_bf16_f32 v106, v140, v141
	v_cvt_pk_bf16_f32 v107, v138, v139
	v_lshl_add_u64 v[136:137], v[128:129], 1, v[144:145]
	v_pk_fma_f32 v[108:109], v[110:111], v[108:109], v[138:139]
	global_store_dwordx4 v[136:137], v[104:107], off
	v_add_f32_e32 v108, v108, v119
	ds_read_b128 v[104:107], v134 offset:512
	v_add_f32_e32 v119, v109, v108
	ds_read_b128 v[108:111], v134 offset:528
	v_cndmask_b32_e64 v139, 0, 1.0, s[0:1]
	v_cmp_gt_i32_e64 s[0:1], v126, v118
	s_waitcnt lgkmcnt(0)
	v_sub_f32_e32 v104, v104, v115
	v_sub_f32_e32 v105, v105, v115
	v_sub_f32_e32 v108, v108, v115
	v_sub_f32_e32 v109, v109, v115
	v_min_f32_e32 v108, 0, v108
	v_min_f32_e32 v109, 0, v109
	v_min_f32_e32 v104, 0, v104
	v_mul_f32_e32 v108, 0x3fb8aa3b, v108
	v_min_f32_e32 v105, 0, v105
	v_mul_f32_e32 v109, 0x3fb8aa3b, v109
	v_mul_f32_e32 v104, 0x3fb8aa3b, v104
	v_exp_f32_e32 v108, v108
	v_mul_f32_e32 v105, 0x3fb8aa3b, v105
	v_cndmask_b32_e64 v138, 1.0, 0, s[0:1]
	v_exp_f32_e32 v109, v109
	v_cmp_gt_i32_e64 s[0:1], v123, v118
	v_exp_f32_e32 v104, v104
	v_exp_f32_e32 v105, v105
	v_pk_mul_f32 v[100:101], v[100:101], v[138:139]
	v_cndmask_b32_e64 v139, 1.0, 0, s[0:1]
	v_cmp_gt_i32_e64 s[0:1], v122, v118
	s_nop 1
	v_cndmask_b32_e64 v138, 1.0, 0, s[0:1]
	v_pk_mul_f32 v[96:97], v[96:97], v[138:139]
	v_cmp_gt_i32_e64 s[0:1], v117, v118
	v_pk_mul_f32 v[108:109], v[96:97], v[108:109]
	s_nop 0
	v_pk_fma_f32 v[96:97], v[100:101], v[104:105], v[108:109]
	v_cndmask_b32_e64 v139, 1.0, 0, s[0:1]
	v_add_f32_e32 v96, v96, v119
	v_add_f32_e32 v119, v97, v96
	v_sub_f32_e32 v97, v110, v115
	v_min_f32_e32 v97, 0, v97
	v_mul_f32_e32 v97, 0x3fb8aa3b, v97
	v_sub_f32_e32 v96, v106, v115
	v_exp_f32_e32 v106, v97
	v_sub_f32_e32 v97, v107, v115
	v_sub_f32_e32 v107, v111, v115
	v_min_f32_e32 v107, 0, v107
	v_min_f32_e32 v96, 0, v96
	v_min_f32_e32 v97, 0, v97
	v_cmp_gt_i32_e64 s[0:1], v116, v118
	v_mul_f32_e32 v107, 0x3fb8aa3b, v107
	v_mul_f32_e32 v96, 0x3fb8aa3b, v96
	v_mul_f32_e32 v97, 0x3fb8aa3b, v97
	v_cndmask_b32_e64 v138, 1.0, 0, s[0:1]
	v_exp_f32_e32 v107, v107
	v_cmp_gt_i32_e64 s[0:1], v113, v118
	v_exp_f32_e32 v96, v96
	v_exp_f32_e32 v97, v97
	v_cndmask_b32_e64 v111, 1.0, 0, s[0:1]
	v_cmp_gt_i32_e64 s[0:1], v112, v118
	v_pk_mul_f32 v[102:103], v[102:103], v[138:139]
	s_nop 0
	v_cndmask_b32_e64 v110, 1.0, 0, s[0:1]
	v_pk_mul_f32 v[98:99], v[98:99], v[110:111]
	s_nop 0
	v_pk_mul_f32 v[106:107], v[98:99], v[106:107]
	s_nop 0
	v_pk_fma_f32 v[98:99], v[102:103], v[96:97], v[106:107]
	s_nop 0
	v_add_f32_e32 v98, v98, v119
	v_add_f32_e32 v110, v99, v98
	v_mov_b32_e32 v111, v110
	s_nop 1
	v_permlane16_swap_b32 v110, v111
	v_pk_mul_f32 v[98:99], v[100:101], v[104:105]
	v_pk_mul_f32 v[100:101], v[102:103], v[96:97]
	v_cvt_pk_bf16_f32 v98, v98, v99
	v_cvt_pk_bf16_f32 v99, v100, v101
	s_waitcnt lgkmcnt(0)
	v_add_f32_e32 v96, v110, v111
	v_mov_b32_e32 v97, v96
	s_nop 1
	v_permlane32_swap_b32 v96, v97
	v_cvt_pk_bf16_f32 v100, v108, v109
	v_cvt_pk_bf16_f32 v101, v106, v107
	global_store_dwordx4 v[136:137], v[98:101], off offset:256
	s_and_saveexec_b64 s[0:1], vcc
	s_cbranch_execz .LBB0_643
	s_waitcnt lgkmcnt(0)
	v_add_f32_e32 v96, v96, v97
	ds_write_b32 v114, v96 offset:64
.LBB0_643:
	s_or_b64 exec, exec, s[0:1]
	v_or_b32_e32 v104, 32, v132
	v_lshl_add_u32 v96, v104, 2, 0
	v_ashrrev_i32_e32 v105, 31, v104
	v_add_u32_e32 v96, 0x20000, v96
	v_lshlrev_b64 v[100:101], 9, v[104:105]
	ds_read_b32 v115, v96
	s_waitcnt lgkmcnt(0)
	ds_read_b128 v[96:99], v134
	v_lshl_add_u64 v[106:107], s[26:27], 0, v[100:101]
	ds_read_b128 v[100:103], v134 offset:16
	v_cmp_gt_i32_e64 s[0:1], v104, v128
	s_waitcnt lgkmcnt(0)
	v_sub_f32_e32 v96, v96, v115
	v_sub_f32_e32 v97, v97, v115
	v_sub_f32_e32 v100, v100, v115
	v_sub_f32_e32 v101, v101, v115
	v_min_f32_e32 v100, 0, v100
	v_min_f32_e32 v101, 0, v101
	v_min_f32_e32 v96, 0, v96
	v_mul_f32_e32 v100, 0x3fb8aa3b, v100
	v_min_f32_e32 v97, 0, v97
	v_cndmask_b32_e64 v109, 0, 1.0, s[0:1]
	v_cmp_gt_i32_e64 s[0:1], v128, v104
	v_mul_f32_e32 v101, 0x3fb8aa3b, v101
	v_mul_f32_e32 v96, 0x3fb8aa3b, v96
	v_exp_f32_e32 v100, v100
	v_mul_f32_e32 v97, 0x3fb8aa3b, v97
	v_cndmask_b32_e64 v108, 1.0, 0, s[0:1]
	v_exp_f32_e32 v101, v101
	v_cmp_gt_i32_e64 s[0:1], v131, v104
	v_exp_f32_e32 v96, v96
	v_exp_f32_e32 v97, v97
	v_cndmask_b32_e64 v111, 1.0, 0, s[0:1]
	v_cmp_gt_i32_e64 s[0:1], v124, v104
	v_pk_mul_f32 v[92:93], v[92:93], v[108:109]
	s_nop 0
	v_cndmask_b32_e64 v110, 1.0, 0, s[0:1]
	v_pk_mul_f32 v[88:89], v[88:89], v[110:111]
	v_pk_mul_f32 v[108:109], v[92:93], v[96:97]
	v_pk_mul_f32 v[100:101], v[88:89], v[100:101]
	v_cmp_gt_i32_e64 s[0:1], v125, v104
	v_pk_fma_f32 v[88:89], v[92:93], v[96:97], v[100:101]
	s_nop 0
	v_add_f32_e32 v88, 0, v88
	v_add_f32_e32 v105, v89, v88
	v_sub_f32_e32 v88, v98, v115
	v_sub_f32_e32 v89, v99, v115
	v_min_f32_e32 v88, 0, v88
	v_min_f32_e32 v89, 0, v89
	v_mul_f32_e32 v88, 0x3fb8aa3b, v88
	v_mul_f32_e32 v89, 0x3fb8aa3b, v89
	v_exp_f32_e32 v92, v88
	v_sub_f32_e32 v88, v102, v115
	v_exp_f32_e32 v93, v89
	v_sub_f32_e32 v89, v103, v115
	v_min_f32_e32 v88, 0, v88
	v_min_f32_e32 v89, 0, v89
	v_mul_f32_e32 v88, 0x3fb8aa3b, v88
	v_cndmask_b32_e64 v97, 1.0, 0, s[0:1]
	v_cmp_gt_i32_e64 s[0:1], v130, v104
	v_mul_f32_e32 v89, 0x3fb8aa3b, v89
	v_exp_f32_e32 v88, v88
	v_cndmask_b32_e64 v96, 1.0, 0, s[0:1]
	v_exp_f32_e32 v89, v89
	v_cmp_gt_i32_e64 s[0:1], v121, v104
	v_pk_mul_f32 v[94:95], v[94:95], v[96:97]
	s_nop 0
	v_cndmask_b32_e64 v99, 1.0, 0, s[0:1]
	v_cmp_gt_i32_e64 s[0:1], v120, v104
	v_pk_mul_f32 v[96:97], v[94:95], v[92:93]
	s_nop 0
	v_cndmask_b32_e64 v98, 1.0, 0, s[0:1]
	v_pk_mul_f32 v[90:91], v[90:91], v[98:99]
	v_cmp_gt_i32_e64 s[0:1], v104, v126
	v_pk_mul_f32 v[98:99], v[90:91], v[88:89]
	v_cvt_pk_bf16_f32 v88, v108, v109
	v_cvt_pk_bf16_f32 v89, v96, v97
	v_cvt_pk_bf16_f32 v90, v100, v101
	v_cvt_pk_bf16_f32 v91, v98, v99
	v_lshl_add_u64 v[96:97], v[128:129], 1, v[106:107]
	v_pk_fma_f32 v[92:93], v[94:95], v[92:93], v[98:99]
	global_store_dwordx4 v[96:97], v[88:91], off
	v_add_f32_e32 v92, v92, v105
	ds_read_b128 v[88:91], v134 offset:512
	v_add_f32_e32 v100, v93, v92
	ds_read_b128 v[92:95], v134 offset:528
	v_cndmask_b32_e64 v99, 0, 1.0, s[0:1]
	v_cmp_gt_i32_e64 s[0:1], v126, v104
	s_waitcnt lgkmcnt(0)
	v_sub_f32_e32 v88, v88, v115
	v_sub_f32_e32 v89, v89, v115
	v_sub_f32_e32 v92, v92, v115
	v_sub_f32_e32 v93, v93, v115
	v_min_f32_e32 v92, 0, v92
	v_min_f32_e32 v93, 0, v93
	v_min_f32_e32 v88, 0, v88
	v_mul_f32_e32 v92, 0x3fb8aa3b, v92
	v_min_f32_e32 v89, 0, v89
	v_mul_f32_e32 v93, 0x3fb8aa3b, v93
	v_mul_f32_e32 v88, 0x3fb8aa3b, v88
	v_exp_f32_e32 v92, v92
	v_mul_f32_e32 v89, 0x3fb8aa3b, v89
	v_cndmask_b32_e64 v98, 1.0, 0, s[0:1]
	v_exp_f32_e32 v93, v93
	v_cmp_gt_i32_e64 s[0:1], v123, v104
	v_exp_f32_e32 v88, v88
	v_exp_f32_e32 v89, v89
	v_pk_mul_f32 v[84:85], v[84:85], v[98:99]
	v_cndmask_b32_e64 v99, 1.0, 0, s[0:1]
	v_cmp_gt_i32_e64 s[0:1], v122, v104
	s_nop 1
	v_cndmask_b32_e64 v98, 1.0, 0, s[0:1]
	v_pk_mul_f32 v[80:81], v[80:81], v[98:99]
	v_cmp_gt_i32_e64 s[0:1], v117, v104
	v_pk_mul_f32 v[92:93], v[80:81], v[92:93]
	s_nop 0
	v_pk_fma_f32 v[80:81], v[84:85], v[88:89], v[92:93]
	v_cndmask_b32_e64 v99, 1.0, 0, s[0:1]
	v_add_f32_e32 v80, v80, v100
	v_add_f32_e32 v100, v81, v80
	v_sub_f32_e32 v81, v94, v115
	v_min_f32_e32 v81, 0, v81
	v_mul_f32_e32 v81, 0x3fb8aa3b, v81
	v_sub_f32_e32 v80, v90, v115
	v_exp_f32_e32 v90, v81
	v_sub_f32_e32 v81, v91, v115
	v_sub_f32_e32 v91, v95, v115
	v_min_f32_e32 v91, 0, v91
	v_min_f32_e32 v80, 0, v80
	v_min_f32_e32 v81, 0, v81
	v_cmp_gt_i32_e64 s[0:1], v116, v104
	v_mul_f32_e32 v91, 0x3fb8aa3b, v91
	v_mul_f32_e32 v80, 0x3fb8aa3b, v80
	v_mul_f32_e32 v81, 0x3fb8aa3b, v81
	v_cndmask_b32_e64 v98, 1.0, 0, s[0:1]
	v_exp_f32_e32 v91, v91
	v_cmp_gt_i32_e64 s[0:1], v113, v104
	v_exp_f32_e32 v80, v80
	v_exp_f32_e32 v81, v81
	v_cndmask_b32_e64 v95, 1.0, 0, s[0:1]
	v_cmp_gt_i32_e64 s[0:1], v112, v104
	v_pk_mul_f32 v[86:87], v[86:87], v[98:99]
	s_nop 0
	v_cndmask_b32_e64 v94, 1.0, 0, s[0:1]
	v_pk_mul_f32 v[82:83], v[82:83], v[94:95]
	s_nop 0
	v_pk_mul_f32 v[90:91], v[82:83], v[90:91]
	s_nop 0
	v_pk_fma_f32 v[82:83], v[86:87], v[80:81], v[90:91]
	s_nop 0
	v_add_f32_e32 v82, v82, v100
	v_add_f32_e32 v94, v83, v82
	v_mov_b32_e32 v95, v94
	s_nop 1
	v_permlane16_swap_b32 v94, v95
	v_pk_mul_f32 v[82:83], v[84:85], v[88:89]
	v_pk_mul_f32 v[84:85], v[86:87], v[80:81]
	v_cvt_pk_bf16_f32 v82, v82, v83
	v_cvt_pk_bf16_f32 v83, v84, v85
	s_waitcnt lgkmcnt(0)
	v_add_f32_e32 v80, v94, v95
	v_mov_b32_e32 v81, v80
	s_nop 1
	v_permlane32_swap_b32 v80, v81
	v_cvt_pk_bf16_f32 v84, v92, v93
	v_cvt_pk_bf16_f32 v85, v90, v91
	global_store_dwordx4 v[96:97], v[82:85], off offset:256
	s_and_saveexec_b64 s[0:1], vcc
	s_cbranch_execz .LBB0_645
	s_waitcnt lgkmcnt(0)
	v_add_f32_e32 v80, v80, v81
	ds_write_b32 v114, v80 offset:128
.LBB0_645:
	s_or_b64 exec, exec, s[0:1]
	v_or_b32_e32 v88, 48, v132
	v_lshl_add_u32 v80, v88, 2, 0
	v_ashrrev_i32_e32 v89, 31, v88
	v_add_u32_e32 v80, 0x20000, v80
	v_lshlrev_b64 v[84:85], 9, v[88:89]
	ds_read_b32 v96, v80
	s_waitcnt lgkmcnt(0)
	ds_read_b128 v[80:83], v134
	v_lshl_add_u64 v[90:91], s[26:27], 0, v[84:85]
	ds_read_b128 v[84:87], v134 offset:16
	v_cmp_gt_i32_e64 s[0:1], v88, v128
	s_waitcnt lgkmcnt(0)
	v_sub_f32_e32 v80, v80, v96
	v_sub_f32_e32 v81, v81, v96
	v_sub_f32_e32 v84, v84, v96
	v_sub_f32_e32 v85, v85, v96
	v_min_f32_e32 v84, 0, v84
	v_min_f32_e32 v85, 0, v85
	v_min_f32_e32 v80, 0, v80
	v_mul_f32_e32 v84, 0x3fb8aa3b, v84
	v_min_f32_e32 v81, 0, v81
	v_cndmask_b32_e64 v93, 0, 1.0, s[0:1]
	v_cmp_gt_i32_e64 s[0:1], v128, v88
	v_mul_f32_e32 v85, 0x3fb8aa3b, v85
	v_mul_f32_e32 v80, 0x3fb8aa3b, v80
	v_exp_f32_e32 v84, v84
	v_mul_f32_e32 v81, 0x3fb8aa3b, v81
	v_cndmask_b32_e64 v92, 1.0, 0, s[0:1]
	v_exp_f32_e32 v85, v85
	v_cmp_gt_i32_e64 s[0:1], v131, v88
	v_exp_f32_e32 v80, v80
	v_exp_f32_e32 v81, v81
	v_cndmask_b32_e64 v95, 1.0, 0, s[0:1]
	v_cmp_gt_i32_e64 s[0:1], v124, v88
	v_pk_mul_f32 v[76:77], v[76:77], v[92:93]
	s_nop 0
	v_cndmask_b32_e64 v94, 1.0, 0, s[0:1]
	v_pk_mul_f32 v[72:73], v[72:73], v[94:95]
	v_pk_mul_f32 v[92:93], v[76:77], v[80:81]
	v_pk_mul_f32 v[84:85], v[72:73], v[84:85]
	v_cmp_gt_i32_e64 s[0:1], v125, v88
	v_pk_fma_f32 v[72:73], v[76:77], v[80:81], v[84:85]
	s_nop 0
	v_add_f32_e32 v72, 0, v72
	v_add_f32_e32 v89, v73, v72
	v_sub_f32_e32 v72, v82, v96
	v_sub_f32_e32 v73, v83, v96
	v_min_f32_e32 v72, 0, v72
	v_min_f32_e32 v73, 0, v73
	v_mul_f32_e32 v72, 0x3fb8aa3b, v72
	v_mul_f32_e32 v73, 0x3fb8aa3b, v73
	v_exp_f32_e32 v76, v72
	v_sub_f32_e32 v72, v86, v96
	v_exp_f32_e32 v77, v73
	v_sub_f32_e32 v73, v87, v96
	v_min_f32_e32 v72, 0, v72
	v_min_f32_e32 v73, 0, v73
	v_mul_f32_e32 v72, 0x3fb8aa3b, v72
	v_cndmask_b32_e64 v81, 1.0, 0, s[0:1]
	v_cmp_gt_i32_e64 s[0:1], v130, v88
	v_mul_f32_e32 v73, 0x3fb8aa3b, v73
	v_exp_f32_e32 v72, v72
	v_cndmask_b32_e64 v80, 1.0, 0, s[0:1]
	v_exp_f32_e32 v73, v73
	v_cmp_gt_i32_e64 s[0:1], v121, v88
	v_pk_mul_f32 v[78:79], v[78:79], v[80:81]
	s_nop 0
	v_cndmask_b32_e64 v83, 1.0, 0, s[0:1]
	v_cmp_gt_i32_e64 s[0:1], v120, v88
	v_pk_mul_f32 v[80:81], v[78:79], v[76:77]
	s_nop 0
	v_cndmask_b32_e64 v82, 1.0, 0, s[0:1]
	v_pk_mul_f32 v[74:75], v[74:75], v[82:83]
	v_cmp_gt_i32_e64 s[0:1], v88, v126
	v_pk_mul_f32 v[82:83], v[74:75], v[72:73]
	v_cvt_pk_bf16_f32 v72, v92, v93
	v_cvt_pk_bf16_f32 v73, v80, v81
	v_cvt_pk_bf16_f32 v74, v84, v85
	v_cvt_pk_bf16_f32 v75, v82, v83
	v_lshl_add_u64 v[80:81], v[128:129], 1, v[90:91]
	v_pk_fma_f32 v[76:77], v[78:79], v[76:77], v[82:83]
	global_store_dwordx4 v[80:81], v[72:75], off
	v_add_f32_e32 v76, v76, v89
	ds_read_b128 v[72:75], v134 offset:512
	v_add_f32_e32 v84, v77, v76
	ds_read_b128 v[76:79], v134 offset:528
	v_cndmask_b32_e64 v83, 0, 1.0, s[0:1]
	v_cmp_gt_i32_e64 s[0:1], v126, v88
	s_waitcnt lgkmcnt(0)
	v_sub_f32_e32 v72, v72, v96
	v_sub_f32_e32 v73, v73, v96
	v_sub_f32_e32 v76, v76, v96
	v_sub_f32_e32 v77, v77, v96
	v_min_f32_e32 v76, 0, v76
	v_min_f32_e32 v77, 0, v77
	v_min_f32_e32 v72, 0, v72
	v_mul_f32_e32 v76, 0x3fb8aa3b, v76
	v_min_f32_e32 v73, 0, v73
	v_mul_f32_e32 v77, 0x3fb8aa3b, v77
	v_mul_f32_e32 v72, 0x3fb8aa3b, v72
	v_exp_f32_e32 v76, v76
	v_mul_f32_e32 v73, 0x3fb8aa3b, v73
	v_cndmask_b32_e64 v82, 1.0, 0, s[0:1]
	v_exp_f32_e32 v77, v77
	v_cmp_gt_i32_e64 s[0:1], v123, v88
	v_exp_f32_e32 v72, v72
	v_exp_f32_e32 v73, v73
	v_pk_mul_f32 v[68:69], v[68:69], v[82:83]
	v_cndmask_b32_e64 v83, 1.0, 0, s[0:1]
	v_cmp_gt_i32_e64 s[0:1], v122, v88
	s_nop 1
	v_cndmask_b32_e64 v82, 1.0, 0, s[0:1]
	v_pk_mul_f32 v[64:65], v[64:65], v[82:83]
	v_cmp_gt_i32_e64 s[0:1], v117, v88
	v_pk_mul_f32 v[76:77], v[64:65], v[76:77]
	s_nop 0
	v_pk_fma_f32 v[64:65], v[68:69], v[72:73], v[76:77]
	v_cndmask_b32_e64 v83, 1.0, 0, s[0:1]
	v_add_f32_e32 v64, v64, v84
	v_add_f32_e32 v84, v65, v64
	v_sub_f32_e32 v65, v78, v96
	v_min_f32_e32 v65, 0, v65
	v_mul_f32_e32 v65, 0x3fb8aa3b, v65
	v_sub_f32_e32 v64, v74, v96
	v_exp_f32_e32 v74, v65
	v_sub_f32_e32 v65, v75, v96
	v_sub_f32_e32 v75, v79, v96
	v_min_f32_e32 v75, 0, v75
	v_min_f32_e32 v64, 0, v64
	v_min_f32_e32 v65, 0, v65
	v_cmp_gt_i32_e64 s[0:1], v116, v88
	v_mul_f32_e32 v75, 0x3fb8aa3b, v75
	v_mul_f32_e32 v64, 0x3fb8aa3b, v64
	v_mul_f32_e32 v65, 0x3fb8aa3b, v65
	v_cndmask_b32_e64 v82, 1.0, 0, s[0:1]
	v_exp_f32_e32 v75, v75
	v_cmp_gt_i32_e64 s[0:1], v113, v88
	v_exp_f32_e32 v64, v64
	v_exp_f32_e32 v65, v65
	v_cndmask_b32_e64 v79, 1.0, 0, s[0:1]
	v_cmp_gt_i32_e64 s[0:1], v112, v88
	v_pk_mul_f32 v[70:71], v[70:71], v[82:83]
	s_nop 0
	v_cndmask_b32_e64 v78, 1.0, 0, s[0:1]
	v_pk_mul_f32 v[66:67], v[66:67], v[78:79]
	s_nop 0
	v_pk_mul_f32 v[74:75], v[66:67], v[74:75]
	s_nop 0
	v_pk_fma_f32 v[66:67], v[70:71], v[64:65], v[74:75]
	s_nop 0
	v_add_f32_e32 v66, v66, v84
	v_add_f32_e32 v78, v67, v66
	v_mov_b32_e32 v79, v78
	s_nop 1
	v_permlane16_swap_b32 v78, v79
	v_pk_mul_f32 v[66:67], v[68:69], v[72:73]
	v_pk_mul_f32 v[68:69], v[70:71], v[64:65]
	v_cvt_pk_bf16_f32 v66, v66, v67
	v_cvt_pk_bf16_f32 v67, v68, v69
	s_waitcnt lgkmcnt(0)
	v_add_f32_e32 v64, v78, v79
	v_mov_b32_e32 v65, v64
	s_nop 1
	v_permlane32_swap_b32 v64, v65
	v_cvt_pk_bf16_f32 v68, v76, v77
	v_cvt_pk_bf16_f32 v69, v74, v75
	global_store_dwordx4 v[80:81], v[66:69], off offset:256
	s_and_saveexec_b64 s[0:1], vcc
	s_cbranch_execz .LBB0_647
	s_waitcnt lgkmcnt(0)
	v_add_f32_e32 v64, v64, v65
	ds_write_b32 v114, v64 offset:192
.LBB0_647:
	s_or_b64 exec, exec, s[0:1]
	v_add_u32_e32 v64, 0x80, v132
	ds_read_b32 v80, v135 offset:512
	ds_read_b128 v[66:69], v134
	s_waitcnt lgkmcnt(0)
	v_ashrrev_i32_e32 v65, 31, v64
	v_lshlrev_b64 v[70:71], 9, v[64:65]
	v_lshl_add_u64 v[74:75], s[26:27], 0, v[70:71]
	ds_read_b128 v[70:73], v134 offset:16
	v_sub_f32_e32 v65, v66, v80
	v_min_f32_e32 v65, 0, v65
	v_mul_f32_e32 v65, 0x3fb8aa3b, v65
	v_exp_f32_e32 v66, v65
	s_waitcnt lgkmcnt(0)
	v_sub_f32_e32 v65, v70, v80
	v_min_f32_e32 v65, 0, v65
	v_mul_f32_e32 v65, 0x3fb8aa3b, v65
	v_exp_f32_e32 v70, v65
	v_sub_f32_e32 v65, v67, v80
	v_min_f32_e32 v65, 0, v65
	v_mul_f32_e32 v65, 0x3fb8aa3b, v65
	v_exp_f32_e32 v67, v65
	v_sub_f32_e32 v65, v71, v80
	v_cmp_gt_i32_e64 s[0:1], v64, v128
	v_min_f32_e32 v65, 0, v65
	v_mul_f32_e32 v65, 0x3fb8aa3b, v65
	v_cndmask_b32_e64 v77, 0, 1.0, s[0:1]
	v_cmp_gt_i32_e64 s[0:1], v128, v64
	v_exp_f32_e32 v71, v65
	s_nop 0
	v_cndmask_b32_e64 v76, 1.0, 0, s[0:1]
	v_cmp_gt_i32_e64 s[0:1], v131, v64
	v_pk_mul_f32 v[60:61], v[60:61], v[76:77]
	s_nop 0
	v_cndmask_b32_e64 v79, 1.0, 0, s[0:1]
	v_cmp_gt_i32_e64 s[0:1], v124, v64
	v_pk_mul_f32 v[76:77], v[60:61], v[66:67]
	s_nop 0
	v_cndmask_b32_e64 v78, 1.0, 0, s[0:1]
	v_pk_mul_f32 v[56:57], v[56:57], v[78:79]
	v_cmp_gt_i32_e64 s[0:1], v125, v64
	v_pk_mul_f32 v[70:71], v[56:57], v[70:71]
	s_nop 0
	v_pk_fma_f32 v[56:57], v[60:61], v[66:67], v[70:71]
	v_cndmask_b32_e64 v67, 1.0, 0, s[0:1]
	v_add_f32_e32 v56, 0, v56
	v_add_f32_e32 v65, v57, v56
	v_sub_f32_e32 v56, v68, v80
	v_sub_f32_e32 v57, v69, v80
	v_min_f32_e32 v56, 0, v56
	v_min_f32_e32 v57, 0, v57
	v_mul_f32_e32 v56, 0x3fb8aa3b, v56
	v_mul_f32_e32 v57, 0x3fb8aa3b, v57
	v_exp_f32_e32 v60, v56
	v_sub_f32_e32 v56, v72, v80
	v_exp_f32_e32 v61, v57
	v_sub_f32_e32 v57, v73, v80
	v_min_f32_e32 v56, 0, v56
	v_min_f32_e32 v57, 0, v57
	v_mul_f32_e32 v56, 0x3fb8aa3b, v56
	v_cmp_gt_i32_e64 s[0:1], v130, v64
	v_mul_f32_e32 v57, 0x3fb8aa3b, v57
	v_exp_f32_e32 v56, v56
	v_cndmask_b32_e64 v66, 1.0, 0, s[0:1]
	v_exp_f32_e32 v57, v57
	v_cmp_gt_i32_e64 s[0:1], v121, v64
	v_pk_mul_f32 v[62:63], v[62:63], v[66:67]
	s_nop 0
	v_cndmask_b32_e64 v69, 1.0, 0, s[0:1]
	v_cmp_gt_i32_e64 s[0:1], v120, v64
	v_pk_mul_f32 v[66:67], v[62:63], v[60:61]
	s_nop 0
	v_cndmask_b32_e64 v68, 1.0, 0, s[0:1]
	v_pk_mul_f32 v[58:59], v[58:59], v[68:69]
	v_cmp_gt_i32_e64 s[0:1], v64, v126
	v_pk_mul_f32 v[68:69], v[58:59], v[56:57]
	v_cvt_pk_bf16_f32 v56, v76, v77
	v_cvt_pk_bf16_f32 v57, v66, v67
	v_cvt_pk_bf16_f32 v58, v70, v71
	v_cvt_pk_bf16_f32 v59, v68, v69
	v_lshl_add_u64 v[66:67], v[128:129], 1, v[74:75]
	v_pk_fma_f32 v[60:61], v[62:63], v[60:61], v[68:69]
	global_store_dwordx4 v[66:67], v[56:59], off
	v_add_f32_e32 v60, v60, v65
	ds_read_b128 v[56:59], v134 offset:512
	v_add_f32_e32 v65, v61, v60
	ds_read_b128 v[60:63], v134 offset:528
	v_cndmask_b32_e64 v69, 0, 1.0, s[0:1]
	v_cmp_gt_i32_e64 s[0:1], v126, v64
	s_waitcnt lgkmcnt(0)
	v_sub_f32_e32 v56, v56, v80
	v_sub_f32_e32 v57, v57, v80
	v_sub_f32_e32 v60, v60, v80
	v_sub_f32_e32 v61, v61, v80
	v_min_f32_e32 v60, 0, v60
	v_min_f32_e32 v61, 0, v61
	v_min_f32_e32 v56, 0, v56
	v_mul_f32_e32 v60, 0x3fb8aa3b, v60
	v_min_f32_e32 v57, 0, v57
	v_mul_f32_e32 v61, 0x3fb8aa3b, v61
	v_mul_f32_e32 v56, 0x3fb8aa3b, v56
	v_exp_f32_e32 v60, v60
	v_mul_f32_e32 v57, 0x3fb8aa3b, v57
	v_cndmask_b32_e64 v68, 1.0, 0, s[0:1]
	v_exp_f32_e32 v61, v61
	v_cmp_gt_i32_e64 s[0:1], v123, v64
	v_exp_f32_e32 v56, v56
	v_exp_f32_e32 v57, v57
	v_pk_mul_f32 v[52:53], v[52:53], v[68:69]
	v_cndmask_b32_e64 v69, 1.0, 0, s[0:1]
	v_cmp_gt_i32_e64 s[0:1], v122, v64
	s_nop 1
	v_cndmask_b32_e64 v68, 1.0, 0, s[0:1]
	v_pk_mul_f32 v[48:49], v[48:49], v[68:69]
	v_cmp_gt_i32_e64 s[0:1], v117, v64
	v_pk_mul_f32 v[60:61], v[48:49], v[60:61]
	s_nop 0
	v_pk_fma_f32 v[48:49], v[52:53], v[56:57], v[60:61]
	v_cndmask_b32_e64 v69, 1.0, 0, s[0:1]
	v_add_f32_e32 v48, v48, v65
	v_add_f32_e32 v65, v49, v48
	v_sub_f32_e32 v49, v62, v80
	v_min_f32_e32 v49, 0, v49
	v_mul_f32_e32 v49, 0x3fb8aa3b, v49
	v_sub_f32_e32 v48, v58, v80
	v_exp_f32_e32 v58, v49
	v_sub_f32_e32 v49, v59, v80
	v_sub_f32_e32 v59, v63, v80
	v_min_f32_e32 v59, 0, v59
	v_min_f32_e32 v48, 0, v48
	v_min_f32_e32 v49, 0, v49
	v_cmp_gt_i32_e64 s[0:1], v116, v64
	v_mul_f32_e32 v59, 0x3fb8aa3b, v59
	v_mul_f32_e32 v48, 0x3fb8aa3b, v48
	v_mul_f32_e32 v49, 0x3fb8aa3b, v49
	v_cndmask_b32_e64 v68, 1.0, 0, s[0:1]
	v_exp_f32_e32 v59, v59
	v_cmp_gt_i32_e64 s[0:1], v113, v64
	v_exp_f32_e32 v48, v48
	v_exp_f32_e32 v49, v49
	v_cndmask_b32_e64 v63, 1.0, 0, s[0:1]
	v_cmp_gt_i32_e64 s[0:1], v112, v64
	v_pk_mul_f32 v[54:55], v[54:55], v[68:69]
	s_nop 0
	v_cndmask_b32_e64 v62, 1.0, 0, s[0:1]
	v_pk_mul_f32 v[50:51], v[50:51], v[62:63]
	s_nop 0
	v_pk_mul_f32 v[58:59], v[50:51], v[58:59]
	s_nop 0
	v_pk_fma_f32 v[50:51], v[54:55], v[48:49], v[58:59]
	s_nop 0
	v_add_f32_e32 v50, v50, v65
	v_add_f32_e32 v62, v51, v50
	v_mov_b32_e32 v63, v62
	s_nop 1
	v_permlane16_swap_b32 v62, v63
	v_pk_mul_f32 v[50:51], v[52:53], v[56:57]
	v_pk_mul_f32 v[52:53], v[54:55], v[48:49]
	v_cvt_pk_bf16_f32 v50, v50, v51
	v_cvt_pk_bf16_f32 v51, v52, v53
	s_waitcnt lgkmcnt(0)
	v_add_f32_e32 v48, v62, v63
	v_mov_b32_e32 v49, v48
	s_nop 1
	v_permlane32_swap_b32 v48, v49
	v_cvt_pk_bf16_f32 v52, v60, v61
	v_cvt_pk_bf16_f32 v53, v58, v59
	global_store_dwordx4 v[66:67], v[50:53], off offset:256
	s_and_saveexec_b64 s[0:1], vcc
	s_cbranch_execz .LBB0_649
	s_waitcnt lgkmcnt(0)
	v_add_f32_e32 v48, v48, v49
	ds_write_b32 v114, v48 offset:512
.LBB0_649:
	s_or_b64 exec, exec, s[0:1]
	v_or_b32_e32 v56, 16, v64
	v_lshl_add_u32 v48, v56, 2, 0
	v_ashrrev_i32_e32 v57, 31, v56
	v_add_u32_e32 v48, 0x20000, v48
	v_lshlrev_b64 v[52:53], 9, v[56:57]
	ds_read_b32 v65, v48
	s_waitcnt lgkmcnt(0)
	ds_read_b128 v[48:51], v134
	v_lshl_add_u64 v[58:59], s[26:27], 0, v[52:53]
	ds_read_b128 v[52:55], v134 offset:16
	v_cmp_gt_i32_e64 s[0:1], v56, v128
	s_waitcnt lgkmcnt(0)
	v_sub_f32_e32 v48, v48, v65
	v_sub_f32_e32 v49, v49, v65
	v_sub_f32_e32 v52, v52, v65
	v_sub_f32_e32 v53, v53, v65
	v_min_f32_e32 v52, 0, v52
	v_min_f32_e32 v53, 0, v53
	v_min_f32_e32 v48, 0, v48
	v_mul_f32_e32 v52, 0x3fb8aa3b, v52
	v_min_f32_e32 v49, 0, v49
	v_cndmask_b32_e64 v61, 0, 1.0, s[0:1]
	v_cmp_gt_i32_e64 s[0:1], v128, v56
	v_mul_f32_e32 v53, 0x3fb8aa3b, v53
	v_mul_f32_e32 v48, 0x3fb8aa3b, v48
	v_exp_f32_e32 v52, v52
	v_mul_f32_e32 v49, 0x3fb8aa3b, v49
	v_cndmask_b32_e64 v60, 1.0, 0, s[0:1]
	v_exp_f32_e32 v53, v53
	v_cmp_gt_i32_e64 s[0:1], v131, v56
	v_exp_f32_e32 v48, v48
	v_exp_f32_e32 v49, v49
	v_cndmask_b32_e64 v63, 1.0, 0, s[0:1]
	v_cmp_gt_i32_e64 s[0:1], v124, v56
	v_pk_mul_f32 v[44:45], v[44:45], v[60:61]
	s_nop 0
	v_cndmask_b32_e64 v62, 1.0, 0, s[0:1]
	v_pk_mul_f32 v[40:41], v[40:41], v[62:63]
	v_pk_mul_f32 v[60:61], v[44:45], v[48:49]
	v_pk_mul_f32 v[52:53], v[40:41], v[52:53]
	v_cmp_gt_i32_e64 s[0:1], v125, v56
	v_pk_fma_f32 v[40:41], v[44:45], v[48:49], v[52:53]
	s_nop 0
	v_add_f32_e32 v40, 0, v40
	v_add_f32_e32 v57, v41, v40
	v_sub_f32_e32 v40, v50, v65
	v_sub_f32_e32 v41, v51, v65
	v_min_f32_e32 v40, 0, v40
	v_min_f32_e32 v41, 0, v41
	v_mul_f32_e32 v40, 0x3fb8aa3b, v40
	v_mul_f32_e32 v41, 0x3fb8aa3b, v41
	v_exp_f32_e32 v44, v40
	v_sub_f32_e32 v40, v54, v65
	v_exp_f32_e32 v45, v41
	v_sub_f32_e32 v41, v55, v65
	v_min_f32_e32 v40, 0, v40
	v_min_f32_e32 v41, 0, v41
	v_mul_f32_e32 v40, 0x3fb8aa3b, v40
	v_cndmask_b32_e64 v49, 1.0, 0, s[0:1]
	v_cmp_gt_i32_e64 s[0:1], v130, v56
	v_mul_f32_e32 v41, 0x3fb8aa3b, v41
	v_exp_f32_e32 v40, v40
	v_cndmask_b32_e64 v48, 1.0, 0, s[0:1]
	v_exp_f32_e32 v41, v41
	v_cmp_gt_i32_e64 s[0:1], v121, v56
	v_pk_mul_f32 v[46:47], v[46:47], v[48:49]
	s_nop 0
	v_cndmask_b32_e64 v51, 1.0, 0, s[0:1]
	v_cmp_gt_i32_e64 s[0:1], v120, v56
	v_pk_mul_f32 v[48:49], v[46:47], v[44:45]
	s_nop 0
	v_cndmask_b32_e64 v50, 1.0, 0, s[0:1]
	v_pk_mul_f32 v[42:43], v[42:43], v[50:51]
	v_cmp_gt_i32_e64 s[0:1], v56, v126
	v_pk_mul_f32 v[50:51], v[42:43], v[40:41]
	v_cvt_pk_bf16_f32 v40, v60, v61
	v_cvt_pk_bf16_f32 v41, v48, v49
	v_cvt_pk_bf16_f32 v42, v52, v53
	v_cvt_pk_bf16_f32 v43, v50, v51
	v_lshl_add_u64 v[48:49], v[128:129], 1, v[58:59]
	v_pk_fma_f32 v[44:45], v[46:47], v[44:45], v[50:51]
	global_store_dwordx4 v[48:49], v[40:43], off
	v_add_f32_e32 v44, v44, v57
	ds_read_b128 v[40:43], v134 offset:512
	v_add_f32_e32 v52, v45, v44
	ds_read_b128 v[44:47], v134 offset:528
	v_cndmask_b32_e64 v51, 0, 1.0, s[0:1]
	v_cmp_gt_i32_e64 s[0:1], v126, v56
	s_waitcnt lgkmcnt(0)
	v_sub_f32_e32 v40, v40, v65
	v_sub_f32_e32 v41, v41, v65
	v_sub_f32_e32 v44, v44, v65
	v_sub_f32_e32 v45, v45, v65
	v_min_f32_e32 v44, 0, v44
	v_min_f32_e32 v45, 0, v45
	v_min_f32_e32 v40, 0, v40
	v_mul_f32_e32 v44, 0x3fb8aa3b, v44
	v_min_f32_e32 v41, 0, v41
	v_mul_f32_e32 v45, 0x3fb8aa3b, v45
	v_mul_f32_e32 v40, 0x3fb8aa3b, v40
	v_exp_f32_e32 v44, v44
	v_mul_f32_e32 v41, 0x3fb8aa3b, v41
	v_cndmask_b32_e64 v50, 1.0, 0, s[0:1]
	v_exp_f32_e32 v45, v45
	v_cmp_gt_i32_e64 s[0:1], v123, v56
	v_exp_f32_e32 v40, v40
	v_exp_f32_e32 v41, v41
	v_pk_mul_f32 v[36:37], v[36:37], v[50:51]
	v_cndmask_b32_e64 v51, 1.0, 0, s[0:1]
	v_cmp_gt_i32_e64 s[0:1], v122, v56
	s_nop 1
	v_cndmask_b32_e64 v50, 1.0, 0, s[0:1]
	v_pk_mul_f32 v[32:33], v[32:33], v[50:51]
	v_cmp_gt_i32_e64 s[0:1], v117, v56
	v_pk_mul_f32 v[44:45], v[32:33], v[44:45]
	s_nop 0
	v_pk_fma_f32 v[32:33], v[36:37], v[40:41], v[44:45]
	v_cndmask_b32_e64 v51, 1.0, 0, s[0:1]
	v_add_f32_e32 v32, v32, v52
	v_add_f32_e32 v52, v33, v32
	v_sub_f32_e32 v33, v46, v65
	v_min_f32_e32 v33, 0, v33
	v_mul_f32_e32 v33, 0x3fb8aa3b, v33
	v_sub_f32_e32 v32, v42, v65
	v_exp_f32_e32 v42, v33
	v_sub_f32_e32 v33, v43, v65
	v_sub_f32_e32 v43, v47, v65
	v_min_f32_e32 v43, 0, v43
	v_min_f32_e32 v32, 0, v32
	v_min_f32_e32 v33, 0, v33
	v_cmp_gt_i32_e64 s[0:1], v116, v56
	v_mul_f32_e32 v43, 0x3fb8aa3b, v43
	v_mul_f32_e32 v32, 0x3fb8aa3b, v32
	v_mul_f32_e32 v33, 0x3fb8aa3b, v33
	v_cndmask_b32_e64 v50, 1.0, 0, s[0:1]
	v_exp_f32_e32 v43, v43
	v_cmp_gt_i32_e64 s[0:1], v113, v56
	v_exp_f32_e32 v32, v32
	v_exp_f32_e32 v33, v33
	v_cndmask_b32_e64 v47, 1.0, 0, s[0:1]
	v_cmp_gt_i32_e64 s[0:1], v112, v56
	v_pk_mul_f32 v[38:39], v[38:39], v[50:51]
	s_nop 0
	v_cndmask_b32_e64 v46, 1.0, 0, s[0:1]
	v_pk_mul_f32 v[34:35], v[34:35], v[46:47]
	s_nop 0
	v_pk_mul_f32 v[42:43], v[34:35], v[42:43]
	s_nop 0
	v_pk_fma_f32 v[34:35], v[38:39], v[32:33], v[42:43]
	s_nop 0
	v_add_f32_e32 v34, v34, v52
	v_add_f32_e32 v46, v35, v34
	v_mov_b32_e32 v47, v46
	s_nop 1
	v_permlane16_swap_b32 v46, v47
	v_pk_mul_f32 v[34:35], v[36:37], v[40:41]
	v_pk_mul_f32 v[36:37], v[38:39], v[32:33]
	v_cvt_pk_bf16_f32 v34, v34, v35
	v_cvt_pk_bf16_f32 v35, v36, v37
	s_waitcnt lgkmcnt(0)
	v_add_f32_e32 v32, v46, v47
	v_mov_b32_e32 v33, v32
	s_nop 1
	v_permlane32_swap_b32 v32, v33
	v_cvt_pk_bf16_f32 v36, v44, v45
	v_cvt_pk_bf16_f32 v37, v42, v43
	global_store_dwordx4 v[48:49], v[34:37], off offset:256
	s_and_saveexec_b64 s[0:1], vcc
	s_cbranch_execz .LBB0_651
	s_waitcnt lgkmcnt(0)
	v_add_f32_e32 v32, v32, v33
	ds_write_b32 v114, v32 offset:576
.LBB0_651:
	s_or_b64 exec, exec, s[0:1]
	v_or_b32_e32 v40, 32, v64
	v_lshl_add_u32 v32, v40, 2, 0
	v_ashrrev_i32_e32 v41, 31, v40
	v_add_u32_e32 v32, 0x20000, v32
	v_lshlrev_b64 v[36:37], 9, v[40:41]
	ds_read_b32 v48, v32
	s_waitcnt lgkmcnt(0)
	ds_read_b128 v[32:35], v134
	v_lshl_add_u64 v[42:43], s[26:27], 0, v[36:37]
	ds_read_b128 v[36:39], v134 offset:16
	v_cmp_gt_i32_e64 s[0:1], v40, v128
	s_waitcnt lgkmcnt(0)
	v_sub_f32_e32 v32, v32, v48
	v_sub_f32_e32 v33, v33, v48
	v_sub_f32_e32 v36, v36, v48
	v_sub_f32_e32 v37, v37, v48
	v_min_f32_e32 v36, 0, v36
	v_min_f32_e32 v37, 0, v37
	v_min_f32_e32 v32, 0, v32
	v_mul_f32_e32 v36, 0x3fb8aa3b, v36
	v_min_f32_e32 v33, 0, v33
	v_cndmask_b32_e64 v45, 0, 1.0, s[0:1]
	v_cmp_gt_i32_e64 s[0:1], v128, v40
	v_mul_f32_e32 v37, 0x3fb8aa3b, v37
	v_mul_f32_e32 v32, 0x3fb8aa3b, v32
	v_exp_f32_e32 v36, v36
	v_mul_f32_e32 v33, 0x3fb8aa3b, v33
	v_cndmask_b32_e64 v44, 1.0, 0, s[0:1]
	v_exp_f32_e32 v37, v37
	v_cmp_gt_i32_e64 s[0:1], v131, v40
	v_exp_f32_e32 v32, v32
	v_exp_f32_e32 v33, v33
	v_cndmask_b32_e64 v47, 1.0, 0, s[0:1]
	v_cmp_gt_i32_e64 s[0:1], v124, v40
	v_pk_mul_f32 v[28:29], v[28:29], v[44:45]
	s_nop 0
	v_cndmask_b32_e64 v46, 1.0, 0, s[0:1]
	v_pk_mul_f32 v[24:25], v[24:25], v[46:47]
	v_pk_mul_f32 v[44:45], v[28:29], v[32:33]
	v_pk_mul_f32 v[36:37], v[24:25], v[36:37]
	v_cmp_gt_i32_e64 s[0:1], v125, v40
	v_pk_fma_f32 v[24:25], v[28:29], v[32:33], v[36:37]
	s_nop 0
	v_add_f32_e32 v24, 0, v24
	v_add_f32_e32 v41, v25, v24
	v_sub_f32_e32 v24, v34, v48
	v_sub_f32_e32 v25, v35, v48
	v_min_f32_e32 v24, 0, v24
	v_min_f32_e32 v25, 0, v25
	v_mul_f32_e32 v24, 0x3fb8aa3b, v24
	v_mul_f32_e32 v25, 0x3fb8aa3b, v25
	v_exp_f32_e32 v28, v24
	v_sub_f32_e32 v24, v38, v48
	v_exp_f32_e32 v29, v25
	v_sub_f32_e32 v25, v39, v48
	v_min_f32_e32 v24, 0, v24
	v_min_f32_e32 v25, 0, v25
	v_mul_f32_e32 v24, 0x3fb8aa3b, v24
	v_cndmask_b32_e64 v33, 1.0, 0, s[0:1]
	v_cmp_gt_i32_e64 s[0:1], v130, v40
	v_mul_f32_e32 v25, 0x3fb8aa3b, v25
	v_exp_f32_e32 v24, v24
	v_cndmask_b32_e64 v32, 1.0, 0, s[0:1]
	v_exp_f32_e32 v25, v25
	v_cmp_gt_i32_e64 s[0:1], v121, v40
	v_pk_mul_f32 v[30:31], v[30:31], v[32:33]
	s_nop 0
	v_cndmask_b32_e64 v35, 1.0, 0, s[0:1]
	v_cmp_gt_i32_e64 s[0:1], v120, v40
	v_pk_mul_f32 v[32:33], v[30:31], v[28:29]
	s_nop 0
	v_cndmask_b32_e64 v34, 1.0, 0, s[0:1]
	v_pk_mul_f32 v[26:27], v[26:27], v[34:35]
	v_cmp_gt_i32_e64 s[0:1], v40, v126
	v_pk_mul_f32 v[34:35], v[26:27], v[24:25]
	v_cvt_pk_bf16_f32 v24, v44, v45
	v_cvt_pk_bf16_f32 v25, v32, v33
	v_cvt_pk_bf16_f32 v26, v36, v37
	v_cvt_pk_bf16_f32 v27, v34, v35
	v_lshl_add_u64 v[32:33], v[128:129], 1, v[42:43]
	v_pk_fma_f32 v[28:29], v[30:31], v[28:29], v[34:35]
	global_store_dwordx4 v[32:33], v[24:27], off
	v_add_f32_e32 v28, v28, v41
	ds_read_b128 v[24:27], v134 offset:512
	v_add_f32_e32 v36, v29, v28
	ds_read_b128 v[28:31], v134 offset:528
	v_cndmask_b32_e64 v35, 0, 1.0, s[0:1]
	v_cmp_gt_i32_e64 s[0:1], v126, v40
	s_waitcnt lgkmcnt(0)
	v_sub_f32_e32 v24, v24, v48
	v_sub_f32_e32 v25, v25, v48
	v_sub_f32_e32 v28, v28, v48
	v_sub_f32_e32 v29, v29, v48
	v_min_f32_e32 v28, 0, v28
	v_min_f32_e32 v29, 0, v29
	v_min_f32_e32 v24, 0, v24
	v_mul_f32_e32 v28, 0x3fb8aa3b, v28
	v_min_f32_e32 v25, 0, v25
	v_mul_f32_e32 v29, 0x3fb8aa3b, v29
	v_mul_f32_e32 v24, 0x3fb8aa3b, v24
	v_exp_f32_e32 v28, v28
	v_mul_f32_e32 v25, 0x3fb8aa3b, v25
	v_cndmask_b32_e64 v34, 1.0, 0, s[0:1]
	v_exp_f32_e32 v29, v29
	v_cmp_gt_i32_e64 s[0:1], v123, v40
	v_exp_f32_e32 v24, v24
	v_exp_f32_e32 v25, v25
	v_pk_mul_f32 v[20:21], v[20:21], v[34:35]
	v_cndmask_b32_e64 v35, 1.0, 0, s[0:1]
	v_cmp_gt_i32_e64 s[0:1], v122, v40
	s_nop 1
	v_cndmask_b32_e64 v34, 1.0, 0, s[0:1]
	v_pk_mul_f32 v[16:17], v[16:17], v[34:35]
	v_cmp_gt_i32_e64 s[0:1], v117, v40
	v_pk_mul_f32 v[28:29], v[16:17], v[28:29]
	s_nop 0
	v_pk_fma_f32 v[16:17], v[20:21], v[24:25], v[28:29]
	v_cndmask_b32_e64 v35, 1.0, 0, s[0:1]
	v_add_f32_e32 v16, v16, v36
	v_add_f32_e32 v36, v17, v16
	v_sub_f32_e32 v17, v30, v48
	v_min_f32_e32 v17, 0, v17
	v_mul_f32_e32 v17, 0x3fb8aa3b, v17
	v_sub_f32_e32 v16, v26, v48
	v_exp_f32_e32 v26, v17
	v_sub_f32_e32 v17, v27, v48
	v_sub_f32_e32 v27, v31, v48
	v_min_f32_e32 v27, 0, v27
	v_min_f32_e32 v16, 0, v16
	v_min_f32_e32 v17, 0, v17
	v_cmp_gt_i32_e64 s[0:1], v116, v40
	v_mul_f32_e32 v27, 0x3fb8aa3b, v27
	v_mul_f32_e32 v16, 0x3fb8aa3b, v16
	v_mul_f32_e32 v17, 0x3fb8aa3b, v17
	v_cndmask_b32_e64 v34, 1.0, 0, s[0:1]
	v_exp_f32_e32 v27, v27
	v_cmp_gt_i32_e64 s[0:1], v113, v40
	v_exp_f32_e32 v16, v16
	v_exp_f32_e32 v17, v17
	v_cndmask_b32_e64 v31, 1.0, 0, s[0:1]
	v_cmp_gt_i32_e64 s[0:1], v112, v40
	v_pk_mul_f32 v[22:23], v[22:23], v[34:35]
	s_nop 0
	v_cndmask_b32_e64 v30, 1.0, 0, s[0:1]
	v_pk_mul_f32 v[18:19], v[18:19], v[30:31]
	s_nop 0
	v_pk_mul_f32 v[26:27], v[18:19], v[26:27]
	s_nop 0
	v_pk_fma_f32 v[18:19], v[22:23], v[16:17], v[26:27]
	s_nop 0
	v_add_f32_e32 v18, v18, v36
	v_add_f32_e32 v30, v19, v18
	v_mov_b32_e32 v31, v30
	s_nop 1
	v_permlane16_swap_b32 v30, v31
	v_pk_mul_f32 v[18:19], v[20:21], v[24:25]
	v_pk_mul_f32 v[20:21], v[22:23], v[16:17]
	v_cvt_pk_bf16_f32 v18, v18, v19
	v_cvt_pk_bf16_f32 v19, v20, v21
	s_waitcnt lgkmcnt(0)
	v_add_f32_e32 v16, v30, v31
	v_mov_b32_e32 v17, v16
	s_nop 1
	v_permlane32_swap_b32 v16, v17
	v_cvt_pk_bf16_f32 v20, v28, v29
	v_cvt_pk_bf16_f32 v21, v26, v27
	global_store_dwordx4 v[32:33], v[18:21], off offset:256
	s_and_saveexec_b64 s[0:1], vcc
	s_cbranch_execz .LBB0_653
	s_waitcnt lgkmcnt(0)
	v_add_f32_e32 v16, v16, v17
	ds_write_b32 v114, v16 offset:640
.LBB0_653:
	s_or_b64 exec, exec, s[0:1]
	v_or_b32_e32 v24, 48, v64
	v_lshl_add_u32 v16, v24, 2, 0
	v_ashrrev_i32_e32 v25, 31, v24
	v_add_u32_e32 v16, 0x20000, v16
	v_lshlrev_b64 v[20:21], 9, v[24:25]
	ds_read_b32 v32, v16
	s_waitcnt lgkmcnt(0)
	ds_read_b128 v[16:19], v134
	v_lshl_add_u64 v[26:27], s[26:27], 0, v[20:21]
	ds_read_b128 v[20:23], v134 offset:16
	v_cmp_gt_i32_e64 s[0:1], v24, v128
	s_waitcnt lgkmcnt(0)
	v_sub_f32_e32 v16, v16, v32
	v_sub_f32_e32 v17, v17, v32
	v_sub_f32_e32 v20, v20, v32
	v_sub_f32_e32 v21, v21, v32
	v_min_f32_e32 v20, 0, v20
	v_min_f32_e32 v21, 0, v21
	v_min_f32_e32 v16, 0, v16
	v_mul_f32_e32 v20, 0x3fb8aa3b, v20
	v_min_f32_e32 v17, 0, v17
	v_cndmask_b32_e64 v29, 0, 1.0, s[0:1]
	v_cmp_gt_i32_e64 s[0:1], v128, v24
	v_mul_f32_e32 v21, 0x3fb8aa3b, v21
	v_mul_f32_e32 v16, 0x3fb8aa3b, v16
	v_exp_f32_e32 v20, v20
	v_mul_f32_e32 v17, 0x3fb8aa3b, v17
	v_cndmask_b32_e64 v28, 1.0, 0, s[0:1]
	v_exp_f32_e32 v21, v21
	v_cmp_gt_i32_e64 s[0:1], v131, v24
	v_exp_f32_e32 v16, v16
	v_exp_f32_e32 v17, v17
	v_cndmask_b32_e64 v31, 1.0, 0, s[0:1]
	v_cmp_gt_i32_e64 s[0:1], v124, v24
	v_pk_mul_f32 v[12:13], v[12:13], v[28:29]
	s_nop 0
	v_cndmask_b32_e64 v30, 1.0, 0, s[0:1]
	v_pk_mul_f32 v[8:9], v[8:9], v[30:31]
	v_pk_mul_f32 v[28:29], v[12:13], v[16:17]
	v_pk_mul_f32 v[20:21], v[8:9], v[20:21]
	v_cmp_gt_i32_e64 s[0:1], v125, v24
	v_pk_fma_f32 v[8:9], v[12:13], v[16:17], v[20:21]
	s_nop 0
	v_add_f32_e32 v8, 0, v8
	v_add_f32_e32 v25, v9, v8
	v_sub_f32_e32 v8, v18, v32
	v_sub_f32_e32 v9, v19, v32
	v_min_f32_e32 v8, 0, v8
	v_min_f32_e32 v9, 0, v9
	v_mul_f32_e32 v8, 0x3fb8aa3b, v8
	v_mul_f32_e32 v9, 0x3fb8aa3b, v9
	v_exp_f32_e32 v12, v8
	v_sub_f32_e32 v8, v22, v32
	v_exp_f32_e32 v13, v9
	v_sub_f32_e32 v9, v23, v32
	v_min_f32_e32 v8, 0, v8
	v_min_f32_e32 v9, 0, v9
	v_mul_f32_e32 v8, 0x3fb8aa3b, v8
	v_cndmask_b32_e64 v17, 1.0, 0, s[0:1]
	v_cmp_gt_i32_e64 s[0:1], v130, v24
	v_mul_f32_e32 v9, 0x3fb8aa3b, v9
	v_exp_f32_e32 v8, v8
	v_cndmask_b32_e64 v16, 1.0, 0, s[0:1]
	v_exp_f32_e32 v9, v9
	v_cmp_gt_i32_e64 s[0:1], v121, v24
	v_pk_mul_f32 v[14:15], v[14:15], v[16:17]
	s_nop 0
	v_cndmask_b32_e64 v19, 1.0, 0, s[0:1]
	v_cmp_gt_i32_e64 s[0:1], v120, v24
	v_pk_mul_f32 v[16:17], v[14:15], v[12:13]
	s_nop 0
	v_cndmask_b32_e64 v18, 1.0, 0, s[0:1]
	v_pk_mul_f32 v[10:11], v[10:11], v[18:19]
	v_cmp_gt_i32_e64 s[0:1], v24, v126
	v_pk_mul_f32 v[18:19], v[10:11], v[8:9]
	v_cvt_pk_bf16_f32 v8, v28, v29
	v_cvt_pk_bf16_f32 v9, v16, v17
	v_cvt_pk_bf16_f32 v10, v20, v21
	v_cvt_pk_bf16_f32 v11, v18, v19
	v_lshl_add_u64 v[16:17], v[128:129], 1, v[26:27]
	v_pk_fma_f32 v[12:13], v[14:15], v[12:13], v[18:19]
	global_store_dwordx4 v[16:17], v[8:11], off
	v_add_f32_e32 v12, v12, v25
	ds_read_b128 v[8:11], v134 offset:512
	v_add_f32_e32 v20, v13, v12
	ds_read_b128 v[12:15], v134 offset:528
	v_cndmask_b32_e64 v19, 0, 1.0, s[0:1]
	v_cmp_gt_i32_e64 s[0:1], v126, v24
	s_waitcnt lgkmcnt(0)
	v_sub_f32_e32 v8, v8, v32
	v_sub_f32_e32 v9, v9, v32
	v_sub_f32_e32 v12, v12, v32
	v_sub_f32_e32 v13, v13, v32
	v_min_f32_e32 v12, 0, v12
	v_min_f32_e32 v13, 0, v13
	v_min_f32_e32 v8, 0, v8
	v_mul_f32_e32 v12, 0x3fb8aa3b, v12
	v_min_f32_e32 v9, 0, v9
	v_mul_f32_e32 v13, 0x3fb8aa3b, v13
	v_mul_f32_e32 v8, 0x3fb8aa3b, v8
	v_exp_f32_e32 v12, v12
	v_mul_f32_e32 v9, 0x3fb8aa3b, v9
	v_cndmask_b32_e64 v18, 1.0, 0, s[0:1]
	v_exp_f32_e32 v13, v13
	v_cmp_gt_i32_e64 s[0:1], v123, v24
	v_exp_f32_e32 v8, v8
	v_exp_f32_e32 v9, v9
	v_pk_mul_f32 v[4:5], v[4:5], v[18:19]
	v_cndmask_b32_e64 v19, 1.0, 0, s[0:1]
	v_cmp_gt_i32_e64 s[0:1], v122, v24
	s_nop 1
	v_cndmask_b32_e64 v18, 1.0, 0, s[0:1]
	v_pk_mul_f32 v[0:1], v[0:1], v[18:19]
	v_cmp_gt_i32_e64 s[0:1], v117, v24
	v_pk_mul_f32 v[12:13], v[0:1], v[12:13]
	s_nop 0
	v_pk_fma_f32 v[0:1], v[4:5], v[8:9], v[12:13]
	v_cndmask_b32_e64 v19, 1.0, 0, s[0:1]
	v_add_f32_e32 v0, v0, v20
	v_add_f32_e32 v20, v1, v0
	v_sub_f32_e32 v1, v14, v32
	v_min_f32_e32 v1, 0, v1
	v_mul_f32_e32 v1, 0x3fb8aa3b, v1
	v_sub_f32_e32 v0, v10, v32
	v_exp_f32_e32 v10, v1
	v_sub_f32_e32 v1, v11, v32
	v_sub_f32_e32 v11, v15, v32
	v_min_f32_e32 v11, 0, v11
	v_min_f32_e32 v0, 0, v0
	v_min_f32_e32 v1, 0, v1
	v_cmp_gt_i32_e64 s[0:1], v116, v24
	v_mul_f32_e32 v11, 0x3fb8aa3b, v11
	v_mul_f32_e32 v0, 0x3fb8aa3b, v0
	v_mul_f32_e32 v1, 0x3fb8aa3b, v1
	v_cndmask_b32_e64 v18, 1.0, 0, s[0:1]
	v_exp_f32_e32 v11, v11
	v_cmp_gt_i32_e64 s[0:1], v113, v24
	v_exp_f32_e32 v0, v0
	v_exp_f32_e32 v1, v1
	v_cndmask_b32_e64 v15, 1.0, 0, s[0:1]
	v_cmp_gt_i32_e64 s[0:1], v112, v24
	v_pk_mul_f32 v[6:7], v[6:7], v[18:19]
	s_nop 0
	v_cndmask_b32_e64 v14, 1.0, 0, s[0:1]
	v_pk_mul_f32 v[2:3], v[2:3], v[14:15]
	s_lshl_b64 s[0:1], s[18:19], 16
	v_pk_mul_f32 v[10:11], v[2:3], v[10:11]
	s_nop 0
	v_pk_fma_f32 v[2:3], v[6:7], v[0:1], v[10:11]
	s_nop 0
	v_add_f32_e32 v2, v2, v20
	v_add_f32_e32 v14, v3, v2
	v_mov_b32_e32 v15, v14
	s_nop 1
	v_permlane16_swap_b32 v14, v15
	v_pk_mul_f32 v[2:3], v[4:5], v[8:9]
	v_pk_mul_f32 v[4:5], v[6:7], v[0:1]
	v_cvt_pk_bf16_f32 v2, v2, v3
	v_cvt_pk_bf16_f32 v3, v4, v5
	s_waitcnt lgkmcnt(0)
	v_add_f32_e32 v0, v14, v15
	v_mov_b32_e32 v1, v0
	s_nop 1
	v_permlane32_swap_b32 v0, v1
	v_cvt_pk_bf16_f32 v4, v12, v13
	v_cvt_pk_bf16_f32 v5, v10, v11
	global_store_dwordx4 v[16:17], v[2:5], off offset:256
	s_and_saveexec_b64 s[26:27], vcc
	s_cbranch_execz .LBB0_655
	s_waitcnt lgkmcnt(0)
	v_add_f32_e32 v0, v0, v1
	ds_write_b32 v114, v0 offset:704

.LBB0_663:
	s_mov_b64 s[98:99], 0xc0000
	s_lshl_b32 s2, s33, 8
	s_mul_i32 s1, s20, 0x1800
	s_mul_hi_i32 s0, s20, 0x1800
	s_add_u32 s24, s58, s1
	v_mov_b32_e32 v92, v182
	s_addc_u32 s25, s59, s0
	s_lshl_b32 s19, s2, 1
	s_add_u32 s0, s24, s19
	v_and_b32_e32 v155, 63, v92
	s_addc_u32 s1, s25, 0
	v_ashrrev_i32_e32 v92, 1, v155
	s_add_u32 s0, s0, 0x8800800
	v_and_b32_e32 v92, -8, v92
	s_addc_u32 s1, s1, 0
	v_add_u32_e32 v92, s80, v92
	v_and_or_b32 v162, v155, 15, s79
	v_ashrrev_i32_e32 v93, 31, v92
	v_mov_b64_e32 v[94:95], s[0:1]
	v_mad_i64_i32 v[96:97], s[22:23], v162, s77, v[94:95]
	v_lshlrev_b64 v[158:159], 1, v[92:93]
	v_lshl_add_u64 v[92:93], v[96:97], 0, v[158:159]
	v_lshl_add_u64 v[232:233], v[92:93], 0, s[98:99]
	global_load_dwordx4 v[164:167], v[92:93], off nt
	v_lshl_add_u32 v96, v162, 2, 0
	v_add_u32_e32 v152, 0x21400, v96
	v_add_u32_e32 v174, 0x20400, v96
	v_add_u32_e32 v175, 0x21000, v96
	v_add_u32_e32 v176, 0x20c00, v96
	ds_read2st64_b32 v[96:97], v152 offset1:4
	ds_read2st64_b32 v[98:99], v152 offset0:8 offset1:12
	ds_read_b32 v116, v174
	ds_read_b32 v117, v175
	ds_read_b32 v118, v176
	global_load_dwordx4 v[168:171], v[92:93], off offset:256 nt
	v_or_b32_e32 v154, 16, v162
	v_mad_i64_i32 v[112:113], s[22:23], v154, s77, v[94:95]
	v_lshl_add_u64 v[92:93], v[112:113], 0, v[158:159]
	v_lshl_add_u64 v[234:235], v[92:93], 0, s[98:99]
	global_load_dwordx4 v[136:139], v[92:93], off nt
	global_load_dwordx4 v[132:135], v[92:93], off offset:256 nt
	s_waitcnt lgkmcnt(0)
	v_add_f32_e32 v92, v96, v97
	v_add_f32_e32 v92, v92, v98
	v_or_b32_e32 v160, 32, v162
	v_or_b32_e32 v163, 48, v162
	v_add_f32_e32 v92, v92, v99
	v_mad_i64_i32 v[114:115], s[22:23], v160, s77, v[94:95]
	v_mad_i64_i32 v[94:95], s[22:23], v163, s77, v[94:95]
	v_max_f32_e32 v93, v118, v118
	v_fmac_f32_e32 v92, v116, v117
	v_lshl_add_u64 v[112:113], v[114:115], 0, v[158:159]
	v_lshl_add_u64 v[94:95], v[94:95], 0, v[158:159]
	v_max_f32_e64 v92, |v92|, v93
	v_rcp_f32_e32 v156, v92
	v_lshl_add_u64 v[236:237], v[112:113], 0, s[98:99]
	global_load_dwordx4 v[116:119], v[112:113], off nt
	s_nop 0
	global_load_dwordx4 v[112:115], v[112:113], off offset:256 nt
	s_nop 0
	v_lshl_add_u64 v[238:239], v[94:95], 0, s[98:99]
	global_load_dwordx4 v[96:99], v[94:95], off nt
	s_nop 0
	global_load_dwordx4 v[92:95], v[94:95], off offset:256 nt
	global_load_dwordx4 v[200:203], v[232:233], off nt
	global_load_dwordx4 v[204:207], v[232:233], off offset:256 nt
	global_load_dwordx4 v[208:211], v[234:235], off nt
	global_load_dwordx4 v[212:215], v[234:235], off offset:256 nt
	global_load_dwordx4 v[216:219], v[236:237], off nt
	global_load_dwordx4 v[220:223], v[236:237], off offset:256 nt
	global_load_dwordx4 v[224:227], v[238:239], off nt
	global_load_dwordx4 v[228:231], v[238:239], off offset:256 nt
	s_lshl_b32 s3, s42, 8
	v_cmp_gt_u32_e32 vcc, 16, v155
	v_pk_mul_f32 v[150:151], v[150:151], v[156:157] op_sel_hi:[1,0]
	v_pk_mul_f32 v[148:149], v[148:149], v[156:157] op_sel_hi:[1,0]
	v_pk_mul_f32 v[178:179], v[30:31], v[156:157] op_sel_hi:[1,0]
	v_pk_mul_f32 v[180:181], v[28:29], v[156:157] op_sel_hi:[1,0]
	s_waitcnt vmcnt(8)
	v_lshlrev_b32_e32 v157, 16, v166
	v_lshlrev_b32_e32 v28, 16, v164
	v_and_b32_e32 v29, 0xffff0000, v164
	v_mul_f32_e32 v157, 0xbfb8aa3b, v157
	v_lshlrev_b32_e32 v30, 16, v165
	v_and_b32_e32 v31, 0xffff0000, v165
	v_and_b32_e32 v161, 0xffff0000, v166
	v_mul_f32_e32 v28, 0xbfb8aa3b, v28
	v_mul_f32_e32 v29, 0xbfb8aa3b, v29
	v_exp_f32_e32 v157, v157
	v_mul_f32_e32 v30, 0xbfb8aa3b, v30
	v_mul_f32_e32 v31, 0xbfb8aa3b, v31
	v_mul_f32_e32 v161, 0xbfb8aa3b, v161
	v_exp_f32_e32 v28, v28
	v_exp_f32_e32 v29, v29
	v_exp_f32_e32 v30, v30
	v_exp_f32_e32 v31, v31
	v_exp_f32_e32 v161, v161
	v_lshlrev_b32_e32 v164, 16, v167
	v_and_b32_e32 v165, 0xffff0000, v167
	v_mul_f32_e32 v164, 0xbfb8aa3b, v164
	v_add_f32_e32 v157, 1.0, v157
	v_exp_f32_e32 v166, v164
	v_add_f32_e32 v28, 1.0, v28
	v_add_f32_e32 v29, 1.0, v29
	v_rcp_f32_e32 v164, v157
	v_mul_f32_e32 v157, 0xbfb8aa3b, v165
	v_add_f32_e32 v30, 1.0, v30
	v_add_f32_e32 v31, 1.0, v31
	v_add_f32_e32 v161, 1.0, v161
	v_rcp_f32_e32 v28, v28
	v_rcp_f32_e32 v29, v29
	v_exp_f32_e32 v157, v157
	v_rcp_f32_e32 v30, v30
	v_rcp_f32_e32 v31, v31
	v_rcp_f32_e32 v165, v161
	v_add_f32_e32 v161, 1.0, v166
	v_add_f32_e32 v157, 1.0, v157
	v_pk_mul_f32 v[28:29], v[28:29], v[148:149]
	v_rcp_f32_e32 v186, v161
	v_rcp_f32_e32 v187, v157
	v_pk_mul_f32 v[30:31], v[30:31], v[150:151]
	v_pk_mul_f32 v[166:167], v[164:165], v[180:181]
	v_add_f32_e32 v148, v28, v29
	v_lshlrev_b32_e32 v164, 16, v170
	v_add_f32_e32 v148, v30, v148
	v_mul_f32_e32 v164, 0xbfb8aa3b, v164
	v_and_b32_e32 v165, 0xffff0000, v170
	v_add_f32_e32 v148, v31, v148
	v_exp_f32_e32 v164, v164
	v_mul_f32_e32 v165, 0xbfb8aa3b, v165
	v_add_f32_e32 v148, v166, v148
	v_exp_f32_e32 v165, v165
	v_pk_mul_f32 v[150:151], v[186:187], v[178:179]
	v_add_f32_e32 v148, v167, v148
	v_add_f32_e32 v148, v150, v148
	v_add_f32_e32 v148, v151, v148
	v_add_f32_e32 v164, 1.0, v164
	v_add_f32_e32 v161, 0, v148
	v_lshlrev_b32_e32 v148, 16, v168
	v_and_b32_e32 v149, 0xffff0000, v168
	v_rcp_f32_e32 v168, v164
	v_add_f32_e32 v164, 1.0, v165
	v_lshlrev_b32_e32 v165, 16, v171
	v_pk_mul_f32 v[146:147], v[146:147], v[156:157] op_sel_hi:[1,0]
	v_pk_mul_f32 v[144:145], v[144:145], v[156:157] op_sel_hi:[1,0]
	v_pk_mul_f32 v[142:143], v[142:143], v[156:157] op_sel_hi:[1,0]
	v_mul_f32_e32 v148, 0xbfb8aa3b, v148
	v_mul_f32_e32 v149, 0xbfb8aa3b, v149
	v_pk_mul_f32 v[140:141], v[140:141], v[156:157] op_sel_hi:[1,0]
	v_lshlrev_b32_e32 v156, 16, v169
	v_and_b32_e32 v157, 0xffff0000, v169
	v_mul_f32_e32 v165, 0xbfb8aa3b, v165
	v_and_b32_e32 v169, 0xffff0000, v171
	v_exp_f32_e32 v148, v148
	v_exp_f32_e32 v149, v149
	v_mul_f32_e32 v156, 0xbfb8aa3b, v156
	v_mul_f32_e32 v157, 0xbfb8aa3b, v157
	v_exp_f32_e32 v165, v165
	v_mul_f32_e32 v169, 0xbfb8aa3b, v169
	v_exp_f32_e32 v156, v156
	v_exp_f32_e32 v157, v157
	v_exp_f32_e32 v170, v169
	v_add_f32_e32 v148, 1.0, v148
	v_add_f32_e32 v149, 1.0, v149
	v_rcp_f32_e32 v169, v164
	v_add_f32_e32 v164, 1.0, v165
	v_rcp_f32_e32 v148, v148
	v_rcp_f32_e32 v149, v149
	v_add_f32_e32 v156, 1.0, v156
	v_add_f32_e32 v157, 1.0, v157
	v_rcp_f32_e32 v190, v164
	v_add_f32_e32 v164, 1.0, v170
	v_rcp_f32_e32 v156, v156
	v_rcp_f32_e32 v157, v157
	v_rcp_f32_e32 v191, v164
	v_pk_mul_f32 v[170:171], v[148:149], v[144:145]
	v_pk_mul_f32 v[148:149], v[168:169], v[140:141]
	v_pk_mul_f32 v[164:165], v[156:157], v[146:147]
	v_pk_mul_f32 v[140:141], v[190:191], v[142:143]
	v_add_f32_e32 v142, v170, v171
	v_add_f32_e32 v142, v164, v142
	v_add_f32_e32 v142, v165, v142
	v_add_f32_e32 v142, v148, v142
	v_add_f32_e32 v142, v149, v142
	v_add_f32_e32 v142, v140, v142
	v_add_f32_e32 v142, v141, v142
	v_pk_mul_f32 v[178:179], v[28:29], v[28:29]
	v_add_f32_e32 v161, v142, v161
	v_pk_mul_f32 v[142:143], v[170:171], v[170:171]
	v_pk_mul_f32 v[180:181], v[30:31], v[30:31]
	v_pk_mul_f32 v[144:145], v[164:165], v[164:165]
	v_add_f32_e32 v142, v142, v143
	v_add_f32_e32 v143, v178, v179
	v_add_f32_e32 v142, v144, v142
	v_add_f32_e32 v143, v180, v143
	v_pk_mul_f32 v[186:187], v[166:167], v[166:167]
	v_pk_mul_f32 v[146:147], v[148:149], v[148:149]
	v_add_f32_e32 v142, v145, v142
	v_add_f32_e32 v143, v181, v143
	v_add_f32_e32 v142, v146, v142
	v_add_f32_e32 v143, v186, v143
	v_pk_mul_f32 v[188:189], v[150:151], v[150:151]
	v_pk_mul_f32 v[156:157], v[140:141], v[140:141]
	v_add_f32_e32 v142, v147, v142
	v_add_f32_e32 v143, v187, v143
	v_add_f32_e32 v142, v156, v142
	v_add_f32_e32 v143, v188, v143
	v_add_f32_e32 v142, v157, v142
	v_add_f32_e32 v143, v189, v143
	v_add_f32_e32 v145, v143, v142
	v_mov_b32_e32 v144, v161
	s_nop 1
	v_permlane16_swap_b32 v161, v144
	v_mov_b32_e32 v146, v145
	s_nop 1
	v_permlane16_swap_b32 v145, v146
	s_waitcnt lgkmcnt(0)
	v_add_f32_e32 v142, v161, v144
	v_add_f32_e32 v144, v145, v146
	v_mov_b32_e32 v143, v142
	s_nop 1
	v_permlane32_swap_b32 v142, v143
	v_mov_b32_e32 v145, v144
	s_nop 1
	v_permlane32_swap_b32 v144, v145
	v_add_u32_e32 v146, s3, v162
	v_lshl_add_u32 v177, v146, 2, 0
	s_and_saveexec_b64 s[22:23], vcc
	s_cbranch_execz .LBB0_665
	s_waitcnt lgkmcnt(1)
	v_add_f32_e32 v142, v142, v143
	s_waitcnt lgkmcnt(0)
	v_add_f32_e32 v143, v144, v145
	ds_write2st64_b32 v177, v142, v143 offset1:16
.LBB0_665:
	s_or_b64 exec, exec, s[22:23]
	v_lshl_add_u32 v146, v154, 2, 0
	v_add_u32_e32 v144, 0x21400, v146
	s_waitcnt lgkmcnt(1)
	ds_read2st64_b32 v[142:143], v144 offset1:4
	s_waitcnt lgkmcnt(1)
	ds_read2st64_b32 v[144:145], v144 offset0:8 offset1:12
	v_add_u32_e32 v147, 0x20400, v146
	v_add_u32_e32 v154, 0x21000, v146
	v_add_u32_e32 v146, 0x20c00, v146
	ds_read_b32 v147, v147
	ds_read_b32 v154, v154
	ds_read_b32 v146, v146
	s_waitcnt lgkmcnt(4)
	v_add_f32_e32 v142, v142, v143
	s_waitcnt lgkmcnt(3)
	v_add_f32_e32 v142, v142, v144
	v_add_f32_e32 v142, v142, v145
	s_waitcnt lgkmcnt(1)
	v_fmac_f32_e32 v142, v147, v154
	s_waitcnt lgkmcnt(0)
	v_max_f32_e32 v143, v146, v146
	v_max_f32_e64 v142, |v142|, v143
	v_rcp_f32_e32 v142, v142
	s_nop 0
	v_pk_mul_f32 v[144:145], v[22:23], v[142:143] op_sel_hi:[1,0]
	v_lshlrev_b32_e32 v22, 16, v136
	v_and_b32_e32 v23, 0xffff0000, v136
	v_mul_f32_e32 v22, 0xbfb8aa3b, v22
	v_mul_f32_e32 v23, 0xbfb8aa3b, v23
	v_exp_f32_e32 v22, v22
	v_exp_f32_e32 v23, v23
	v_pk_mul_f32 v[146:147], v[20:21], v[142:143] op_sel_hi:[1,0]
	v_pk_mul_f32 v[130:131], v[130:131], v[142:143] op_sel_hi:[1,0]
	v_add_f32_e32 v20, 1.0, v22
	v_add_f32_e32 v21, 1.0, v23
	v_lshlrev_b32_e32 v22, 16, v137
	v_and_b32_e32 v23, 0xffff0000, v137
	v_mul_f32_e32 v22, 0xbfb8aa3b, v22
	v_mul_f32_e32 v23, 0xbfb8aa3b, v23
	v_exp_f32_e32 v22, v22
	v_exp_f32_e32 v23, v23
	v_pk_mul_f32 v[128:129], v[128:129], v[142:143] op_sel_hi:[1,0]
	v_pk_mul_f32 v[126:127], v[126:127], v[142:143] op_sel_hi:[1,0]
	v_add_f32_e32 v22, 1.0, v22
	v_add_f32_e32 v23, 1.0, v23
	v_pk_mul_f32 v[124:125], v[124:125], v[142:143] op_sel_hi:[1,0]
	v_pk_mul_f32 v[122:123], v[122:123], v[142:143] op_sel_hi:[1,0]
	v_pk_mul_f32 v[120:121], v[120:121], v[142:143] op_sel_hi:[1,0]
	v_lshlrev_b32_e32 v142, 16, v134
	v_and_b32_e32 v134, 0xffff0000, v134
	v_rcp_f32_e32 v22, v22
	v_rcp_f32_e32 v23, v23
	v_mul_f32_e32 v142, 0xbfb8aa3b, v142
	v_mul_f32_e32 v134, 0xbfb8aa3b, v134
	v_exp_f32_e32 v142, v142
	v_exp_f32_e32 v143, v134
	v_pk_mul_f32 v[22:23], v[22:23], v[130:131]
	v_lshlrev_b32_e32 v130, 16, v132
	v_and_b32_e32 v131, 0xffff0000, v132
	v_mul_f32_e32 v130, 0xbfb8aa3b, v130
	v_mul_f32_e32 v131, 0xbfb8aa3b, v131
	v_lshlrev_b32_e32 v132, 16, v133
	v_and_b32_e32 v133, 0xffff0000, v133
	v_add_f32_e32 v134, 1.0, v142
	v_add_f32_e32 v142, 1.0, v143
	v_lshlrev_b32_e32 v143, 16, v135
	v_and_b32_e32 v135, 0xffff0000, v135
	v_lshlrev_b32_e32 v136, 16, v138
	v_and_b32_e32 v137, 0xffff0000, v138
	v_exp_f32_e32 v130, v130
	v_exp_f32_e32 v131, v131
	v_mul_f32_e32 v132, 0xbfb8aa3b, v132
	v_mul_f32_e32 v133, 0xbfb8aa3b, v133
	v_mul_f32_e32 v143, 0xbfb8aa3b, v143
	v_mul_f32_e32 v135, 0xbfb8aa3b, v135
	v_mul_f32_e32 v136, 0xbfb8aa3b, v136
	v_mul_f32_e32 v137, 0xbfb8aa3b, v137
	v_exp_f32_e32 v132, v132
	v_exp_f32_e32 v133, v133
	v_exp_f32_e32 v143, v143
	v_exp_f32_e32 v156, v135
	v_exp_f32_e32 v136, v136
	v_exp_f32_e32 v137, v137
	v_lshlrev_b32_e32 v138, 16, v139
	v_and_b32_e32 v139, 0xffff0000, v139
	v_mul_f32_e32 v138, 0xbfb8aa3b, v138
	v_mul_f32_e32 v139, 0xbfb8aa3b, v139
	v_rcp_f32_e32 v20, v20
	v_rcp_f32_e32 v21, v21
	v_exp_f32_e32 v138, v138
	v_exp_f32_e32 v139, v139
	v_add_f32_e32 v130, 1.0, v130
	v_add_f32_e32 v131, 1.0, v131
	v_rcp_f32_e32 v130, v130
	v_rcp_f32_e32 v131, v131
	v_add_f32_e32 v132, 1.0, v132
	v_add_f32_e32 v133, 1.0, v133
	v_rcp_f32_e32 v135, v142
	v_add_f32_e32 v142, 1.0, v143
	v_add_f32_e32 v143, 1.0, v156
	v_add_f32_e32 v136, 1.0, v136
	v_add_f32_e32 v137, 1.0, v137
	v_rcp_f32_e32 v132, v132
	v_rcp_f32_e32 v133, v133
	v_rcp_f32_e32 v134, v134
	v_rcp_f32_e32 v142, v142
	v_rcp_f32_e32 v143, v143
	v_rcp_f32_e32 v136, v136
	v_rcp_f32_e32 v137, v137
	v_add_f32_e32 v138, 1.0, v138
	v_add_f32_e32 v139, 1.0, v139
	v_pk_mul_f32 v[20:21], v[20:21], v[128:129]
	v_rcp_f32_e32 v138, v138
	v_rcp_f32_e32 v139, v139
	v_add_f32_e32 v128, v20, v21
	v_pk_mul_f32 v[168:169], v[130:131], v[124:125]
	v_add_f32_e32 v128, v22, v128
	v_pk_mul_f32 v[156:157], v[132:133], v[126:127]
	v_pk_mul_f32 v[130:131], v[134:135], v[120:121]
	v_pk_mul_f32 v[120:121], v[142:143], v[122:123]
	v_add_f32_e32 v122, v168, v169
	v_pk_mul_f32 v[154:155], v[136:137], v[146:147]
	v_add_f32_e32 v128, v23, v128
	v_add_f32_e32 v122, v156, v122
	v_add_f32_e32 v128, v154, v128
	v_add_f32_e32 v122, v157, v122
	v_pk_mul_f32 v[136:137], v[138:139], v[144:145]
	v_add_f32_e32 v128, v155, v128
	v_add_f32_e32 v122, v130, v122
	v_add_f32_e32 v128, v136, v128
	v_add_f32_e32 v122, v131, v122
	v_add_f32_e32 v128, v137, v128
	v_add_f32_e32 v122, v120, v122
	v_add_f32_e32 v161, 0, v128
	v_add_f32_e32 v122, v121, v122
	v_pk_mul_f32 v[128:129], v[20:21], v[20:21]
	v_add_f32_e32 v134, v122, v161
	v_pk_mul_f32 v[122:123], v[168:169], v[168:169]
	v_pk_mul_f32 v[138:139], v[22:23], v[22:23]
	v_pk_mul_f32 v[124:125], v[156:157], v[156:157]
	v_add_f32_e32 v122, v122, v123
	v_add_f32_e32 v123, v128, v129
	v_add_f32_e32 v122, v124, v122
	v_add_f32_e32 v123, v138, v123
	v_pk_mul_f32 v[144:145], v[154:155], v[154:155]
	v_pk_mul_f32 v[126:127], v[130:131], v[130:131]
	v_add_f32_e32 v122, v125, v122
	v_add_f32_e32 v123, v139, v123
	v_add_f32_e32 v122, v126, v122
	v_add_f32_e32 v123, v144, v123
	v_pk_mul_f32 v[146:147], v[136:137], v[136:137]
	v_pk_mul_f32 v[132:133], v[120:121], v[120:121]
	v_add_f32_e32 v122, v127, v122
	v_add_f32_e32 v123, v145, v123
	v_add_f32_e32 v122, v132, v122
	v_add_f32_e32 v123, v146, v123
	v_add_f32_e32 v122, v133, v122
	v_add_f32_e32 v123, v147, v123
	v_add_f32_e32 v125, v123, v122
	v_mov_b32_e32 v124, v134
	s_nop 1
	v_permlane16_swap_b32 v134, v124
	v_mov_b32_e32 v126, v125
	s_nop 1
	v_permlane16_swap_b32 v125, v126
	s_waitcnt lgkmcnt(1)
	v_add_f32_e32 v122, v134, v124
	s_waitcnt lgkmcnt(0)
	v_add_f32_e32 v124, v125, v126
	v_mov_b32_e32 v123, v122
	s_nop 1
	v_permlane32_swap_b32 v122, v123
	v_mov_b32_e32 v125, v124
	s_nop 1
	v_permlane32_swap_b32 v124, v125
	s_and_saveexec_b64 s[22:23], vcc
	s_cbranch_execz .LBB0_667
	s_waitcnt lgkmcnt(1)
	v_add_f32_e32 v122, v122, v123
	s_waitcnt lgkmcnt(0)
	v_add_f32_e32 v123, v124, v125
	v_add_u32_e32 v124, 64, v177
	ds_write2st64_b32 v124, v122, v123 offset1:16
.LBB0_667:
	s_or_b64 exec, exec, s[22:23]
	v_lshl_add_u32 v126, v160, 2, 0
	v_add_u32_e32 v124, 0x21400, v126
	s_waitcnt lgkmcnt(1)
	ds_read2st64_b32 v[122:123], v124 offset1:4
	s_waitcnt lgkmcnt(1)
	ds_read2st64_b32 v[124:125], v124 offset0:8 offset1:12
	v_add_u32_e32 v127, 0x20400, v126
	v_add_u32_e32 v128, 0x21000, v126
	v_add_u32_e32 v126, 0x20c00, v126
	ds_read_b32 v127, v127
	ds_read_b32 v128, v128
	ds_read_b32 v126, v126
	s_waitcnt lgkmcnt(4)
	v_add_f32_e32 v122, v122, v123
	s_waitcnt lgkmcnt(3)
	v_add_f32_e32 v122, v122, v124
	v_add_f32_e32 v122, v122, v125
	s_waitcnt lgkmcnt(1)
	v_fmac_f32_e32 v122, v127, v128
	s_waitcnt lgkmcnt(0)
	v_max_f32_e32 v123, v126, v126
	v_max_f32_e64 v122, |v122|, v123
	v_rcp_f32_e32 v122, v122
	s_nop 0
	v_pk_mul_f32 v[124:125], v[18:19], v[122:123] op_sel_hi:[1,0]
	v_lshlrev_b32_e32 v18, 16, v116
	v_and_b32_e32 v19, 0xffff0000, v116
	v_mul_f32_e32 v18, 0xbfb8aa3b, v18
	v_mul_f32_e32 v19, 0xbfb8aa3b, v19
	v_exp_f32_e32 v18, v18
	v_exp_f32_e32 v19, v19
	v_pk_mul_f32 v[126:127], v[16:17], v[122:123] op_sel_hi:[1,0]
	v_lshlrev_b32_e32 v116, 16, v118
	v_add_f32_e32 v16, 1.0, v18
	v_add_f32_e32 v17, 1.0, v19
	v_lshlrev_b32_e32 v18, 16, v117
	v_and_b32_e32 v19, 0xffff0000, v117
	v_and_b32_e32 v117, 0xffff0000, v118
	v_mul_f32_e32 v116, 0xbfb8aa3b, v116
	v_mul_f32_e32 v117, 0xbfb8aa3b, v117
	v_exp_f32_e32 v116, v116
	v_exp_f32_e32 v117, v117
	v_pk_mul_f32 v[110:111], v[110:111], v[122:123] op_sel_hi:[1,0]
	v_pk_mul_f32 v[108:109], v[108:109], v[122:123] op_sel_hi:[1,0]
	v_add_f32_e32 v116, 1.0, v116
	v_add_f32_e32 v117, 1.0, v117
	v_rcp_f32_e32 v116, v116
	v_rcp_f32_e32 v117, v117
	v_pk_mul_f32 v[106:107], v[106:107], v[122:123] op_sel_hi:[1,0]
	v_pk_mul_f32 v[104:105], v[104:105], v[122:123] op_sel_hi:[1,0]
	v_pk_mul_f32 v[102:103], v[102:103], v[122:123] op_sel_hi:[1,0]
	v_lshlrev_b32_e32 v123, 16, v112
	v_mul_f32_e32 v123, 0xbfb8aa3b, v123
	v_exp_f32_e32 v123, v123
	v_and_b32_e32 v112, 0xffff0000, v112
	v_mul_f32_e32 v112, 0xbfb8aa3b, v112
	v_pk_mul_f32 v[134:135], v[116:117], v[126:127]
	v_exp_f32_e32 v126, v112
	v_pk_mul_f32 v[100:101], v[100:101], v[122:123] op_sel_hi:[1,0]
	v_add_f32_e32 v112, 1.0, v123
	v_lshlrev_b32_e32 v123, 16, v113
	v_and_b32_e32 v113, 0xffff0000, v113
	v_mul_f32_e32 v123, 0xbfb8aa3b, v123
	v_mul_f32_e32 v113, 0xbfb8aa3b, v113
	v_add_f32_e32 v122, 1.0, v126
	v_exp_f32_e32 v123, v123
	v_exp_f32_e32 v126, v113
	v_rcp_f32_e32 v113, v122
	v_mul_f32_e32 v18, 0xbfb8aa3b, v18
	v_add_f32_e32 v122, 1.0, v123
	v_add_f32_e32 v123, 1.0, v126
	v_lshlrev_b32_e32 v126, 16, v114
	v_and_b32_e32 v114, 0xffff0000, v114
	v_mul_f32_e32 v126, 0xbfb8aa3b, v126
	v_mul_f32_e32 v114, 0xbfb8aa3b, v114
	v_mul_f32_e32 v19, 0xbfb8aa3b, v19
	v_exp_f32_e32 v126, v126
	v_exp_f32_e32 v127, v114
	v_exp_f32_e32 v18, v18
	v_exp_f32_e32 v19, v19
	v_lshlrev_b32_e32 v118, 16, v119
	v_and_b32_e32 v119, 0xffff0000, v119
	v_mul_f32_e32 v118, 0xbfb8aa3b, v118
	v_mul_f32_e32 v119, 0xbfb8aa3b, v119
	v_add_f32_e32 v114, 1.0, v126
	v_add_f32_e32 v126, 1.0, v127
	v_lshlrev_b32_e32 v127, 16, v115
	v_and_b32_e32 v115, 0xffff0000, v115
	v_rcp_f32_e32 v16, v16
	v_rcp_f32_e32 v17, v17
	v_add_f32_e32 v18, 1.0, v18
	v_add_f32_e32 v19, 1.0, v19
	v_exp_f32_e32 v118, v118
	v_exp_f32_e32 v119, v119
	v_mul_f32_e32 v127, 0xbfb8aa3b, v127
	v_mul_f32_e32 v115, 0xbfb8aa3b, v115
	v_rcp_f32_e32 v18, v18
	v_rcp_f32_e32 v19, v19
	v_rcp_f32_e32 v112, v112
	v_exp_f32_e32 v127, v127
	v_exp_f32_e32 v129, v115
	v_rcp_f32_e32 v122, v122
	v_rcp_f32_e32 v123, v123
	v_rcp_f32_e32 v114, v114
	v_rcp_f32_e32 v115, v126
	v_add_f32_e32 v118, 1.0, v118
	v_add_f32_e32 v119, 1.0, v119
	v_pk_mul_f32 v[16:17], v[16:17], v[108:109]
	v_rcp_f32_e32 v118, v118
	v_rcp_f32_e32 v119, v119
	v_pk_mul_f32 v[18:19], v[18:19], v[110:111]
	v_add_f32_e32 v108, v16, v17
	v_add_f32_e32 v126, 1.0, v127
	v_add_f32_e32 v127, 1.0, v129
	v_pk_mul_f32 v[160:161], v[112:113], v[104:105]
	v_add_f32_e32 v108, v18, v108
	v_rcp_f32_e32 v126, v126
	v_rcp_f32_e32 v127, v127
	v_pk_mul_f32 v[138:139], v[122:123], v[106:107]
	v_pk_mul_f32 v[114:115], v[114:115], v[100:101]
	v_add_f32_e32 v100, v160, v161
	v_add_f32_e32 v108, v19, v108
	v_add_f32_e32 v100, v138, v100
	v_add_f32_e32 v108, v134, v108
	v_add_f32_e32 v100, v139, v100
	v_pk_mul_f32 v[116:117], v[118:119], v[124:125]
	v_add_f32_e32 v108, v135, v108
	v_add_f32_e32 v100, v114, v100
	v_add_f32_e32 v108, v116, v108
	v_pk_mul_f32 v[106:107], v[126:127], v[102:103]
	v_add_f32_e32 v100, v115, v100
	v_add_f32_e32 v108, v117, v108
	v_add_f32_e32 v100, v106, v100
	v_add_f32_e32 v128, 0, v108
	v_add_f32_e32 v100, v107, v100
	v_pk_mul_f32 v[108:109], v[16:17], v[16:17]
	v_add_f32_e32 v122, v100, v128
	v_pk_mul_f32 v[100:101], v[160:161], v[160:161]
	v_pk_mul_f32 v[110:111], v[18:19], v[18:19]
	v_pk_mul_f32 v[102:103], v[138:139], v[138:139]
	v_add_f32_e32 v100, v100, v101
	v_add_f32_e32 v101, v108, v109
	v_add_f32_e32 v100, v102, v100
	v_add_f32_e32 v101, v110, v101
	v_pk_mul_f32 v[118:119], v[134:135], v[134:135]
	v_pk_mul_f32 v[104:105], v[114:115], v[114:115]
	v_add_f32_e32 v100, v103, v100
	v_add_f32_e32 v101, v111, v101
	v_add_f32_e32 v100, v104, v100
	v_add_f32_e32 v101, v118, v101
	v_pk_mul_f32 v[124:125], v[116:117], v[116:117]
	v_pk_mul_f32 v[112:113], v[106:107], v[106:107]
	v_add_f32_e32 v100, v105, v100
	v_add_f32_e32 v101, v119, v101
	v_add_f32_e32 v100, v112, v100
	v_add_f32_e32 v101, v124, v101
	v_add_f32_e32 v100, v113, v100
	v_add_f32_e32 v101, v125, v101
	v_add_f32_e32 v103, v101, v100
	v_mov_b32_e32 v102, v122
	s_nop 1
	v_permlane16_swap_b32 v122, v102
	v_mov_b32_e32 v104, v103
	s_nop 1
	v_permlane16_swap_b32 v103, v104
	s_waitcnt lgkmcnt(1)
	v_add_f32_e32 v100, v122, v102
	s_waitcnt lgkmcnt(0)
	v_add_f32_e32 v102, v103, v104
	v_mov_b32_e32 v101, v100
	s_nop 1
	v_permlane32_swap_b32 v100, v101
	v_mov_b32_e32 v103, v102
	s_nop 1
	v_permlane32_swap_b32 v102, v103
	s_and_saveexec_b64 s[22:23], vcc
	s_cbranch_execz .LBB0_669
	s_waitcnt lgkmcnt(1)
	v_add_f32_e32 v100, v100, v101
	s_waitcnt lgkmcnt(0)
	v_add_f32_e32 v101, v102, v103
	v_add_u32_e32 v102, 0x80, v177
	ds_write2st64_b32 v102, v100, v101 offset1:16
.LBB0_669:
	s_or_b64 exec, exec, s[22:23]
	v_lshl_add_u32 v104, v163, 2, 0
	v_add_u32_e32 v102, 0x21400, v104
	s_waitcnt lgkmcnt(1)
	ds_read2st64_b32 v[100:101], v102 offset1:4
	s_waitcnt lgkmcnt(1)
	ds_read2st64_b32 v[102:103], v102 offset0:8 offset1:12
	v_add_u32_e32 v105, 0x20400, v104
	v_add_u32_e32 v108, 0x21000, v104
	v_add_u32_e32 v104, 0x20c00, v104
	ds_read_b32 v105, v105
	ds_read_b32 v108, v108
	ds_read_b32 v104, v104
	s_waitcnt lgkmcnt(4)
	v_add_f32_e32 v100, v100, v101
	s_waitcnt lgkmcnt(3)
	v_add_f32_e32 v100, v100, v102
	v_add_f32_e32 v100, v100, v103
	s_waitcnt lgkmcnt(1)
	v_fmac_f32_e32 v100, v105, v108
	s_waitcnt lgkmcnt(0)
	v_max_f32_e32 v101, v104, v104
	v_max_f32_e64 v100, |v100|, v101
	v_rcp_f32_e32 v100, v100
	s_nop 0
	v_pk_mul_f32 v[102:103], v[10:11], v[100:101] op_sel_hi:[1,0]
	v_lshlrev_b32_e32 v10, 16, v96
	v_and_b32_e32 v11, 0xffff0000, v96
	v_mul_f32_e32 v10, 0xbfb8aa3b, v10
	v_mul_f32_e32 v11, 0xbfb8aa3b, v11
	v_exp_f32_e32 v10, v10
	v_exp_f32_e32 v11, v11
	v_pk_mul_f32 v[104:105], v[8:9], v[100:101] op_sel_hi:[1,0]
	v_lshlrev_b32_e32 v96, 16, v98
	v_add_f32_e32 v8, 1.0, v10
	v_add_f32_e32 v9, 1.0, v11
	v_lshlrev_b32_e32 v10, 16, v97
	v_and_b32_e32 v11, 0xffff0000, v97
	v_and_b32_e32 v97, 0xffff0000, v98
	v_lshlrev_b32_e32 v98, 16, v99
	v_and_b32_e32 v99, 0xffff0000, v99
	v_mul_f32_e32 v98, 0xbfb8aa3b, v98
	v_mul_f32_e32 v99, 0xbfb8aa3b, v99
	v_exp_f32_e32 v98, v98
	v_exp_f32_e32 v99, v99
	v_pk_mul_f32 v[90:91], v[90:91], v[100:101] op_sel_hi:[1,0]
	v_pk_mul_f32 v[88:89], v[88:89], v[100:101] op_sel_hi:[1,0]
	v_add_f32_e32 v98, 1.0, v98
	v_add_f32_e32 v99, 1.0, v99
	v_rcp_f32_e32 v98, v98
	v_rcp_f32_e32 v99, v99
	v_pk_mul_f32 v[86:87], v[86:87], v[100:101] op_sel_hi:[1,0]
	v_pk_mul_f32 v[84:85], v[84:85], v[100:101] op_sel_hi:[1,0]
	v_pk_mul_f32 v[82:83], v[82:83], v[100:101] op_sel_hi:[1,0]
	v_lshlrev_b32_e32 v101, 16, v92
	v_mul_f32_e32 v101, 0xbfb8aa3b, v101
	v_exp_f32_e32 v101, v101
	v_and_b32_e32 v92, 0xffff0000, v92
	v_mul_f32_e32 v92, 0xbfb8aa3b, v92
	v_pk_mul_f32 v[110:111], v[98:99], v[102:103]
	v_exp_f32_e32 v102, v92
	v_pk_mul_f32 v[80:81], v[80:81], v[100:101] op_sel_hi:[1,0]
	v_add_f32_e32 v92, 1.0, v101
	v_lshlrev_b32_e32 v101, 16, v93
	v_and_b32_e32 v93, 0xffff0000, v93
	v_mul_f32_e32 v101, 0xbfb8aa3b, v101
	v_mul_f32_e32 v93, 0xbfb8aa3b, v93
	v_add_f32_e32 v100, 1.0, v102
	v_exp_f32_e32 v101, v101
	v_exp_f32_e32 v102, v93
	v_mul_f32_e32 v96, 0xbfb8aa3b, v96
	v_mul_f32_e32 v97, 0xbfb8aa3b, v97
	v_exp_f32_e32 v96, v96
	v_exp_f32_e32 v97, v97
	v_rcp_f32_e32 v93, v100
	v_add_f32_e32 v100, 1.0, v101
	v_add_f32_e32 v101, 1.0, v102
	v_lshlrev_b32_e32 v102, 16, v94
	v_and_b32_e32 v94, 0xffff0000, v94
	v_mul_f32_e32 v102, 0xbfb8aa3b, v102
	v_mul_f32_e32 v94, 0xbfb8aa3b, v94
	v_mul_f32_e32 v10, 0xbfb8aa3b, v10
	v_mul_f32_e32 v11, 0xbfb8aa3b, v11
	v_exp_f32_e32 v102, v102
	v_exp_f32_e32 v103, v94
	v_exp_f32_e32 v10, v10
	v_exp_f32_e32 v11, v11
	v_add_f32_e32 v96, 1.0, v96
	v_add_f32_e32 v97, 1.0, v97
	v_rcp_f32_e32 v96, v96
	v_rcp_f32_e32 v97, v97
	v_add_f32_e32 v94, 1.0, v102
	v_add_f32_e32 v102, 1.0, v103
	v_lshlrev_b32_e32 v103, 16, v95
	v_and_b32_e32 v95, 0xffff0000, v95
	v_rcp_f32_e32 v8, v8
	v_rcp_f32_e32 v9, v9
	v_add_f32_e32 v10, 1.0, v10
	v_add_f32_e32 v11, 1.0, v11
	v_mul_f32_e32 v103, 0xbfb8aa3b, v103
	v_mul_f32_e32 v95, 0xbfb8aa3b, v95
	v_rcp_f32_e32 v10, v10
	v_rcp_f32_e32 v11, v11
	v_pk_mul_f32 v[118:119], v[96:97], v[104:105]
	v_rcp_f32_e32 v92, v92
	v_exp_f32_e32 v103, v103
	v_exp_f32_e32 v104, v95
	v_rcp_f32_e32 v100, v100
	v_rcp_f32_e32 v101, v101
	v_rcp_f32_e32 v94, v94
	v_rcp_f32_e32 v95, v102
	v_pk_mul_f32 v[8:9], v[8:9], v[88:89]
	v_pk_mul_f32 v[10:11], v[10:11], v[90:91]
	v_add_f32_e32 v88, v8, v9
	v_add_f32_e32 v102, 1.0, v103
	v_add_f32_e32 v103, 1.0, v104
	v_pk_mul_f32 v[142:143], v[92:93], v[84:85]
	v_add_f32_e32 v88, v10, v88
	v_rcp_f32_e32 v102, v102
	v_rcp_f32_e32 v103, v103
	v_pk_mul_f32 v[122:123], v[100:101], v[86:87]
	v_pk_mul_f32 v[108:109], v[94:95], v[80:81]
	v_add_f32_e32 v80, v142, v143
	v_add_f32_e32 v88, v11, v88
	v_add_f32_e32 v80, v122, v80
	v_add_f32_e32 v88, v118, v88
	v_add_f32_e32 v80, v123, v80
	v_add_f32_e32 v88, v119, v88
	v_add_f32_e32 v80, v108, v80
	v_add_f32_e32 v88, v110, v88
	v_pk_mul_f32 v[104:105], v[102:103], v[82:83]
	v_add_f32_e32 v80, v109, v80
	v_add_f32_e32 v88, v111, v88
	v_add_f32_e32 v80, v104, v80
	v_add_f32_e32 v112, 0, v88
	v_add_f32_e32 v80, v105, v80
	v_pk_mul_f32 v[88:89], v[8:9], v[8:9]
	v_add_f32_e32 v92, v80, v112
	v_pk_mul_f32 v[80:81], v[142:143], v[142:143]
	v_pk_mul_f32 v[90:91], v[10:11], v[10:11]
	v_pk_mul_f32 v[82:83], v[122:123], v[122:123]
	v_add_f32_e32 v80, v80, v81
	v_add_f32_e32 v81, v88, v89
	v_add_f32_e32 v80, v82, v80
	v_add_f32_e32 v81, v90, v81
	v_pk_mul_f32 v[96:97], v[118:119], v[118:119]
	v_pk_mul_f32 v[84:85], v[108:109], v[108:109]
	v_add_f32_e32 v80, v83, v80
	v_add_f32_e32 v81, v91, v81
	v_add_f32_e32 v80, v84, v80
	v_add_f32_e32 v81, v96, v81
	v_pk_mul_f32 v[98:99], v[110:111], v[110:111]
	v_pk_mul_f32 v[86:87], v[104:105], v[104:105]
	v_add_f32_e32 v80, v85, v80
	v_add_f32_e32 v81, v97, v81
	v_add_f32_e32 v80, v86, v80
	v_add_f32_e32 v81, v98, v81
	v_add_f32_e32 v80, v87, v80
	v_add_f32_e32 v81, v99, v81
	v_add_f32_e32 v83, v81, v80
	v_mov_b32_e32 v82, v92
	s_nop 1
	v_permlane16_swap_b32 v92, v82
	v_mov_b32_e32 v84, v83
	s_nop 1
	v_permlane16_swap_b32 v83, v84
	s_waitcnt lgkmcnt(1)
	v_add_f32_e32 v80, v92, v82
	s_waitcnt lgkmcnt(0)
	v_add_f32_e32 v82, v83, v84
	v_mov_b32_e32 v81, v80
	s_nop 1
	v_permlane32_swap_b32 v80, v81
	v_mov_b32_e32 v83, v82
	s_nop 1
	v_permlane32_swap_b32 v82, v83
	s_and_saveexec_b64 s[22:23], vcc
	s_cbranch_execz .LBB0_671
	s_waitcnt lgkmcnt(1)
	v_add_f32_e32 v80, v80, v81
	s_waitcnt lgkmcnt(0)
	v_add_f32_e32 v81, v82, v83
	v_add_u32_e32 v82, 0xc0, v177
	ds_write2st64_b32 v82, v80, v81 offset1:16
.LBB0_671:
	s_or_b64 exec, exec, s[22:23]
	v_add_u32_e32 v82, 0x80, v162
	s_waitcnt lgkmcnt(1)
	v_mov_b64_e32 v[80:81], s[0:1]
	s_waitcnt lgkmcnt(0)
	v_mad_i64_i32 v[82:83], s[0:1], v82, s77, v[80:81]
	v_lshl_add_u64 v[82:83], v[82:83], 0, v[158:159]
	s_waitcnt vmcnt(0)
	v_mov_b64_e32 v[124:125], v[200:201]
	v_mov_b64_e32 v[126:127], v[202:203]
	v_mov_b64_e32 v[144:145], v[204:205]
	v_mov_b64_e32 v[146:147], v[206:207]
	v_add_u32_e32 v82, 0x90, v162
	v_add_u32_e32 v84, 0xa0, v162
	v_add_u32_e32 v86, 0xb0, v162
	v_mad_i64_i32 v[82:83], s[0:1], v82, s77, v[80:81]
	v_mad_i64_i32 v[84:85], s[0:1], v84, s77, v[80:81]
	v_mad_i64_i32 v[80:81], s[0:1], v86, s77, v[80:81]
	ds_read2st64_b32 v[86:87], v152 offset0:2 offset1:6
	ds_read2st64_b32 v[88:89], v152 offset0:10 offset1:14
	ds_read_b32 v90, v174 offset:512
	ds_read_b32 v91, v175 offset:512
	ds_read_b32 v92, v176 offset:512
	v_lshl_add_u64 v[82:83], v[82:83], 0, v[158:159]
	v_mov_b64_e32 v[100:101], v[208:209]
	v_mov_b64_e32 v[102:103], v[210:211]
	v_mov_b64_e32 v[96:97], v[212:213]
	v_mov_b64_e32 v[98:99], v[214:215]
	s_waitcnt lgkmcnt(0)
	v_add_f32_e32 v82, v86, v87
	v_add_f32_e32 v82, v82, v88
	v_add_f32_e32 v82, v82, v89
	v_max_f32_e32 v83, v92, v92
	v_fmac_f32_e32 v82, v90, v91
	v_lshl_add_u64 v[84:85], v[84:85], 0, v[158:159]
	v_lshl_add_u64 v[80:81], v[80:81], 0, v[158:159]
	v_max_f32_e64 v82, |v82|, v83
	v_rcp_f32_e32 v112, v82
	v_mov_b64_e32 v[92:93], v[216:217]
	v_mov_b64_e32 v[94:95], v[218:219]
	v_mov_b64_e32 v[88:89], v[220:221]
	v_mov_b64_e32 v[90:91], v[222:223]
	s_nop 0
	v_mov_b64_e32 v[84:85], v[224:225]
	v_mov_b64_e32 v[86:87], v[226:227]
	s_nop 0
	v_mov_b64_e32 v[80:81], v[228:229]
	v_mov_b64_e32 v[82:83], v[230:231]
	v_pk_mul_f32 v[162:163], v[24:25], v[112:113] op_sel_hi:[1,0]
	v_pk_mul_f32 v[128:129], v[26:27], v[112:113] op_sel_hi:[1,0]
	v_pk_mul_f32 v[78:79], v[78:79], v[112:113] op_sel_hi:[1,0]
	v_pk_mul_f32 v[76:77], v[76:77], v[112:113] op_sel_hi:[1,0]
	v_pk_mul_f32 v[74:75], v[74:75], v[112:113] op_sel_hi:[1,0]
	v_pk_mul_f32 v[72:73], v[72:73], v[112:113] op_sel_hi:[1,0]
	v_pk_mul_f32 v[70:71], v[70:71], v[112:113] op_sel_hi:[1,0]
	v_lshlrev_b32_e32 v24, 16, v124
	v_and_b32_e32 v25, 0xffff0000, v124
	v_lshlrev_b32_e32 v26, 16, v125
	v_and_b32_e32 v27, 0xffff0000, v125
	v_mul_f32_e32 v24, 0xbfb8aa3b, v24
	v_mul_f32_e32 v25, 0xbfb8aa3b, v25
	v_mul_f32_e32 v26, 0xbfb8aa3b, v26
	v_mul_f32_e32 v27, 0xbfb8aa3b, v27
	v_exp_f32_e32 v24, v24
	v_exp_f32_e32 v25, v25
	v_lshlrev_b32_e32 v113, 16, v126
	v_and_b32_e32 v124, 0xffff0000, v126
	v_exp_f32_e32 v26, v26
	v_exp_f32_e32 v27, v27
	v_lshlrev_b32_e32 v125, 16, v127
	v_mul_f32_e32 v113, 0xbfb8aa3b, v113
	v_mul_f32_e32 v124, 0xbfb8aa3b, v124
	v_and_b32_e32 v126, 0xffff0000, v127
	v_mul_f32_e32 v125, 0xbfb8aa3b, v125
	v_exp_f32_e32 v113, v113
	v_exp_f32_e32 v124, v124
	v_mul_f32_e32 v126, 0xbfb8aa3b, v126
	v_exp_f32_e32 v125, v125
	v_add_f32_e32 v24, 1.0, v24
	v_add_f32_e32 v25, 1.0, v25
	v_exp_f32_e32 v126, v126
	v_add_f32_e32 v26, 1.0, v26
	v_add_f32_e32 v27, 1.0, v27
	v_rcp_f32_e32 v24, v24
	v_rcp_f32_e32 v25, v25
	v_lshlrev_b32_e32 v127, 16, v144
	v_rcp_f32_e32 v26, v26
	v_rcp_f32_e32 v27, v27
	v_mul_f32_e32 v178, 0xbfb8aa3b, v127
	v_add_f32_e32 v113, 1.0, v113
	v_add_f32_e32 v127, 1.0, v124
	v_add_f32_e32 v132, 1.0, v125
	v_rcp_f32_e32 v124, v113
	v_rcp_f32_e32 v125, v127
	v_add_f32_e32 v133, 1.0, v126
	v_pk_mul_f32 v[24:25], v[24:25], v[76:77]
	v_rcp_f32_e32 v126, v132
	v_rcp_f32_e32 v127, v133
	v_pk_mul_f32 v[26:27], v[26:27], v[78:79]
	v_add_f32_e32 v113, v24, v25
	v_add_f32_e32 v113, v26, v113
	v_pk_mul_f32 v[158:159], v[124:125], v[72:73]
	v_add_f32_e32 v113, v27, v113
	v_add_f32_e32 v113, v158, v113
	v_pk_mul_f32 v[132:133], v[126:127], v[74:75]
	v_add_f32_e32 v113, v159, v113
	v_add_f32_e32 v113, v132, v113
	v_and_b32_e32 v124, 0xffff0000, v144
	v_add_f32_e32 v113, v133, v113
	v_mul_f32_e32 v124, 0xbfb8aa3b, v124
	v_add_f32_e32 v179, 0, v113
	v_exp_f32_e32 v113, v178
	v_exp_f32_e32 v124, v124
	v_and_b32_e32 v125, 0xffff0000, v145
	v_lshlrev_b32_e32 v126, 16, v146
	v_pk_mul_f32 v[68:69], v[68:69], v[112:113] op_sel_hi:[1,0]
	v_add_f32_e32 v112, 1.0, v113
	v_add_f32_e32 v113, 1.0, v124
	v_lshlrev_b32_e32 v124, 16, v145
	v_and_b32_e32 v127, 0xffff0000, v146
	v_mul_f32_e32 v124, 0xbfb8aa3b, v124
	v_mul_f32_e32 v125, 0xbfb8aa3b, v125
	v_mul_f32_e32 v126, 0xbfb8aa3b, v126
	v_mul_f32_e32 v127, 0xbfb8aa3b, v127
	v_exp_f32_e32 v124, v124
	v_exp_f32_e32 v125, v125
	v_exp_f32_e32 v126, v126
	v_exp_f32_e32 v127, v127
	v_lshlrev_b32_e32 v144, 16, v147
	v_and_b32_e32 v145, 0xffff0000, v147
	v_mul_f32_e32 v144, 0xbfb8aa3b, v144
	v_mul_f32_e32 v145, 0xbfb8aa3b, v145
	v_rcp_f32_e32 v112, v112
	v_rcp_f32_e32 v113, v113
	v_add_f32_e32 v124, 1.0, v124
	v_add_f32_e32 v125, 1.0, v125
	v_add_f32_e32 v126, 1.0, v126
	v_add_f32_e32 v127, 1.0, v127
	v_exp_f32_e32 v144, v144
	v_exp_f32_e32 v145, v145
	v_rcp_f32_e32 v124, v124
	v_rcp_f32_e32 v125, v125
	v_rcp_f32_e32 v126, v126
	v_rcp_f32_e32 v127, v127
	v_add_f32_e32 v144, 1.0, v144
	v_add_f32_e32 v145, 1.0, v145
	v_pk_mul_f32 v[162:163], v[112:113], v[162:163]
	v_rcp_f32_e32 v144, v144
	v_rcp_f32_e32 v145, v145
	v_pk_mul_f32 v[146:147], v[124:125], v[128:129]
	v_pk_mul_f32 v[128:129], v[126:127], v[68:69]
	v_add_f32_e32 v68, v162, v163
	v_add_f32_e32 v68, v146, v68
	v_add_f32_e32 v68, v147, v68
	v_add_f32_e32 v68, v128, v68
	v_pk_mul_f32 v[112:113], v[144:145], v[70:71]
	v_add_f32_e32 v68, v129, v68
	v_add_f32_e32 v68, v112, v68
	v_add_f32_e32 v68, v113, v68
	v_pk_mul_f32 v[72:73], v[24:25], v[24:25]
	v_add_f32_e32 v144, v68, v179
	v_pk_mul_f32 v[68:69], v[162:163], v[162:163]
	v_pk_mul_f32 v[74:75], v[26:27], v[26:27]
	v_pk_mul_f32 v[70:71], v[146:147], v[146:147]
	v_add_f32_e32 v68, v68, v69
	v_add_f32_e32 v69, v72, v73
	v_add_f32_e32 v68, v70, v68
	v_add_f32_e32 v69, v74, v69
	v_pk_mul_f32 v[76:77], v[158:159], v[158:159]
	v_pk_mul_f32 v[124:125], v[128:129], v[128:129]
	v_add_f32_e32 v68, v71, v68
	v_add_f32_e32 v69, v75, v69
	v_add_f32_e32 v68, v124, v68
	v_add_f32_e32 v69, v76, v69
	v_pk_mul_f32 v[78:79], v[132:133], v[132:133]
	v_pk_mul_f32 v[126:127], v[112:113], v[112:113]
	v_add_f32_e32 v68, v125, v68
	v_add_f32_e32 v69, v77, v69
	v_add_f32_e32 v68, v126, v68
	v_add_f32_e32 v69, v78, v69
	v_add_f32_e32 v68, v127, v68
	v_add_f32_e32 v69, v79, v69
	v_add_f32_e32 v71, v69, v68
	v_mov_b32_e32 v70, v144
	s_nop 1
	v_permlane16_swap_b32 v144, v70
	v_mov_b32_e32 v72, v71
	s_nop 1
	v_permlane16_swap_b32 v71, v72
	s_waitcnt lgkmcnt(0)
	v_add_f32_e32 v68, v144, v70
	v_add_f32_e32 v70, v71, v72
	v_mov_b32_e32 v69, v68
	s_nop 1
	v_permlane32_swap_b32 v68, v69
	v_mov_b32_e32 v71, v70
	s_nop 1
	v_permlane32_swap_b32 v70, v71
	s_and_saveexec_b64 s[0:1], vcc
	s_cbranch_execz .LBB0_673
	s_waitcnt lgkmcnt(1)
	v_add_f32_e32 v68, v68, v69
	s_waitcnt lgkmcnt(0)
	v_add_f32_e32 v69, v70, v71
	ds_write2st64_b32 v177, v68, v69 offset0:2 offset1:18
.LBB0_673:
	s_or_b64 exec, exec, s[0:1]
	v_add_u32_e32 v70, 64, v152
	s_waitcnt lgkmcnt(1)
	ds_read2st64_b32 v[68:69], v70 offset0:2 offset1:6
	s_waitcnt lgkmcnt(1)
	ds_read2st64_b32 v[70:71], v70 offset0:10 offset1:14
	ds_read_b32 v72, v174 offset:576
	ds_read_b32 v73, v175 offset:576
	ds_read_b32 v74, v176 offset:576
	s_waitcnt lgkmcnt(4)
	v_add_f32_e32 v68, v68, v69
	s_waitcnt lgkmcnt(3)
	v_add_f32_e32 v68, v68, v70
	v_add_f32_e32 v68, v68, v71
	s_waitcnt lgkmcnt(1)
	v_fmac_f32_e32 v68, v72, v73
	s_waitcnt lgkmcnt(0)
	v_max_f32_e32 v69, v74, v74
	v_max_f32_e64 v68, |v68|, v69
	v_rcp_f32_e32 v68, v68
	v_and_b32_e32 v74, 0xffff0000, v102
	v_mul_f32_e32 v74, 0xbfb8aa3b, v74
	v_exp_f32_e32 v75, v74
	v_pk_mul_f32 v[66:67], v[66:67], v[68:69] op_sel_hi:[1,0]
	v_pk_mul_f32 v[64:65], v[64:65], v[68:69] op_sel_hi:[1,0]
	v_pk_mul_f32 v[70:71], v[14:15], v[68:69] op_sel_hi:[1,0]
	v_pk_mul_f32 v[72:73], v[12:13], v[68:69] op_sel_hi:[1,0]
	v_lshlrev_b32_e32 v69, 16, v102
	v_mul_f32_e32 v69, 0xbfb8aa3b, v69
	v_exp_f32_e32 v69, v69
	v_lshlrev_b32_e32 v14, 16, v100
	v_and_b32_e32 v15, 0xffff0000, v100
	v_mul_f32_e32 v14, 0xbfb8aa3b, v14
	v_add_f32_e32 v69, 1.0, v69
	v_rcp_f32_e32 v74, v69
	v_add_f32_e32 v69, 1.0, v75
	v_lshlrev_b32_e32 v75, 16, v103
	v_mul_f32_e32 v75, 0xbfb8aa3b, v75
	v_exp_f32_e32 v76, v75
	v_and_b32_e32 v75, 0xffff0000, v103
	v_mul_f32_e32 v75, 0xbfb8aa3b, v75
	v_exp_f32_e32 v77, v75
	v_rcp_f32_e32 v75, v69
	v_add_f32_e32 v69, 1.0, v76
	v_rcp_f32_e32 v76, v69
	v_add_f32_e32 v69, 1.0, v77
	v_mul_f32_e32 v15, 0xbfb8aa3b, v15
	v_rcp_f32_e32 v77, v69
	v_pk_mul_f32 v[124:125], v[74:75], v[72:73]
	v_pk_mul_f32 v[62:63], v[62:63], v[68:69] op_sel_hi:[1,0]
	v_pk_mul_f32 v[60:61], v[60:61], v[68:69] op_sel_hi:[1,0]
	v_pk_mul_f32 v[58:59], v[58:59], v[68:69] op_sel_hi:[1,0]
	v_lshlrev_b32_e32 v69, 16, v96
	v_and_b32_e32 v74, 0xffff0000, v96
	v_exp_f32_e32 v14, v14
	v_exp_f32_e32 v15, v15
	v_mul_f32_e32 v69, 0xbfb8aa3b, v69
	v_mul_f32_e32 v74, 0xbfb8aa3b, v74
	v_exp_f32_e32 v69, v69
	v_exp_f32_e32 v74, v74
	v_add_f32_e32 v12, 1.0, v14
	v_add_f32_e32 v13, 1.0, v15
	v_lshlrev_b32_e32 v14, 16, v101
	v_and_b32_e32 v15, 0xffff0000, v101
	v_mul_f32_e32 v14, 0xbfb8aa3b, v14
	v_mul_f32_e32 v15, 0xbfb8aa3b, v15
	v_pk_mul_f32 v[100:101], v[76:77], v[70:71]
	v_pk_mul_f32 v[56:57], v[56:57], v[68:69] op_sel_hi:[1,0]
	v_add_f32_e32 v68, 1.0, v69
	v_add_f32_e32 v69, 1.0, v74
	v_lshlrev_b32_e32 v74, 16, v97
	v_and_b32_e32 v75, 0xffff0000, v97
	v_lshlrev_b32_e32 v76, 16, v98
	v_and_b32_e32 v77, 0xffff0000, v98
	v_exp_f32_e32 v14, v14
	v_exp_f32_e32 v15, v15
	v_mul_f32_e32 v74, 0xbfb8aa3b, v74
	v_mul_f32_e32 v75, 0xbfb8aa3b, v75
	v_mul_f32_e32 v76, 0xbfb8aa3b, v76
	v_mul_f32_e32 v77, 0xbfb8aa3b, v77
	v_exp_f32_e32 v74, v74
	v_exp_f32_e32 v75, v75
	v_exp_f32_e32 v76, v76
	v_exp_f32_e32 v77, v77
	v_lshlrev_b32_e32 v78, 16, v99
	v_and_b32_e32 v79, 0xffff0000, v99
	v_rcp_f32_e32 v12, v12
	v_rcp_f32_e32 v13, v13
	v_add_f32_e32 v14, 1.0, v14
	v_add_f32_e32 v15, 1.0, v15
	v_mul_f32_e32 v78, 0xbfb8aa3b, v78
	v_mul_f32_e32 v79, 0xbfb8aa3b, v79
	v_rcp_f32_e32 v14, v14
	v_rcp_f32_e32 v15, v15
	v_rcp_f32_e32 v68, v68
	v_rcp_f32_e32 v69, v69
	v_add_f32_e32 v74, 1.0, v74
	v_add_f32_e32 v75, 1.0, v75
	v_add_f32_e32 v76, 1.0, v76
	v_add_f32_e32 v77, 1.0, v77
	v_exp_f32_e32 v78, v78
	v_exp_f32_e32 v79, v79
	v_rcp_f32_e32 v74, v74
	v_rcp_f32_e32 v75, v75
	v_rcp_f32_e32 v76, v76
	v_rcp_f32_e32 v77, v77
	v_pk_mul_f32 v[12:13], v[12:13], v[64:65]
	v_pk_mul_f32 v[14:15], v[14:15], v[66:67]
	v_add_f32_e32 v64, v12, v13
	v_add_f32_e32 v78, 1.0, v78
	v_add_f32_e32 v79, 1.0, v79
	v_pk_mul_f32 v[144:145], v[68:69], v[60:61]
	v_add_f32_e32 v64, v14, v64
	v_rcp_f32_e32 v78, v78
	v_rcp_f32_e32 v79, v79
	v_pk_mul_f32 v[126:127], v[74:75], v[62:63]
	v_pk_mul_f32 v[98:99], v[76:77], v[56:57]
	v_add_f32_e32 v56, v144, v145
	v_add_f32_e32 v64, v15, v64
	v_add_f32_e32 v56, v126, v56
	v_add_f32_e32 v64, v124, v64
	v_add_f32_e32 v56, v127, v56
	v_add_f32_e32 v64, v125, v64
	v_add_f32_e32 v56, v98, v56
	v_add_f32_e32 v64, v100, v64
	v_pk_mul_f32 v[96:97], v[78:79], v[58:59]
	v_add_f32_e32 v56, v99, v56
	v_add_f32_e32 v64, v101, v64
	v_add_f32_e32 v56, v96, v56
	v_add_f32_e32 v102, 0, v64
	v_add_f32_e32 v56, v97, v56
	v_pk_mul_f32 v[64:65], v[12:13], v[12:13]
	v_add_f32_e32 v68, v56, v102
	v_pk_mul_f32 v[56:57], v[144:145], v[144:145]
	v_pk_mul_f32 v[66:67], v[14:15], v[14:15]
	v_pk_mul_f32 v[58:59], v[126:127], v[126:127]
	v_add_f32_e32 v56, v56, v57
	v_add_f32_e32 v57, v64, v65
	v_add_f32_e32 v56, v58, v56
	v_add_f32_e32 v57, v66, v57
	v_pk_mul_f32 v[70:71], v[124:125], v[124:125]
	v_pk_mul_f32 v[60:61], v[98:99], v[98:99]
	v_add_f32_e32 v56, v59, v56
	v_add_f32_e32 v57, v67, v57
	v_add_f32_e32 v56, v60, v56
	v_add_f32_e32 v57, v70, v57
	v_pk_mul_f32 v[72:73], v[100:101], v[100:101]
	v_pk_mul_f32 v[62:63], v[96:97], v[96:97]
	v_add_f32_e32 v56, v61, v56
	v_add_f32_e32 v57, v71, v57
	v_add_f32_e32 v56, v62, v56
	v_add_f32_e32 v57, v72, v57
	v_add_f32_e32 v56, v63, v56
	v_add_f32_e32 v57, v73, v57
	v_add_f32_e32 v59, v57, v56
	v_mov_b32_e32 v58, v68
	s_nop 1
	v_permlane16_swap_b32 v68, v58
	v_mov_b32_e32 v60, v59
	s_nop 1
	v_permlane16_swap_b32 v59, v60
	s_waitcnt lgkmcnt(1)
	v_add_f32_e32 v56, v68, v58
	s_waitcnt lgkmcnt(0)
	v_add_f32_e32 v58, v59, v60
	v_mov_b32_e32 v57, v56
	s_nop 1
	v_permlane32_swap_b32 v56, v57
	v_mov_b32_e32 v59, v58
	s_nop 1
	v_permlane32_swap_b32 v58, v59
	s_and_saveexec_b64 s[0:1], vcc
	s_cbranch_execz .LBB0_675
	s_waitcnt lgkmcnt(1)
	v_add_f32_e32 v56, v56, v57
	s_waitcnt lgkmcnt(0)
	v_add_f32_e32 v57, v58, v59
	v_add_u32_e32 v58, 64, v177
	ds_write2st64_b32 v58, v56, v57 offset0:2 offset1:18
.LBB0_675:
	s_or_b64 exec, exec, s[0:1]
	v_add_u32_e32 v58, 0x80, v152
	s_waitcnt lgkmcnt(1)
	ds_read2st64_b32 v[56:57], v58 offset0:2 offset1:6
	s_waitcnt lgkmcnt(1)
	ds_read2st64_b32 v[58:59], v58 offset0:10 offset1:14
	ds_read_b32 v60, v174 offset:640
	ds_read_b32 v61, v175 offset:640
	ds_read_b32 v62, v176 offset:640
	s_waitcnt lgkmcnt(4)
	v_add_f32_e32 v56, v56, v57
	s_waitcnt lgkmcnt(3)
	v_add_f32_e32 v56, v56, v58
	v_add_f32_e32 v56, v56, v59
	s_waitcnt lgkmcnt(1)
	v_fmac_f32_e32 v56, v60, v61
	s_waitcnt lgkmcnt(0)
	v_max_f32_e32 v57, v62, v62
	v_max_f32_e64 v56, |v56|, v57
	v_rcp_f32_e32 v56, v56
	v_and_b32_e32 v62, 0xffff0000, v94
	v_mul_f32_e32 v62, 0xbfb8aa3b, v62
	v_exp_f32_e32 v63, v62
	v_pk_mul_f32 v[54:55], v[54:55], v[56:57] op_sel_hi:[1,0]
	v_pk_mul_f32 v[52:53], v[52:53], v[56:57] op_sel_hi:[1,0]
	v_pk_mul_f32 v[58:59], v[6:7], v[56:57] op_sel_hi:[1,0]
	v_pk_mul_f32 v[60:61], v[4:5], v[56:57] op_sel_hi:[1,0]
	v_lshlrev_b32_e32 v57, 16, v94
	v_mul_f32_e32 v57, 0xbfb8aa3b, v57
	v_exp_f32_e32 v57, v57
	v_lshlrev_b32_e32 v6, 16, v92
	v_and_b32_e32 v7, 0xffff0000, v92
	v_mul_f32_e32 v6, 0xbfb8aa3b, v6
	v_add_f32_e32 v57, 1.0, v57
	v_rcp_f32_e32 v62, v57
	v_add_f32_e32 v57, 1.0, v63
	v_lshlrev_b32_e32 v63, 16, v95
	v_mul_f32_e32 v63, 0xbfb8aa3b, v63
	v_exp_f32_e32 v64, v63
	v_and_b32_e32 v63, 0xffff0000, v95
	v_mul_f32_e32 v63, 0xbfb8aa3b, v63
	v_exp_f32_e32 v65, v63
	v_rcp_f32_e32 v63, v57
	v_add_f32_e32 v57, 1.0, v64
	v_rcp_f32_e32 v64, v57
	v_add_f32_e32 v57, 1.0, v65
	v_mul_f32_e32 v7, 0xbfb8aa3b, v7
	v_rcp_f32_e32 v65, v57
	v_pk_mul_f32 v[94:95], v[62:63], v[60:61]
	v_pk_mul_f32 v[50:51], v[50:51], v[56:57] op_sel_hi:[1,0]
	v_pk_mul_f32 v[48:49], v[48:49], v[56:57] op_sel_hi:[1,0]
	v_pk_mul_f32 v[46:47], v[46:47], v[56:57] op_sel_hi:[1,0]
	v_lshlrev_b32_e32 v57, 16, v88
	v_and_b32_e32 v62, 0xffff0000, v88
	v_exp_f32_e32 v6, v6
	v_exp_f32_e32 v7, v7
	v_mul_f32_e32 v57, 0xbfb8aa3b, v57
	v_mul_f32_e32 v62, 0xbfb8aa3b, v62
	v_exp_f32_e32 v57, v57
	v_exp_f32_e32 v62, v62
	v_add_f32_e32 v4, 1.0, v6
	v_add_f32_e32 v5, 1.0, v7
	v_lshlrev_b32_e32 v6, 16, v93
	v_and_b32_e32 v7, 0xffff0000, v93
	v_mul_f32_e32 v6, 0xbfb8aa3b, v6
	v_mul_f32_e32 v7, 0xbfb8aa3b, v7
	v_pk_mul_f32 v[92:93], v[64:65], v[58:59]
	v_pk_mul_f32 v[44:45], v[44:45], v[56:57] op_sel_hi:[1,0]
	v_add_f32_e32 v56, 1.0, v57
	v_add_f32_e32 v57, 1.0, v62
	v_lshlrev_b32_e32 v62, 16, v89
	v_and_b32_e32 v63, 0xffff0000, v89
	v_lshlrev_b32_e32 v64, 16, v90
	v_and_b32_e32 v65, 0xffff0000, v90
	v_exp_f32_e32 v6, v6
	v_exp_f32_e32 v7, v7
	v_mul_f32_e32 v62, 0xbfb8aa3b, v62
	v_mul_f32_e32 v63, 0xbfb8aa3b, v63
	v_mul_f32_e32 v64, 0xbfb8aa3b, v64
	v_mul_f32_e32 v65, 0xbfb8aa3b, v65
	v_exp_f32_e32 v62, v62
	v_exp_f32_e32 v63, v63
	v_exp_f32_e32 v64, v64
	v_exp_f32_e32 v65, v65
	v_lshlrev_b32_e32 v66, 16, v91
	v_and_b32_e32 v67, 0xffff0000, v91
	v_rcp_f32_e32 v4, v4
	v_rcp_f32_e32 v5, v5
	v_add_f32_e32 v6, 1.0, v6
	v_add_f32_e32 v7, 1.0, v7
	v_mul_f32_e32 v66, 0xbfb8aa3b, v66
	v_mul_f32_e32 v67, 0xbfb8aa3b, v67
	v_rcp_f32_e32 v6, v6
	v_rcp_f32_e32 v7, v7
	v_rcp_f32_e32 v56, v56
	v_rcp_f32_e32 v57, v57
	v_add_f32_e32 v62, 1.0, v62
	v_add_f32_e32 v63, 1.0, v63
	v_add_f32_e32 v64, 1.0, v64
	v_add_f32_e32 v65, 1.0, v65
	v_exp_f32_e32 v66, v66
	v_exp_f32_e32 v67, v67
	v_rcp_f32_e32 v62, v62
	v_rcp_f32_e32 v63, v63
	v_rcp_f32_e32 v64, v64
	v_rcp_f32_e32 v65, v65
	v_pk_mul_f32 v[4:5], v[4:5], v[52:53]
	v_pk_mul_f32 v[6:7], v[6:7], v[54:55]
	v_add_f32_e32 v52, v4, v5
	v_add_f32_e32 v66, 1.0, v66
	v_add_f32_e32 v67, 1.0, v67
	v_pk_mul_f32 v[102:103], v[56:57], v[48:49]
	v_add_f32_e32 v52, v6, v52
	v_rcp_f32_e32 v66, v66
	v_rcp_f32_e32 v67, v67
	v_pk_mul_f32 v[90:91], v[62:63], v[50:51]
	v_pk_mul_f32 v[88:89], v[64:65], v[44:45]
	v_add_f32_e32 v44, v102, v103
	v_add_f32_e32 v52, v7, v52
	v_add_f32_e32 v44, v90, v44
	v_add_f32_e32 v52, v94, v52
	v_add_f32_e32 v44, v91, v44
	v_add_f32_e32 v52, v95, v52
	v_add_f32_e32 v44, v88, v44
	v_add_f32_e32 v52, v92, v52
	v_pk_mul_f32 v[78:79], v[66:67], v[46:47]
	v_add_f32_e32 v44, v89, v44
	v_add_f32_e32 v52, v93, v52
	v_add_f32_e32 v44, v78, v44
	v_add_f32_e32 v68, 0, v52
	v_add_f32_e32 v44, v79, v44
	v_pk_mul_f32 v[52:53], v[4:5], v[4:5]
	v_add_f32_e32 v56, v44, v68
	v_pk_mul_f32 v[44:45], v[102:103], v[102:103]
	v_pk_mul_f32 v[54:55], v[6:7], v[6:7]
	v_pk_mul_f32 v[46:47], v[90:91], v[90:91]
	v_add_f32_e32 v44, v44, v45
	v_add_f32_e32 v45, v52, v53
	v_add_f32_e32 v44, v46, v44
	v_add_f32_e32 v45, v54, v45
	v_pk_mul_f32 v[58:59], v[94:95], v[94:95]
	v_pk_mul_f32 v[48:49], v[88:89], v[88:89]
	v_add_f32_e32 v44, v47, v44
	v_add_f32_e32 v45, v55, v45
	v_add_f32_e32 v44, v48, v44
	v_add_f32_e32 v45, v58, v45
	v_pk_mul_f32 v[60:61], v[92:93], v[92:93]
	v_pk_mul_f32 v[50:51], v[78:79], v[78:79]
	v_add_f32_e32 v44, v49, v44
	v_add_f32_e32 v45, v59, v45
	v_add_f32_e32 v44, v50, v44
	v_add_f32_e32 v45, v60, v45
	v_add_f32_e32 v44, v51, v44
	v_add_f32_e32 v45, v61, v45
	v_add_f32_e32 v47, v45, v44
	v_mov_b32_e32 v46, v56
	s_nop 1
	v_permlane16_swap_b32 v56, v46
	v_mov_b32_e32 v48, v47
	s_nop 1
	v_permlane16_swap_b32 v47, v48
	s_waitcnt lgkmcnt(1)
	v_add_f32_e32 v44, v56, v46
	s_waitcnt lgkmcnt(0)
	v_add_f32_e32 v46, v47, v48
	v_mov_b32_e32 v45, v44
	s_nop 1
	v_permlane32_swap_b32 v44, v45
	v_mov_b32_e32 v47, v46
	s_nop 1
	v_permlane32_swap_b32 v46, v47
	s_and_saveexec_b64 s[0:1], vcc
	s_cbranch_execz .LBB0_677
	s_waitcnt lgkmcnt(1)
	v_add_f32_e32 v44, v44, v45
	s_waitcnt lgkmcnt(0)
	v_add_f32_e32 v45, v46, v47
	v_add_u32_e32 v46, 0x80, v177
	ds_write2st64_b32 v46, v44, v45 offset0:2 offset1:18
.LBB0_677:
	s_or_b64 exec, exec, s[0:1]
	v_add_u32_e32 v46, 0xc0, v152
	s_waitcnt lgkmcnt(1)
	ds_read2st64_b32 v[44:45], v46 offset0:2 offset1:6
	s_waitcnt lgkmcnt(1)
	ds_read2st64_b32 v[46:47], v46 offset0:10 offset1:14
	ds_read_b32 v48, v174 offset:704
	ds_read_b32 v49, v175 offset:704
	ds_read_b32 v50, v176 offset:704
	s_waitcnt lgkmcnt(4)
	v_add_f32_e32 v44, v44, v45
	s_waitcnt lgkmcnt(3)
	v_add_f32_e32 v44, v44, v46
	v_add_f32_e32 v44, v44, v47
	s_waitcnt lgkmcnt(1)
	v_fmac_f32_e32 v44, v48, v49
	s_waitcnt lgkmcnt(0)
	v_max_f32_e32 v45, v50, v50
	v_max_f32_e64 v44, |v44|, v45
	v_rcp_f32_e32 v44, v44
	v_and_b32_e32 v50, 0xffff0000, v86
	v_mul_f32_e32 v50, 0xbfb8aa3b, v50
	v_exp_f32_e32 v51, v50
	v_pk_mul_f32 v[42:43], v[42:43], v[44:45] op_sel_hi:[1,0]
	v_pk_mul_f32 v[40:41], v[40:41], v[44:45] op_sel_hi:[1,0]
	v_pk_mul_f32 v[46:47], v[2:3], v[44:45] op_sel_hi:[1,0]
	v_pk_mul_f32 v[48:49], v[0:1], v[44:45] op_sel_hi:[1,0]
	v_lshlrev_b32_e32 v45, 16, v86
	v_mul_f32_e32 v45, 0xbfb8aa3b, v45
	v_exp_f32_e32 v45, v45
	v_lshlrev_b32_e32 v2, 16, v84
	v_and_b32_e32 v3, 0xffff0000, v84
	v_mul_f32_e32 v2, 0xbfb8aa3b, v2
	v_add_f32_e32 v45, 1.0, v45
	v_rcp_f32_e32 v50, v45
	v_add_f32_e32 v45, 1.0, v51
	v_lshlrev_b32_e32 v51, 16, v87
	v_mul_f32_e32 v51, 0xbfb8aa3b, v51
	v_exp_f32_e32 v52, v51
	v_and_b32_e32 v51, 0xffff0000, v87
	v_mul_f32_e32 v51, 0xbfb8aa3b, v51
	v_mul_f32_e32 v3, 0xbfb8aa3b, v3
	v_exp_f32_e32 v53, v51
	v_exp_f32_e32 v2, v2
	v_exp_f32_e32 v3, v3
	v_rcp_f32_e32 v51, v45
	v_add_f32_e32 v45, 1.0, v52
	v_rcp_f32_e32 v52, v45
	v_add_f32_e32 v45, 1.0, v53
	v_add_f32_e32 v0, 1.0, v2
	v_add_f32_e32 v1, 1.0, v3
	v_lshlrev_b32_e32 v2, 16, v85
	v_and_b32_e32 v3, 0xffff0000, v85
	v_rcp_f32_e32 v53, v45
	v_pk_mul_f32 v[84:85], v[50:51], v[48:49]
	v_pk_mul_f32 v[38:39], v[38:39], v[44:45] op_sel_hi:[1,0]
	v_pk_mul_f32 v[36:37], v[36:37], v[44:45] op_sel_hi:[1,0]
	v_pk_mul_f32 v[34:35], v[34:35], v[44:45] op_sel_hi:[1,0]
	v_lshlrev_b32_e32 v45, 16, v80
	v_and_b32_e32 v50, 0xffff0000, v80
	v_mul_f32_e32 v45, 0xbfb8aa3b, v45
	v_mul_f32_e32 v50, 0xbfb8aa3b, v50
	v_exp_f32_e32 v45, v45
	v_exp_f32_e32 v50, v50
	v_mul_f32_e32 v2, 0xbfb8aa3b, v2
	v_mul_f32_e32 v3, 0xbfb8aa3b, v3
	v_pk_mul_f32 v[76:77], v[52:53], v[46:47]
	v_pk_mul_f32 v[32:33], v[32:33], v[44:45] op_sel_hi:[1,0]
	v_add_f32_e32 v44, 1.0, v45
	v_add_f32_e32 v45, 1.0, v50
	v_lshlrev_b32_e32 v50, 16, v81
	v_and_b32_e32 v51, 0xffff0000, v81
	v_lshlrev_b32_e32 v52, 16, v82
	v_and_b32_e32 v53, 0xffff0000, v82
	v_exp_f32_e32 v2, v2
	v_exp_f32_e32 v3, v3
	v_mul_f32_e32 v50, 0xbfb8aa3b, v50
	v_mul_f32_e32 v51, 0xbfb8aa3b, v51
	v_mul_f32_e32 v52, 0xbfb8aa3b, v52
	v_mul_f32_e32 v53, 0xbfb8aa3b, v53
	v_exp_f32_e32 v50, v50
	v_exp_f32_e32 v51, v51
	v_exp_f32_e32 v52, v52
	v_exp_f32_e32 v53, v53
	v_lshlrev_b32_e32 v54, 16, v83
	v_and_b32_e32 v55, 0xffff0000, v83
	v_rcp_f32_e32 v0, v0
	v_rcp_f32_e32 v1, v1
	v_add_f32_e32 v2, 1.0, v2
	v_add_f32_e32 v3, 1.0, v3
	v_mul_f32_e32 v54, 0xbfb8aa3b, v54
	v_mul_f32_e32 v55, 0xbfb8aa3b, v55
	v_rcp_f32_e32 v2, v2
	v_rcp_f32_e32 v3, v3
	v_rcp_f32_e32 v44, v44
	v_rcp_f32_e32 v45, v45
	v_add_f32_e32 v50, 1.0, v50
	v_add_f32_e32 v51, 1.0, v51
	v_add_f32_e32 v52, 1.0, v52
	v_add_f32_e32 v53, 1.0, v53
	v_exp_f32_e32 v54, v54
	v_exp_f32_e32 v55, v55
	v_rcp_f32_e32 v50, v50
	v_rcp_f32_e32 v51, v51
	v_rcp_f32_e32 v52, v52
	v_rcp_f32_e32 v53, v53
	v_pk_mul_f32 v[0:1], v[0:1], v[40:41]
	v_pk_mul_f32 v[2:3], v[2:3], v[42:43]
	v_add_f32_e32 v40, v0, v1
	v_add_f32_e32 v54, 1.0, v54
	v_add_f32_e32 v55, 1.0, v55
	v_pk_mul_f32 v[82:83], v[44:45], v[36:37]
	v_add_f32_e32 v40, v2, v40
	v_rcp_f32_e32 v54, v54
	v_rcp_f32_e32 v55, v55
	v_pk_mul_f32 v[80:81], v[50:51], v[38:39]
	v_pk_mul_f32 v[74:75], v[52:53], v[32:33]
	v_add_f32_e32 v32, v82, v83
	v_add_f32_e32 v40, v3, v40
	v_add_f32_e32 v32, v80, v32
	v_add_f32_e32 v40, v84, v40
	v_add_f32_e32 v32, v81, v32
	v_add_f32_e32 v40, v85, v40
	v_add_f32_e32 v32, v74, v32
	v_add_f32_e32 v40, v76, v40
	v_pk_mul_f32 v[72:73], v[54:55], v[34:35]
	v_add_f32_e32 v32, v75, v32
	v_add_f32_e32 v40, v77, v40
	v_add_f32_e32 v32, v72, v32
	v_add_f32_e32 v56, 0, v40
	v_add_f32_e32 v32, v73, v32
	v_pk_mul_f32 v[40:41], v[0:1], v[0:1]
	v_add_f32_e32 v44, v32, v56
	v_pk_mul_f32 v[32:33], v[82:83], v[82:83]
	v_pk_mul_f32 v[42:43], v[2:3], v[2:3]
	v_pk_mul_f32 v[34:35], v[80:81], v[80:81]
	v_add_f32_e32 v32, v32, v33
	v_add_f32_e32 v33, v40, v41
	v_add_f32_e32 v32, v34, v32
	v_add_f32_e32 v33, v42, v33
	v_pk_mul_f32 v[46:47], v[84:85], v[84:85]
	v_pk_mul_f32 v[36:37], v[74:75], v[74:75]
	v_add_f32_e32 v32, v35, v32
	v_add_f32_e32 v33, v43, v33
	v_add_f32_e32 v32, v36, v32
	v_add_f32_e32 v33, v46, v33
	v_pk_mul_f32 v[48:49], v[76:77], v[76:77]
	v_pk_mul_f32 v[38:39], v[72:73], v[72:73]
	v_add_f32_e32 v32, v37, v32
	v_add_f32_e32 v33, v47, v33
	v_add_f32_e32 v32, v38, v32
	v_add_f32_e32 v33, v48, v33
	v_add_f32_e32 v32, v39, v32
	v_add_f32_e32 v33, v49, v33
	v_add_f32_e32 v35, v33, v32
	v_mov_b32_e32 v34, v44
	s_nop 1
	v_permlane16_swap_b32 v44, v34
	v_mov_b32_e32 v36, v35
	s_nop 1
	v_permlane16_swap_b32 v35, v36
	s_lshl_b64 s[0:1], s[20:21], 10
	s_waitcnt lgkmcnt(1)
	v_add_f32_e32 v32, v44, v34
	s_waitcnt lgkmcnt(0)
	v_add_f32_e32 v34, v35, v36
	v_mov_b32_e32 v33, v32
	s_nop 1
	v_permlane32_swap_b32 v32, v33
	v_mov_b32_e32 v35, v34
	s_nop 1
	v_permlane32_swap_b32 v34, v35
	s_and_saveexec_b64 s[20:21], vcc
	s_cbranch_execz .LBB0_614
	s_waitcnt lgkmcnt(1)
	v_add_f32_e32 v32, v32, v33
	s_waitcnt lgkmcnt(0)
	v_add_f32_e32 v33, v34, v35
	v_add_u32_e32 v34, 0xc0, v177
	ds_write2st64_b32 v34, v32, v33 offset0:2 offset1:18
	s_branch .LBB0_614
	s_nop 0
	s_nop 0
	s_nop 0
	s_nop 0
	s_nop 0
	s_nop 0
	s_nop 0
	s_nop 0
	s_nop 0
	s_nop 0
	s_nop 0
	s_nop 0
	s_nop 0
	s_nop 0
	s_nop 0
	s_nop 0
	s_nop 0
	s_nop 0
	s_nop 0
	s_nop 0
	s_nop 0
	s_nop 0
	s_nop 0
	s_nop 0
	s_nop 0
	s_nop 0
	s_nop 0
	s_nop 0
	s_nop 0
	s_nop 0
	s_nop 0
	s_nop 0
	s_nop 0
	s_nop 0
	s_nop 0
	s_nop 0
	s_nop 0
	s_nop 0
	s_nop 0
	s_nop 0
	s_nop 0
	s_nop 0
	s_nop 0
	s_nop 0
	s_nop 0
	s_nop 0
	s_nop 0
	s_nop 0
	s_nop 0
	s_nop 0
